# adds: P1 modulation-parameter loads issued together; b_f loaded once per wave
# speedup vs baseline: 1.0051x; 1.0001x over previous
.LBB0_89:
	s_or_b64 exec, exec, s[0:1]
	s_lshl_b32 s0, s3, 3
	s_add_i32 s3, s0, s49
	v_and_b32_e32 v181, 63, v180
	s_cmpk_gt_i32 s3, 0x7ff
	s_waitcnt lgkmcnt(0)
	s_barrier
	s_cbranch_scc1 .LBB0_108
	v_mbcnt_lo_u32_b32 v1, -1, 0
	v_mbcnt_hi_u32_b32 v1, -1, v1
	v_mov_b32_e32 v3, 0
	v_and_b32_e32 v4, 64, v1
	v_add_u32_e32 v7, 64, v4
	v_lshlrev_b32_e32 v4, 3, v181
	v_mov_b32_e32 v5, v3
	v_lshl_add_u64 v[130:131], s[94:95], 0, v[4:5]
	v_and_b32_e32 v4, 1, v180
	v_cmp_eq_u32_e32 vcc, 0, v4
	v_and_b32_e32 v4, 2, v180
	v_cmp_eq_u32_e64 s[4:5], 0, v4
	v_and_b32_e32 v4, 4, v180
	v_cmp_eq_u32_e64 s[6:7], 0, v4
	v_and_b32_e32 v4, 3, v180
	v_bfrev_b32_e32 v4, v4
	v_lshrrev_b32_e32 v4, 29, v4
	v_lshrrev_b32_e32 v5, 2, v181
	s_lshl_b32 s18, s3, 3
	v_or_b32_e32 v183, v5, v4
	v_lshlrev_b32_e32 v0, 2, v181
	s_add_u32 s0, s58, 0x1000
	v_lshlrev_b32_e32 v4, 2, v183
	v_mov_b32_e32 v5, v3
	s_addc_u32 s1, s59, 0
	v_lshlrev_b32_e32 v2, 4, v181
	v_lshl_add_u64 v[132:133], s[64:65], 0, v[4:5]
	v_or_b32_e32 v4, 0x100, v0
	v_lshl_add_u64 v[128:129], s[52:53], 0, v[2:3]
	v_add_u32_e32 v182, 0, v2
	v_lshl_add_u64 v[134:135], s[60:61], 0, v[2:3]
	v_lshl_add_u64 v[136:137], s[0:1], 0, v[2:3]
	v_lshl_add_u64 v[138:139], s[58:59], 0, v[2:3]
	v_lshlrev_b32_e32 v2, 2, v4
	v_or_b32_e32 v6, 0x200, v0
	v_lshl_add_u64 v[140:141], s[0:1], 0, v[2:3]
	v_lshlrev_b32_e32 v2, 2, v6
	v_or_b32_e32 v8, 0x300, v0
	v_lshl_add_u64 v[142:143], s[0:1], 0, v[2:3]
	v_lshlrev_b32_e32 v2, 2, v8
	v_lshl_add_u64 v[144:145], s[0:1], 0, v[2:3]
	v_xor_b32_e32 v2, 1, v1
	v_cmp_lt_i32_e64 s[0:1], v2, v7
	v_cmp_gt_u32_e64 s[8:9], 8, v181
	s_lshl_b32 s40, s33, 6
	v_cndmask_b32_e64 v2, v1, v2, s[0:1]
	v_lshlrev_b32_e32 v184, 2, v2
	v_xor_b32_e32 v2, 2, v1
	v_cmp_lt_i32_e64 s[0:1], v2, v7
	v_lshlrev_b32_e32 v190, 2, v0
	v_lshlrev_b32_e32 v191, 2, v4
	v_cndmask_b32_e64 v2, v1, v2, s[0:1]
	v_lshlrev_b32_e32 v185, 2, v2
	v_xor_b32_e32 v2, 4, v1
	v_cmp_lt_i32_e64 s[0:1], v2, v7
	v_lshlrev_b32_e32 v192, 2, v6
	v_lshlrev_b32_e32 v193, 2, v8
	v_cndmask_b32_e64 v2, v1, v2, s[0:1]
	v_lshlrev_b32_e32 v186, 2, v2
	v_xor_b32_e32 v2, 8, v1
	v_cmp_lt_i32_e64 s[0:1], v2, v7
	v_mov_b32_e32 v194, 0x358637bd
	s_mov_b32 s41, 0xbfb8aa3b
	v_cndmask_b32_e64 v2, v1, v2, s[0:1]
	v_lshlrev_b32_e32 v187, 2, v2
	v_xor_b32_e32 v2, 16, v1
	v_cmp_lt_i32_e64 s[0:1], v2, v7
	s_mov_b32 s42, 0x3f2aaaab
	v_mov_b32_e32 v195, 0x3ecc95a3
	v_cndmask_b32_e64 v2, v1, v2, s[0:1]
	v_lshlrev_b32_e32 v188, 2, v2
	v_xor_b32_e32 v2, 32, v1
	v_cmp_lt_i32_e64 s[0:1], v2, v7
	s_mov_b32 s43, 0x3f317218
	s_mov_b32 s44, 0x7f800000
	v_cndmask_b32_e64 v1, v1, v2, s[0:1]
	v_lshlrev_b32_e32 v189, 2, v1
	s_mov_b32 s45, 0x33800000
	v_mov_b32_e32 v146, 0x3f317218
	v_mov_b32_e32 v196, 0x7f800000
	v_mov_b32_e32 v197, 0x7fc00000
	v_mov_b32_e32 v198, 0xff800000
	global_load_dword v216, v[132:133], off
	s_branch .LBB0_92

.LBB0_92:
	s_ashr_i32 s19, s18, 31
	s_lshr_b32 s0, s19, 19
	s_add_i32 s0, s18, s0
	s_ashr_i32 s38, s0, 13
	s_mul_i32 s0, s38, 0x1800
	s_ashr_i32 s1, s0, 31
	s_lshl_b64 s[0:1], s[0:1], 2
	s_add_u32 s0, s14, s0
	s_addc_u32 s1, s15, s1
	s_add_u32 s20, s0, 0x1000
	s_addc_u32 s21, s1, 0
	s_waitcnt lgkmcnt(0)
	global_load_dwordx4 v[16:19], v[134:135], off
	global_load_dwordx4 v[20:23], v190, s[20:21]
	global_load_dwordx4 v[24:27], v[136:137], off
	global_load_dwordx4 v[28:31], v190, s[0:1]
	global_load_dwordx4 v[32:35], v[138:139], off
	global_load_dwordx4 v[36:39], v[134:135], off offset:1024
	global_load_dwordx4 v[40:43], v191, s[20:21]
	global_load_dwordx4 v[44:47], v[140:141], off
	global_load_dwordx4 v[48:51], v190, s[0:1] offset:1024
	global_load_dwordx4 v[52:55], v[138:139], off offset:1024
	global_load_dwordx4 v[56:59], v[134:135], off offset:2048
	global_load_dwordx4 v[60:63], v192, s[20:21]
	global_load_dwordx4 v[64:67], v[142:143], off
	global_load_dwordx4 v[68:71], v190, s[0:1] offset:2048
	global_load_dwordx4 v[72:75], v[138:139], off offset:2048
	global_load_dwordx4 v[76:79], v[134:135], off offset:3072
	global_load_dwordx4 v[80:83], v193, s[20:21]
	global_load_dwordx4 v[84:87], v[144:145], off
	global_load_dwordx4 v[88:91], v190, s[0:1] offset:3072
	global_load_dwordx4 v[92:95], v[138:139], off offset:3072
	s_add_i32 s34, s18, 1
	s_ashr_i32 s35, s34, 31
	s_add_i32 s30, s18, 2
	s_ashr_i32 s31, s30, 31
	s_add_i32 s28, s18, 3
	s_ashr_i32 s29, s28, 31
	s_add_i32 s26, s18, 4
	s_ashr_i32 s27, s26, 31
	s_add_i32 s24, s18, 5
	s_ashr_i32 s25, s24, 31
	s_add_i32 s22, s18, 6
	s_ashr_i32 s23, s22, 31
	s_add_i32 s20, s18, 7
	s_ashr_i32 s21, s20, 31
	s_lshl_b64 s[0:1], s[18:19], 12
	s_waitcnt vmcnt(0)
	v_pk_add_f32 v[12:13], v[22:23], v[26:27]
	v_pk_add_f32 v[14:15], v[20:21], v[24:25]
	v_pk_add_f32 v[148:149], v[30:31], v[34:35]
	v_pk_add_f32 v[150:151], v[28:29], v[32:33]
	v_pk_add_f32 v[4:5], v[12:13], 1.0 op_sel_hi:[1,0]
	v_pk_add_f32 v[6:7], v[14:15], 1.0 op_sel_hi:[1,0]
	v_pk_mul_f32 v[152:153], v[18:19], v[4:5]
	v_pk_mul_f32 v[154:155], v[16:17], v[6:7]
	v_pk_add_f32 v[12:13], v[42:43], v[46:47]
	v_pk_add_f32 v[14:15], v[40:41], v[44:45]
	v_pk_add_f32 v[156:157], v[50:51], v[54:55]
	v_pk_add_f32 v[158:159], v[48:49], v[52:53]
	v_pk_add_f32 v[4:5], v[12:13], 1.0 op_sel_hi:[1,0]
	v_pk_add_f32 v[6:7], v[14:15], 1.0 op_sel_hi:[1,0]
	v_pk_mul_f32 v[160:161], v[38:39], v[4:5]
	v_pk_mul_f32 v[162:163], v[36:37], v[6:7]
	v_pk_add_f32 v[12:13], v[62:63], v[66:67]
	v_pk_add_f32 v[14:15], v[60:61], v[64:65]
	v_pk_add_f32 v[164:165], v[70:71], v[74:75]
	v_pk_add_f32 v[166:167], v[68:69], v[72:73]
	v_pk_add_f32 v[4:5], v[12:13], 1.0 op_sel_hi:[1,0]
	v_pk_add_f32 v[6:7], v[14:15], 1.0 op_sel_hi:[1,0]
	v_pk_mul_f32 v[168:169], v[58:59], v[4:5]
	v_pk_mul_f32 v[170:171], v[56:57], v[6:7]
	v_pk_add_f32 v[12:13], v[82:83], v[86:87]
	v_pk_add_f32 v[14:15], v[80:81], v[84:85]
	v_pk_add_f32 v[172:173], v[90:91], v[94:95]
	v_pk_add_f32 v[174:175], v[88:89], v[92:93]
	v_pk_add_f32 v[4:5], v[12:13], 1.0 op_sel_hi:[1,0]
	v_pk_add_f32 v[6:7], v[14:15], 1.0 op_sel_hi:[1,0]
	v_pk_mul_f32 v[176:177], v[78:79], v[4:5]
	v_pk_mul_f32 v[178:179], v[76:77], v[6:7]
	v_lshl_add_u64 v[0:1], v[128:129], 0, s[0:1]
	global_load_dwordx4 v[124:127], v[0:1], off nt
	global_load_dwordx4 v[120:123], v[0:1], off offset:1024 nt
	global_load_dwordx4 v[116:119], v[0:1], off offset:2048 nt
	global_load_dwordx4 v[112:115], v[0:1], off offset:3072 nt
	s_lshl_b64 s[0:1], s[34:35], 12
	v_lshl_add_u64 v[0:1], v[128:129], 0, s[0:1]
	global_load_dwordx4 v[108:111], v[0:1], off nt
	global_load_dwordx4 v[104:107], v[0:1], off offset:1024 nt
	global_load_dwordx4 v[100:103], v[0:1], off offset:2048 nt
	global_load_dwordx4 v[96:99], v[0:1], off offset:3072 nt
	s_lshl_b64 s[0:1], s[30:31], 12
	v_lshl_add_u64 v[0:1], v[128:129], 0, s[0:1]
	global_load_dwordx4 v[92:95], v[0:1], off nt
	global_load_dwordx4 v[88:91], v[0:1], off offset:1024 nt
	global_load_dwordx4 v[84:87], v[0:1], off offset:2048 nt
	global_load_dwordx4 v[80:83], v[0:1], off offset:3072 nt
	s_lshl_b64 s[0:1], s[28:29], 12
	v_lshl_add_u64 v[0:1], v[128:129], 0, s[0:1]
	global_load_dwordx4 v[76:79], v[0:1], off nt
	global_load_dwordx4 v[72:75], v[0:1], off offset:1024 nt
	global_load_dwordx4 v[68:71], v[0:1], off offset:2048 nt
	global_load_dwordx4 v[64:67], v[0:1], off offset:3072 nt
	s_lshl_b64 s[0:1], s[26:27], 12
	v_lshl_add_u64 v[0:1], v[128:129], 0, s[0:1]
	s_lshl_b64 s[0:1], s[24:25], 12
	global_load_dwordx4 v[60:63], v[0:1], off nt
	global_load_dwordx4 v[56:59], v[0:1], off offset:1024 nt
	global_load_dwordx4 v[52:55], v[0:1], off offset:2048 nt
	global_load_dwordx4 v[48:51], v[0:1], off offset:3072 nt
	v_lshl_add_u64 v[0:1], v[128:129], 0, s[0:1]
	s_lshl_b64 s[0:1], s[22:23], 12
	global_load_dwordx4 v[44:47], v[0:1], off nt
	global_load_dwordx4 v[40:43], v[0:1], off offset:1024 nt
	global_load_dwordx4 v[36:39], v[0:1], off offset:2048 nt
	global_load_dwordx4 v[32:35], v[0:1], off offset:3072 nt
	v_lshl_add_u64 v[0:1], v[128:129], 0, s[0:1]
	s_lshl_b64 s[0:1], s[20:21], 12
	global_load_dwordx4 v[28:31], v[0:1], off nt
	global_load_dwordx4 v[24:27], v[0:1], off offset:1024 nt
	global_load_dwordx4 v[20:23], v[0:1], off offset:2048 nt
	global_load_dwordx4 v[16:19], v[0:1], off offset:3072 nt
	v_lshl_add_u64 v[0:1], v[128:129], 0, s[0:1]
	s_lshl_b64 s[0:1], s[18:19], 11
	v_lshl_add_u64 v[210:211], v[130:131], 0, s[0:1]
	global_load_dwordx4 v[12:15], v[0:1], off nt
	global_load_dwordx4 v[8:11], v[0:1], off offset:1024 nt
	global_load_dwordx4 v[4:7], v[0:1], off offset:2048 nt
	s_nop 0
	global_load_dwordx4 v[0:3], v[0:1], off offset:3072 nt
	s_waitcnt vmcnt(31)
	v_pk_mul_f32 v[200:201], v[126:127], v[126:127]
	v_pk_mul_f32 v[202:203], v[124:125], v[124:125]
	s_waitcnt vmcnt(28)
	v_mul_f32_e32 v147, v112, v112
	v_pk_mov_b32 v[204:205], v[202:203], v[200:201] op_sel:[1,0]
	v_mov_b32_e32 v203, v201
	v_pk_add_f32 v[200:201], v[204:205], v[202:203]
	v_pk_mul_f32 v[202:203], v[122:123], v[122:123]
	v_pk_mul_f32 v[204:205], v[120:121], v[120:121]
	v_mul_f32_e32 v199, v113, v113
	v_pk_mov_b32 v[206:207], v[204:205], v[202:203] op_sel:[1,0]
	v_mov_b32_e32 v205, v203
	v_pk_add_f32 v[202:203], v[206:207], v[204:205]
	v_pk_add_f32 v[200:201], v[200:201], v[200:201] op_sel:[0,1] op_sel_hi:[1,0]
	v_pk_add_f32 v[202:203], v[202:203], v[202:203] op_sel:[0,1] op_sel_hi:[1,0]
	v_mov_b32_e32 v201, v147
	v_mov_b32_e32 v203, v199
	v_pk_add_f32 v[200:201], v[200:201], v[202:203]
	v_mul_f32_e32 v202, v117, v117
	v_mul_f32_e32 v204, v114, v114
	v_pk_fma_f32 v[202:203], v[116:117], v[116:117], v[202:203] op_sel_hi:[1,1,0]
	v_mul_f32_e32 v206, v115, v115
	v_mov_b32_e32 v203, v204
	v_mul_f32_e32 v204, v119, v119
	v_pk_fma_f32 v[204:205], v[118:119], v[118:119], v[204:205] op_sel_hi:[1,1,0]
	s_waitcnt vmcnt(27)
	v_mul_f32_e32 v199, v109, v109
	v_mov_b32_e32 v205, v206
	v_pk_add_f32 v[202:203], v[202:203], v[204:205]
	v_fmac_f32_e32 v199, v108, v108
	v_pk_add_f32 v[200:201], v[200:201], v[202:203]
	s_waitcnt vmcnt(22)
	v_mul_f32_e32 v202, v91, v91
	v_add_f32_e32 v147, v200, v201
	v_mul_f32_e32 v200, v111, v111
	v_fmac_f32_e32 v200, v110, v110
	v_add_f32_e32 v199, v199, v200
	v_mul_f32_e32 v200, v105, v105
	v_mul_f32_e32 v201, v107, v107
	v_fmac_f32_e32 v200, v104, v104
	v_fmac_f32_e32 v201, v106, v106
	v_add_f32_e32 v200, v200, v201
	v_add_f32_e32 v199, v199, v200
	v_mul_f32_e32 v200, v101, v101
	v_mul_f32_e32 v201, v103, v103
	v_fmac_f32_e32 v200, v100, v100
	v_fmac_f32_e32 v201, v102, v102
	v_add_f32_e32 v200, v200, v201
	v_add_f32_e32 v199, v199, v200
	v_mul_f32_e32 v200, v97, v97
	v_mul_f32_e32 v201, v99, v99
	v_fmac_f32_e32 v200, v96, v96
	v_fmac_f32_e32 v201, v98, v98
	v_add_f32_e32 v200, v200, v201
	v_add_f32_e32 v199, v199, v200
	v_mul_f32_e32 v200, v93, v93
	v_mul_f32_e32 v201, v95, v95
	v_fmac_f32_e32 v200, v92, v92
	v_fmac_f32_e32 v201, v94, v94
	v_add_f32_e32 v200, v200, v201
	v_mul_f32_e32 v201, v89, v89
	v_fmac_f32_e32 v201, v88, v88
	v_fmac_f32_e32 v202, v90, v90
	v_add_f32_e32 v201, v201, v202
	v_add_f32_e32 v200, v200, v201
	s_waitcnt vmcnt(21)
	v_mul_f32_e32 v201, v85, v85
	v_mul_f32_e32 v202, v87, v87
	v_fmac_f32_e32 v201, v84, v84
	v_fmac_f32_e32 v202, v86, v86
	v_add_f32_e32 v201, v201, v202
	v_add_f32_e32 v200, v200, v201
	s_waitcnt vmcnt(20)
	v_mul_f32_e32 v201, v81, v81
	v_mul_f32_e32 v202, v83, v83
	v_fmac_f32_e32 v201, v80, v80
	v_fmac_f32_e32 v202, v82, v82
	v_add_f32_e32 v201, v201, v202
	v_add_f32_e32 v200, v200, v201
	s_waitcnt vmcnt(19)
	v_mul_f32_e32 v201, v77, v77
	v_mul_f32_e32 v202, v79, v79
	v_fmac_f32_e32 v201, v76, v76
	v_fmac_f32_e32 v202, v78, v78
	v_add_f32_e32 v201, v201, v202
	s_waitcnt vmcnt(18)
	v_mul_f32_e32 v202, v73, v73
	v_mul_f32_e32 v203, v75, v75
	v_fmac_f32_e32 v202, v72, v72
	v_fmac_f32_e32 v203, v74, v74
	v_add_f32_e32 v202, v202, v203
	v_add_f32_e32 v201, v201, v202
	s_waitcnt vmcnt(17)
	v_mul_f32_e32 v202, v69, v69
	v_mul_f32_e32 v203, v71, v71
	v_fmac_f32_e32 v202, v68, v68
	v_fmac_f32_e32 v203, v70, v70
	v_add_f32_e32 v202, v202, v203
	v_add_f32_e32 v201, v201, v202
	s_waitcnt vmcnt(16)
	v_mul_f32_e32 v202, v65, v65
	v_mul_f32_e32 v203, v67, v67
	v_fmac_f32_e32 v202, v64, v64
	v_fmac_f32_e32 v203, v66, v66
	v_add_f32_e32 v202, v202, v203
	v_add_f32_e32 v201, v201, v202
	ds_bpermute_b32 v202, v184, v147
	s_waitcnt lgkmcnt(0)
	v_add_f32_e32 v147, v147, v202
	ds_bpermute_b32 v202, v184, v199
	s_waitcnt lgkmcnt(0)
	v_add_f32_e32 v199, v199, v202
	ds_bpermute_b32 v202, v184, v200
	s_waitcnt lgkmcnt(0)
	v_add_f32_e32 v200, v200, v202
	ds_bpermute_b32 v202, v184, v201
	s_waitcnt lgkmcnt(0)
	v_add_f32_e32 v201, v201, v202
	ds_bpermute_b32 v202, v185, v147
	s_waitcnt lgkmcnt(0)
	v_add_f32_e32 v147, v147, v202
	ds_bpermute_b32 v202, v185, v199
	s_waitcnt lgkmcnt(0)
	v_add_f32_e32 v199, v199, v202
	ds_bpermute_b32 v202, v185, v200
	s_waitcnt lgkmcnt(0)
	v_add_f32_e32 v200, v200, v202
	ds_bpermute_b32 v202, v185, v201
	s_waitcnt lgkmcnt(0)
	v_add_f32_e32 v201, v201, v202
	ds_bpermute_b32 v202, v186, v147
	s_waitcnt lgkmcnt(0)
	v_add_f32_e32 v147, v147, v202
	ds_bpermute_b32 v202, v186, v199
	s_waitcnt lgkmcnt(0)
	v_add_f32_e32 v199, v199, v202
	ds_bpermute_b32 v202, v186, v200
	s_waitcnt lgkmcnt(0)
	v_add_f32_e32 v200, v200, v202
	ds_bpermute_b32 v202, v186, v201
	s_waitcnt lgkmcnt(0)
	v_add_f32_e32 v201, v201, v202
	ds_bpermute_b32 v202, v187, v147
	s_waitcnt lgkmcnt(0)
	v_add_f32_e32 v147, v147, v202
	ds_bpermute_b32 v202, v187, v199
	s_waitcnt lgkmcnt(0)
	v_add_f32_e32 v199, v199, v202
	ds_bpermute_b32 v202, v187, v200
	s_waitcnt lgkmcnt(0)
	v_add_f32_e32 v200, v200, v202
	ds_bpermute_b32 v202, v187, v201
	s_waitcnt lgkmcnt(0)
	v_add_f32_e32 v202, v201, v202
	ds_bpermute_b32 v201, v188, v147
	s_waitcnt lgkmcnt(0)
	v_add_f32_e32 v147, v147, v201
	ds_bpermute_b32 v201, v188, v199
	s_waitcnt lgkmcnt(0)
	v_add_f32_e32 v203, v199, v201
	ds_bpermute_b32 v199, v188, v200
	ds_bpermute_b32 v204, v189, v203
	s_waitcnt lgkmcnt(1)
	v_add_f32_e32 v201, v200, v199
	ds_bpermute_b32 v200, v189, v147
	ds_bpermute_b32 v199, v188, v202
	s_waitcnt lgkmcnt(1)
	v_add_f32_e32 v147, v147, v200
	v_fmamk_f32 v147, v147, 0x3a800000, v194
	v_rsq_f32_e32 v206, v147
	s_waitcnt lgkmcnt(0)
	v_add_f32_e32 v199, v202, v199
	ds_bpermute_b32 v202, v189, v201
	ds_bpermute_b32 v200, v189, v199
	v_pk_mul_f32 v[212:213], v[124:125], v[206:207] op_sel_hi:[1,0]
	v_pk_mul_f32 v[124:125], v[126:127], v[206:207] op_sel_hi:[1,0]
	v_pk_fma_f32 v[126:127], v[154:155], v[212:213], v[150:151]
	v_pk_fma_f32 v[124:125], v[152:153], v[124:125], v[148:149]
	v_cvt_pk_bf16_f32 v212, v126, v127
	s_nop 0
	v_cvt_pk_bf16_f32 v213, v124, v125
	global_store_dwordx2 v[210:211], v[212:213], off
	v_pk_mul_f32 v[212:213], v[120:121], v[206:207] op_sel_hi:[1,0]
	v_pk_mul_f32 v[120:121], v[122:123], v[206:207] op_sel_hi:[1,0]
	v_pk_fma_f32 v[122:123], v[162:163], v[212:213], v[158:159]
	v_pk_fma_f32 v[120:121], v[160:161], v[120:121], v[156:157]
	v_cvt_pk_bf16_f32 v212, v122, v123
	s_nop 0
	v_cvt_pk_bf16_f32 v213, v120, v121
	global_store_dwordx2 v[210:211], v[212:213], off offset:512
	v_pk_mul_f32 v[212:213], v[116:117], v[206:207] op_sel_hi:[1,0]
	v_pk_mul_f32 v[116:117], v[118:119], v[206:207] op_sel_hi:[1,0]
	v_pk_fma_f32 v[118:119], v[170:171], v[212:213], v[166:167]
	v_pk_fma_f32 v[116:117], v[168:169], v[116:117], v[164:165]
	v_cvt_pk_bf16_f32 v212, v118, v119
	s_nop 0
	v_cvt_pk_bf16_f32 v213, v116, v117
	global_store_dwordx2 v[210:211], v[212:213], off offset:1024
	v_pk_mul_f32 v[212:213], v[112:113], v[206:207] op_sel_hi:[1,0]
	v_pk_mul_f32 v[112:113], v[114:115], v[206:207] op_sel_hi:[1,0]
	v_pk_fma_f32 v[114:115], v[178:179], v[212:213], v[174:175]
	v_pk_fma_f32 v[112:113], v[176:177], v[112:113], v[172:173]
	v_cvt_pk_bf16_f32 v206, v114, v115
	s_nop 0
	v_cvt_pk_bf16_f32 v207, v112, v113
	global_store_dwordx2 v[210:211], v[206:207], off offset:1536
	ds_read_b128 v[210:213], v182
	s_waitcnt lgkmcnt(0)
	v_mul_f32_e32 v147, v127, v211
	v_mul_f32_e32 v205, v125, v213
	v_fmac_f32_e32 v147, v126, v210
	v_fmac_f32_e32 v205, v124, v212
	ds_read_b128 v[210:213], v182 offset:1024
	v_add_f32_e32 v147, v147, v205
	v_add_f32_e32 v147, 0, v147
	s_waitcnt lgkmcnt(0)
	v_mul_f32_e32 v205, v123, v211
	v_mul_f32_e32 v206, v121, v213
	v_fmac_f32_e32 v205, v122, v210
	v_fmac_f32_e32 v206, v120, v212
	ds_read_b128 v[210:213], v182 offset:2048
	v_add_f32_e32 v205, v205, v206
	v_add_f32_e32 v147, v147, v205
	s_waitcnt lgkmcnt(0)
	v_mul_f32_e32 v205, v119, v211
	v_mul_f32_e32 v206, v117, v213
	v_fmac_f32_e32 v205, v118, v210
	v_fmac_f32_e32 v206, v116, v212
	ds_read_b128 v[210:213], v182 offset:3072
	v_add_f32_e32 v205, v205, v206
	v_add_f32_e32 v147, v147, v205
	s_waitcnt lgkmcnt(0)
	v_mul_f32_e32 v205, v115, v211
	v_mul_f32_e32 v206, v113, v213
	v_fmac_f32_e32 v205, v114, v210
	v_fmac_f32_e32 v206, v112, v212
	ds_read_b128 v[210:213], v182 offset:4096
	v_add_f32_e32 v205, v205, v206
	v_add_f32_e32 v147, v147, v205
	s_waitcnt lgkmcnt(0)
	v_mul_f32_e32 v205, v127, v211
	v_mul_f32_e32 v206, v125, v213
	v_fmac_f32_e32 v205, v126, v210
	v_fmac_f32_e32 v206, v124, v212
	ds_read_b128 v[210:213], v182 offset:5120
	v_add_f32_e32 v205, v205, v206
	v_add_f32_e32 v205, 0, v205
	s_waitcnt lgkmcnt(0)
	v_mul_f32_e32 v206, v123, v211
	v_mul_f32_e32 v207, v121, v213
	v_fmac_f32_e32 v206, v122, v210
	v_fmac_f32_e32 v207, v120, v212
	ds_read_b128 v[210:213], v182 offset:6144
	v_add_f32_e32 v206, v206, v207
	v_add_f32_e32 v205, v205, v206
	s_waitcnt lgkmcnt(0)
	v_mul_f32_e32 v206, v119, v211
	v_mul_f32_e32 v207, v117, v213
	v_fmac_f32_e32 v206, v118, v210
	v_fmac_f32_e32 v207, v116, v212
	ds_read_b128 v[210:213], v182 offset:7168
	v_add_f32_e32 v206, v206, v207
	v_add_f32_e32 v205, v205, v206
	s_waitcnt lgkmcnt(0)
	v_mul_f32_e32 v206, v115, v211
	v_mul_f32_e32 v207, v113, v213
	v_fmac_f32_e32 v206, v114, v210
	v_fmac_f32_e32 v207, v112, v212
	ds_read_b128 v[210:213], v182 offset:8192
	v_add_f32_e32 v206, v206, v207
	v_add_f32_e32 v205, v205, v206
	s_waitcnt lgkmcnt(0)
	v_mul_f32_e32 v206, v127, v211
	v_mul_f32_e32 v207, v125, v213
	v_fmac_f32_e32 v206, v126, v210
	v_fmac_f32_e32 v207, v124, v212
	ds_read_b128 v[210:213], v182 offset:9216
	v_add_f32_e32 v206, v206, v207
	v_add_f32_e32 v206, 0, v206
	s_waitcnt lgkmcnt(0)
	v_mul_f32_e32 v207, v123, v211
	v_mul_f32_e32 v208, v121, v213
	v_fmac_f32_e32 v207, v122, v210
	v_fmac_f32_e32 v208, v120, v212
	ds_read_b128 v[210:213], v182 offset:10240
	v_add_f32_e32 v207, v207, v208
	v_add_f32_e32 v206, v206, v207
	s_waitcnt lgkmcnt(0)
	v_mul_f32_e32 v207, v119, v211
	v_mul_f32_e32 v208, v117, v213
	v_fmac_f32_e32 v207, v118, v210
	v_fmac_f32_e32 v208, v116, v212
	ds_read_b128 v[210:213], v182 offset:11264
	v_add_f32_e32 v207, v207, v208
	v_add_f32_e32 v206, v206, v207
	s_waitcnt lgkmcnt(0)
	v_mul_f32_e32 v207, v115, v211
	v_mul_f32_e32 v208, v113, v213
	v_fmac_f32_e32 v207, v114, v210
	v_fmac_f32_e32 v208, v112, v212
	ds_read_b128 v[210:213], v182 offset:12288
	v_add_f32_e32 v207, v207, v208
	v_add_f32_e32 v206, v206, v207
	s_waitcnt lgkmcnt(0)
	v_mul_f32_e32 v207, v127, v211
	v_mul_f32_e32 v208, v125, v213
	v_fmac_f32_e32 v207, v126, v210
	v_fmac_f32_e32 v208, v124, v212
	ds_read_b128 v[210:213], v182 offset:13312
	v_add_f32_e32 v207, v207, v208
	v_add_f32_e32 v207, 0, v207
	s_waitcnt lgkmcnt(0)
	v_mul_f32_e32 v208, v123, v211
	v_mul_f32_e32 v209, v121, v213
	v_fmac_f32_e32 v208, v122, v210
	v_fmac_f32_e32 v209, v120, v212
	ds_read_b128 v[210:213], v182 offset:14336
	v_add_f32_e32 v208, v208, v209
	v_add_f32_e32 v207, v207, v208
	s_waitcnt lgkmcnt(0)
	v_mul_f32_e32 v208, v119, v211
	v_mul_f32_e32 v209, v117, v213
	v_fmac_f32_e32 v208, v118, v210
	v_fmac_f32_e32 v209, v116, v212
	ds_read_b128 v[210:213], v182 offset:15360
	v_add_f32_e32 v208, v208, v209
	v_add_f32_e32 v207, v207, v208
	s_waitcnt lgkmcnt(0)
	v_mul_f32_e32 v208, v115, v211
	v_mul_f32_e32 v209, v113, v213
	v_fmac_f32_e32 v208, v114, v210
	v_fmac_f32_e32 v209, v112, v212
	ds_read_b128 v[210:213], v182 offset:16384
	v_add_f32_e32 v208, v208, v209
	v_add_f32_e32 v207, v207, v208
	s_waitcnt lgkmcnt(0)
	v_mul_f32_e32 v208, v127, v211
	v_mul_f32_e32 v209, v125, v213
	v_fmac_f32_e32 v208, v126, v210
	v_fmac_f32_e32 v209, v124, v212
	ds_read_b128 v[210:213], v182 offset:17408
	v_add_f32_e32 v208, v208, v209
	v_add_f32_e32 v208, 0, v208
	s_waitcnt lgkmcnt(0)
	v_mul_f32_e32 v209, v123, v211
	v_fmac_f32_e32 v209, v122, v210
	v_mul_f32_e32 v210, v121, v213
	v_fmac_f32_e32 v210, v120, v212
	v_add_f32_e32 v209, v209, v210
	ds_read_b128 v[210:213], v182 offset:18432
	v_add_f32_e32 v208, v208, v209
	s_waitcnt lgkmcnt(0)
	v_mul_f32_e32 v209, v119, v211
	v_fmac_f32_e32 v209, v118, v210
	v_mul_f32_e32 v210, v117, v213
	v_fmac_f32_e32 v210, v116, v212
	v_add_f32_e32 v209, v209, v210
	ds_read_b128 v[210:213], v182 offset:19456
	v_add_f32_e32 v208, v208, v209
	s_waitcnt lgkmcnt(0)
	v_mul_f32_e32 v209, v115, v211
	v_fmac_f32_e32 v209, v114, v210
	v_mul_f32_e32 v210, v113, v213
	v_fmac_f32_e32 v210, v112, v212
	v_add_f32_e32 v209, v209, v210
	ds_read_b128 v[210:213], v182 offset:20480
	v_add_f32_e32 v209, v208, v209
	s_waitcnt lgkmcnt(0)
	v_mul_f32_e32 v208, v127, v211
	v_fmac_f32_e32 v208, v126, v210
	v_mul_f32_e32 v210, v125, v213
	v_fmac_f32_e32 v210, v124, v212
	v_add_f32_e32 v208, v208, v210
	ds_read_b128 v[210:213], v182 offset:21504
	v_add_f32_e32 v208, 0, v208
	s_waitcnt lgkmcnt(0)
	v_mul_f32_e32 v211, v123, v211
	v_fmac_f32_e32 v211, v122, v210
	v_mul_f32_e32 v210, v121, v213
	v_fmac_f32_e32 v210, v120, v212
	v_add_f32_e32 v210, v211, v210
	v_add_f32_e32 v208, v208, v210
	ds_read_b128 v[210:213], v182 offset:22528
	s_waitcnt lgkmcnt(0)
	v_mul_f32_e32 v211, v119, v211
	v_fmac_f32_e32 v211, v118, v210
	v_mul_f32_e32 v210, v117, v213
	v_fmac_f32_e32 v210, v116, v212
	v_add_f32_e32 v210, v211, v210
	v_add_f32_e32 v208, v208, v210
	ds_read_b128 v[210:213], v182 offset:23552
	s_waitcnt lgkmcnt(0)
	v_mul_f32_e32 v211, v115, v211
	v_fmac_f32_e32 v211, v114, v210
	v_mul_f32_e32 v210, v113, v213
	v_fmac_f32_e32 v210, v112, v212
	ds_read_b128 v[212:215], v182 offset:24576
	v_add_f32_e32 v210, v211, v210
	v_add_f32_e32 v210, v208, v210
	s_waitcnt lgkmcnt(0)
	v_mul_f32_e32 v208, v127, v213
	v_mul_f32_e32 v211, v125, v215
	v_fmac_f32_e32 v208, v126, v212
	v_fmac_f32_e32 v211, v124, v214
	ds_read_b128 v[212:215], v182 offset:25600
	v_add_f32_e32 v208, v208, v211
	v_add_f32_e32 v208, 0, v208
	s_waitcnt lgkmcnt(0)
	v_mul_f32_e32 v211, v123, v213
	v_fmac_f32_e32 v211, v122, v212
	v_mul_f32_e32 v212, v121, v215
	v_fmac_f32_e32 v212, v120, v214
	v_add_f32_e32 v211, v211, v212
	ds_read_b128 v[212:215], v182 offset:26624
	v_add_f32_e32 v208, v208, v211
	s_waitcnt lgkmcnt(0)
	v_mul_f32_e32 v211, v119, v213
	v_fmac_f32_e32 v211, v118, v212
	v_mul_f32_e32 v212, v117, v215
	v_fmac_f32_e32 v212, v116, v214
	v_add_f32_e32 v211, v211, v212
	ds_read_b128 v[212:215], v182 offset:27648
	v_add_f32_e32 v208, v208, v211
	s_waitcnt lgkmcnt(0)
	v_mul_f32_e32 v211, v115, v213
	v_fmac_f32_e32 v211, v114, v212
	v_mul_f32_e32 v212, v113, v215
	v_fmac_f32_e32 v212, v112, v214
	v_add_f32_e32 v211, v211, v212
	ds_read_b128 v[212:215], v182 offset:28672
	v_add_f32_e32 v208, v208, v211
	s_waitcnt lgkmcnt(0)
	v_mul_f32_e32 v127, v127, v213
	v_mul_f32_e32 v125, v125, v215
	v_fmac_f32_e32 v127, v126, v212
	v_fmac_f32_e32 v125, v124, v214
	v_add_f32_e32 v124, v127, v125
	v_add_f32_e32 v211, 0, v124
	ds_read_b128 v[124:127], v182 offset:29696
	s_waitcnt lgkmcnt(0)
	v_mul_f32_e32 v123, v123, v125
	v_mul_f32_e32 v121, v121, v127
	v_fmac_f32_e32 v123, v122, v124
	v_fmac_f32_e32 v121, v120, v126
	v_add_f32_e32 v120, v123, v121
	v_add_f32_e32 v124, v211, v120
	ds_read_b128 v[120:123], v182 offset:30720
	s_waitcnt lgkmcnt(0)
	v_mul_f32_e32 v119, v119, v121
	v_mul_f32_e32 v117, v117, v123
	v_fmac_f32_e32 v119, v118, v120
	v_fmac_f32_e32 v117, v116, v122
	v_add_f32_e32 v116, v119, v117
	v_add_f32_e32 v120, v124, v116
	ds_read_b128 v[116:119], v182 offset:31744
	s_waitcnt lgkmcnt(0)
	v_mul_f32_e32 v115, v115, v117
	v_mul_f32_e32 v113, v113, v119
	v_fmac_f32_e32 v115, v114, v116
	v_fmac_f32_e32 v113, v112, v118
	v_add_f32_e32 v112, v115, v113
	v_cndmask_b32_e32 v113, v147, v209, vcc
	ds_bpermute_b32 v113, v184, v113
	v_cndmask_b32_e32 v114, v209, v147, vcc
	v_cndmask_b32_e32 v115, v210, v205, vcc
	v_add_f32_e32 v112, v120, v112
	v_cndmask_b32_e32 v116, v208, v206, vcc
	s_waitcnt lgkmcnt(0)
	v_add_f32_e32 v113, v114, v113
	v_cndmask_b32_e32 v114, v205, v210, vcc
	ds_bpermute_b32 v114, v184, v114
	s_waitcnt lgkmcnt(0)
	v_add_f32_e32 v114, v115, v114
	v_cndmask_b32_e32 v115, v206, v208, vcc
	ds_bpermute_b32 v115, v184, v115
	s_waitcnt lgkmcnt(0)
	v_add_f32_e32 v115, v116, v115
	v_cndmask_b32_e32 v116, v207, v112, vcc
	ds_bpermute_b32 v116, v184, v116
	v_cndmask_b32_e32 v112, v112, v207, vcc
	s_waitcnt lgkmcnt(0)
	v_add_f32_e32 v112, v112, v116
	v_cndmask_b32_e64 v116, v113, v115, s[4:5]
	v_cndmask_b32_e64 v113, v115, v113, s[4:5]
	ds_bpermute_b32 v115, v185, v116
	s_waitcnt lgkmcnt(0)
	v_add_f32_e32 v113, v113, v115
	v_cndmask_b32_e64 v115, v114, v112, s[4:5]
	v_cndmask_b32_e64 v112, v112, v114, s[4:5]
	ds_bpermute_b32 v114, v185, v115
	s_waitcnt lgkmcnt(0)
	v_add_f32_e32 v112, v112, v114
	v_cndmask_b32_e64 v114, v113, v112, s[6:7]
	v_cndmask_b32_e64 v112, v112, v113, s[6:7]
	ds_bpermute_b32 v113, v186, v114
	s_waitcnt lgkmcnt(0)
	v_add_f32_e32 v112, v112, v113
	ds_bpermute_b32 v113, v187, v112
	s_waitcnt lgkmcnt(0)
	v_add_f32_e32 v112, v112, v113
	ds_bpermute_b32 v113, v188, v112
	s_waitcnt lgkmcnt(0)
	v_add_f32_e32 v112, v112, v113
	ds_bpermute_b32 v113, v189, v112
	s_and_saveexec_b64 s[36:37], s[8:9]
	s_cbranch_execz .LBB0_94
	v_mov_b32_e32 v114, v216
	s_waitcnt lgkmcnt(0)
	v_add_f32_e32 v115, v112, v113
	s_lshl_b32 s0, s38, 13
	v_lshl_or_b32 v112, s38, 3, v183
	s_sub_i32 s38, s18, s0
	v_ashrrev_i32_e32 v113, 31, v112
	v_lshlrev_b64 v[112:113], 15, v[112:113]
	s_ashr_i32 s39, s38, 31
	v_lshl_add_u64 v[112:113], s[12:13], 0, v[112:113]
	v_lshl_add_u64 v[112:113], s[38:39], 2, v[112:113]
	v_add_f32_e32 v114, v115, v114
	v_mul_f32_e64 v115, |v114|, s41
	v_exp_f32_e32 v205, v115
	v_min_f32_e32 v206, 0, v114
	v_add_f32_e32 v116, 1.0, v205
	v_add_f32_e32 v117, -1.0, v116
	v_frexp_mant_f32_e32 v118, v116
	v_cvt_f64_f32_e32 v[114:115], v116
	v_sub_f32_e32 v119, v117, v116
	v_frexp_exp_i32_f64_e32 v114, v[114:115]
	v_cmp_gt_f32_e64 s[0:1], s42, v118
	v_sub_f32_e32 v117, v205, v117
	v_add_f32_e32 v115, 1.0, v119
	v_subbrev_co_u32_e64 v114, s[0:1], 0, v114, s[0:1]
	v_add_f32_e32 v115, v117, v115
	v_sub_u32_e32 v117, 0, v114
	v_ldexp_f32 v116, v116, v117
	v_add_f32_e32 v118, -1.0, v116
	v_add_f32_e32 v119, 1.0, v116
	v_ldexp_f32 v115, v115, v117
	v_add_f32_e32 v117, 1.0, v118
	v_add_f32_e32 v120, -1.0, v119
	v_sub_f32_e32 v117, v116, v117
	v_sub_f32_e32 v116, v116, v120
	v_add_f32_e32 v120, v115, v117
	v_add_f32_e32 v115, v115, v116
	v_add_f32_e32 v122, v119, v115
	v_rcp_f32_e32 v123, v122
	v_add_f32_e32 v117, v118, v120
	v_sub_f32_e32 v118, v117, v118
	v_sub_f32_e32 v116, v122, v119
	v_mul_f32_e32 v125, v117, v123
	v_sub_f32_e32 v124, v120, v118
	v_mul_f32_e32 v118, v122, v125
	v_sub_f32_e32 v115, v115, v116
	v_fma_f32 v120, v125, v122, -v118
	v_fmac_f32_e32 v120, v125, v115
	v_add_f32_e32 v116, v118, v120
	v_sub_f32_e32 v119, v117, v116
	v_mov_b32_e32 v121, v116
	v_pk_add_f32 v[116:117], v[116:117], v[118:119] neg_lo:[0,1] neg_hi:[0,1]
	v_cvt_f32_i32_e32 v114, v114
	v_pk_add_f32 v[116:117], v[116:117], v[120:121] neg_lo:[0,1] neg_hi:[0,1]
	v_cmp_neq_f32_e64 s[0:1], s44, v205
	v_add_f32_e32 v117, v124, v117
	v_add_f32_e32 v116, v116, v117
	v_add_f32_e32 v117, v119, v116
	v_mul_f32_e32 v121, v123, v117
	v_mul_f32_e32 v118, v122, v121
	v_sub_f32_e32 v119, v119, v117
	v_add_f32_e32 v126, v125, v121
	v_fma_f32 v120, v121, v122, -v118
	v_add_f32_e32 v124, v116, v119
	v_sub_f32_e32 v116, v126, v125
	v_fmac_f32_e32 v120, v121, v115
	v_sub_f32_e32 v115, v121, v116
	v_add_f32_e32 v116, v118, v120
	v_sub_f32_e32 v119, v117, v116
	v_mov_b32_e32 v121, v116
	v_pk_add_f32 v[116:117], v[116:117], v[118:119] neg_lo:[0,1] neg_hi:[0,1]
	s_nop 0
	v_pk_add_f32 v[116:117], v[116:117], v[120:121] neg_lo:[0,1] neg_hi:[0,1]
	s_nop 0
	v_add_f32_e32 v117, v124, v117
	v_add_f32_e32 v116, v116, v117
	v_add_f32_e32 v116, v119, v116
	v_mul_f32_e32 v116, v123, v116
	v_add_f32_e32 v115, v115, v116
	v_add_f32_e32 v116, v126, v115
	v_mul_f32_e32 v118, v116, v116
	v_sub_f32_e32 v119, v116, v126
	v_fmamk_f32 v120, v118, 0x3e9b6dac, v195
	v_sub_f32_e32 v119, v115, v119
	v_mul_f32_e32 v115, v116, v118
	v_fmaak_f32 v147, v118, v120, 0x3f2aaada
	v_ldexp_f32 v121, v119, 1
	v_pk_mul_f32 v[118:119], v[114:115], v[146:147]
	v_ldexp_f32 v117, v116, 1
	v_fma_f32 v116, v114, s43, -v118
	v_fmac_f32_e32 v116, 0xb102e308, v114
	v_pk_add_f32 v[114:115], v[118:119], v[116:117]
	v_mov_b32_e32 v120, v118
	v_sub_f32_e32 v124, v115, v117
	v_pk_add_f32 v[122:123], v[114:115], v[118:119] neg_lo:[0,1] neg_hi:[0,1]
	v_sub_f32_e32 v118, v119, v124
	v_add_f32_e32 v121, v121, v118
	v_pk_add_f32 v[118:119], v[114:115], v[120:121]
	v_mov_b32_e32 v117, v114
	v_mov_b32_e32 v123, v119
	v_pk_add_f32 v[126:127], v[116:117], v[122:123] neg_lo:[0,1] neg_hi:[0,1]
	v_pk_add_f32 v[116:117], v[116:117], v[122:123]
	v_mov_b32_e32 v125, v114
	v_pk_add_f32 v[122:123], v[116:117], v[114:115] op_sel:[1,0] op_sel_hi:[0,1] neg_lo:[0,1] neg_hi:[0,1]
	v_mov_b32_e32 v124, v121
	v_mov_b32_e32 v120, v119
	v_mov_b32_e32 v121, v117
	v_pk_mov_b32 v[114:115], v[114:115], v[122:123] op_sel:[1,0]
	v_pk_add_f32 v[118:119], v[118:119], v[122:123] op_sel_hi:[1,0] neg_lo:[0,1] neg_hi:[0,1]
	v_pk_add_f32 v[114:115], v[120:121], v[114:115] neg_lo:[0,1] neg_hi:[0,1]
	v_mov_b32_e32 v118, v126
	v_pk_add_f32 v[114:115], v[124:125], v[114:115] neg_lo:[0,1] neg_hi:[0,1]
	v_mov_b32_e32 v127, v117
	v_pk_add_f32 v[118:119], v[118:119], v[114:115]
	s_nop 0
	v_pk_add_f32 v[120:121], v[118:119], v[118:119] op_sel:[0,1] op_sel_hi:[1,0]
	s_nop 0
	v_pk_add_f32 v[116:117], v[116:117], v[120:121] op_sel:[1,0] op_sel_hi:[0,1]
	v_mov_b32_e32 v119, v116
	v_mov_b32_e32 v115, v120
	v_pk_add_f32 v[120:121], v[118:119], v[126:127] neg_lo:[0,1] neg_hi:[0,1]
	s_nop 0
	v_sub_f32_e32 v117, v118, v120
	v_pk_add_f32 v[114:115], v[114:115], v[120:121] neg_lo:[0,1] neg_hi:[0,1]
	v_sub_f32_e32 v117, v126, v117
	v_add_f32_e32 v114, v114, v117
	v_add_f32_e32 v114, v114, v115
	v_add_f32_e32 v114, v116, v114
	v_cndmask_b32_e64 v114, v196, v114, s[0:1]
	v_cmp_ngt_f32_e64 s[0:1], -1.0, v205
	s_nop 1
	v_cndmask_b32_e64 v114, v197, v114, s[0:1]
	v_cmp_neq_f32_e64 s[0:1], -1.0, v205
	s_nop 1
	v_cndmask_b32_e64 v114, v198, v114, s[0:1]
	v_cmp_lt_f32_e64 s[0:1], |v205|, s45
	s_nop 1
	v_cndmask_b32_e64 v114, v114, v205, s[0:1]
	v_sub_f32_e32 v114, v206, v114
	global_store_dword v[112:113], v114, off
.LBB0_94:
	s_or_b64 exec, exec, s[36:37]
	v_add_f32_e32 v112, v203, v204
	v_fmamk_f32 v112, v112, 0x3a800000, v194
	v_rsq_f32_e32 v112, v112
	s_lshl_b64 s[0:1], s[34:35], 11
	v_lshl_add_u64 v[114:115], v[130:131], 0, s[0:1]
	s_waitcnt lgkmcnt(0)
	v_pk_mul_f32 v[110:111], v[110:111], v[112:113] op_sel_hi:[1,0]
	v_pk_mul_f32 v[116:117], v[108:109], v[112:113] op_sel_hi:[1,0]
	v_pk_fma_f32 v[108:109], v[152:153], v[110:111], v[148:149]
	v_pk_fma_f32 v[110:111], v[154:155], v[116:117], v[150:151]
	v_cvt_pk_bf16_f32 v117, v108, v109
	v_pk_mul_f32 v[106:107], v[106:107], v[112:113] op_sel_hi:[1,0]
	v_cvt_pk_bf16_f32 v116, v110, v111
	global_store_dwordx2 v[114:115], v[116:117], off
	v_pk_mul_f32 v[116:117], v[104:105], v[112:113] op_sel_hi:[1,0]
	v_pk_fma_f32 v[104:105], v[160:161], v[106:107], v[156:157]
	v_pk_fma_f32 v[106:107], v[162:163], v[116:117], v[158:159]
	v_cvt_pk_bf16_f32 v117, v104, v105
	v_pk_mul_f32 v[102:103], v[102:103], v[112:113] op_sel_hi:[1,0]
	v_cvt_pk_bf16_f32 v116, v106, v107
	global_store_dwordx2 v[114:115], v[116:117], off offset:512
	v_pk_mul_f32 v[116:117], v[100:101], v[112:113] op_sel_hi:[1,0]
	v_pk_mul_f32 v[98:99], v[98:99], v[112:113] op_sel_hi:[1,0]
	v_pk_mul_f32 v[112:113], v[96:97], v[112:113] op_sel_hi:[1,0]
	v_pk_fma_f32 v[100:101], v[168:169], v[102:103], v[164:165]
	v_pk_fma_f32 v[102:103], v[170:171], v[116:117], v[166:167]
	v_cvt_pk_bf16_f32 v117, v100, v101
	v_pk_fma_f32 v[96:97], v[176:177], v[98:99], v[172:173]
	v_cvt_pk_bf16_f32 v116, v102, v103
	global_store_dwordx2 v[114:115], v[116:117], off offset:1024
	v_pk_fma_f32 v[98:99], v[178:179], v[112:113], v[174:175]
	v_cvt_pk_bf16_f32 v113, v96, v97
	s_nop 0
	v_cvt_pk_bf16_f32 v112, v98, v99
	global_store_dwordx2 v[114:115], v[112:113], off offset:1536
	ds_read_b128 v[112:115], v182
	ds_read_b128 v[116:119], v182 offset:1024
	s_waitcnt lgkmcnt(1)
	v_mul_f32_e32 v113, v111, v113
	v_fmac_f32_e32 v113, v110, v112
	v_mul_f32_e32 v112, v109, v115
	v_fmac_f32_e32 v112, v108, v114
	s_waitcnt lgkmcnt(0)
	v_mul_f32_e32 v117, v107, v117
	v_add_f32_e32 v112, v113, v112
	v_fmac_f32_e32 v117, v106, v116
	v_mul_f32_e32 v116, v105, v119
	v_add_f32_e32 v120, 0, v112
	ds_read_b128 v[112:115], v182 offset:2048
	v_fmac_f32_e32 v116, v104, v118
	v_add_f32_e32 v116, v117, v116
	v_add_f32_e32 v120, v120, v116
	ds_read_b128 v[116:119], v182 offset:3072
	s_waitcnt lgkmcnt(1)
	v_mul_f32_e32 v113, v103, v113
	v_fmac_f32_e32 v113, v102, v112
	v_mul_f32_e32 v112, v101, v115
	v_fmac_f32_e32 v112, v100, v114
	s_waitcnt lgkmcnt(0)
	v_mul_f32_e32 v117, v99, v117
	v_add_f32_e32 v112, v113, v112
	v_fmac_f32_e32 v117, v98, v116
	v_mul_f32_e32 v116, v97, v119
	v_add_f32_e32 v120, v120, v112
	ds_read_b128 v[112:115], v182 offset:4096
	v_fmac_f32_e32 v116, v96, v118
	v_add_f32_e32 v116, v117, v116
	v_add_f32_e32 v120, v120, v116
	ds_read_b128 v[116:119], v182 offset:5120
	s_waitcnt lgkmcnt(1)
	v_mul_f32_e32 v113, v111, v113
	v_fmac_f32_e32 v113, v110, v112
	v_mul_f32_e32 v112, v109, v115
	v_fmac_f32_e32 v112, v108, v114
	s_waitcnt lgkmcnt(0)
	v_mul_f32_e32 v117, v107, v117
	v_add_f32_e32 v112, v113, v112
	v_fmac_f32_e32 v117, v106, v116
	v_mul_f32_e32 v116, v105, v119
	v_add_f32_e32 v121, 0, v112
	ds_read_b128 v[112:115], v182 offset:6144
	v_fmac_f32_e32 v116, v104, v118
	v_add_f32_e32 v116, v117, v116
	v_add_f32_e32 v121, v121, v116
	ds_read_b128 v[116:119], v182 offset:7168
	s_waitcnt lgkmcnt(1)
	v_mul_f32_e32 v113, v103, v113
	v_fmac_f32_e32 v113, v102, v112
	v_mul_f32_e32 v112, v101, v115
	v_fmac_f32_e32 v112, v100, v114
	s_waitcnt lgkmcnt(0)
	v_mul_f32_e32 v117, v99, v117
	v_add_f32_e32 v112, v113, v112
	v_fmac_f32_e32 v117, v98, v116
	v_mul_f32_e32 v116, v97, v119
	v_add_f32_e32 v121, v121, v112
	ds_read_b128 v[112:115], v182 offset:8192
	v_fmac_f32_e32 v116, v96, v118
	v_add_f32_e32 v116, v117, v116
	v_add_f32_e32 v121, v121, v116
	ds_read_b128 v[116:119], v182 offset:9216
	s_waitcnt lgkmcnt(1)
	v_mul_f32_e32 v113, v111, v113
	v_fmac_f32_e32 v113, v110, v112
	v_mul_f32_e32 v112, v109, v115
	v_fmac_f32_e32 v112, v108, v114
	s_waitcnt lgkmcnt(0)
	v_mul_f32_e32 v117, v107, v117
	v_add_f32_e32 v112, v113, v112
	v_fmac_f32_e32 v117, v106, v116
	v_mul_f32_e32 v116, v105, v119
	v_add_f32_e32 v122, 0, v112
	ds_read_b128 v[112:115], v182 offset:10240
	v_fmac_f32_e32 v116, v104, v118
	v_add_f32_e32 v116, v117, v116
	v_add_f32_e32 v122, v122, v116
	ds_read_b128 v[116:119], v182 offset:11264
	s_waitcnt lgkmcnt(1)
	v_mul_f32_e32 v113, v103, v113
	v_fmac_f32_e32 v113, v102, v112
	v_mul_f32_e32 v112, v101, v115
	v_fmac_f32_e32 v112, v100, v114
	s_waitcnt lgkmcnt(0)
	v_mul_f32_e32 v117, v99, v117
	v_add_f32_e32 v112, v113, v112
	v_fmac_f32_e32 v117, v98, v116
	v_mul_f32_e32 v116, v97, v119
	v_add_f32_e32 v122, v122, v112
	ds_read_b128 v[112:115], v182 offset:12288
	v_fmac_f32_e32 v116, v96, v118
	v_add_f32_e32 v116, v117, v116
	v_add_f32_e32 v122, v122, v116
	ds_read_b128 v[116:119], v182 offset:13312
	s_waitcnt lgkmcnt(1)
	v_mul_f32_e32 v113, v111, v113
	v_fmac_f32_e32 v113, v110, v112
	v_mul_f32_e32 v112, v109, v115
	v_fmac_f32_e32 v112, v108, v114
	s_waitcnt lgkmcnt(0)
	v_mul_f32_e32 v117, v107, v117
	v_add_f32_e32 v112, v113, v112
	v_fmac_f32_e32 v117, v106, v116
	v_mul_f32_e32 v116, v105, v119
	v_add_f32_e32 v123, 0, v112
	ds_read_b128 v[112:115], v182 offset:14336
	v_fmac_f32_e32 v116, v104, v118
	v_add_f32_e32 v116, v117, v116
	v_add_f32_e32 v123, v123, v116
	ds_read_b128 v[116:119], v182 offset:15360
	s_waitcnt lgkmcnt(1)
	v_mul_f32_e32 v113, v103, v113
	v_fmac_f32_e32 v113, v102, v112
	v_mul_f32_e32 v112, v101, v115
	v_fmac_f32_e32 v112, v100, v114
	s_waitcnt lgkmcnt(0)
	v_mul_f32_e32 v117, v99, v117
	v_add_f32_e32 v112, v113, v112
	v_fmac_f32_e32 v117, v98, v116
	v_mul_f32_e32 v116, v97, v119
	v_add_f32_e32 v123, v123, v112
	ds_read_b128 v[112:115], v182 offset:16384
	v_fmac_f32_e32 v116, v96, v118
	v_add_f32_e32 v116, v117, v116
	v_add_f32_e32 v123, v123, v116
	ds_read_b128 v[116:119], v182 offset:17408
	s_waitcnt lgkmcnt(1)
	v_mul_f32_e32 v113, v111, v113
	v_fmac_f32_e32 v113, v110, v112
	v_mul_f32_e32 v112, v109, v115
	v_fmac_f32_e32 v112, v108, v114
	s_waitcnt lgkmcnt(0)
	v_mul_f32_e32 v117, v107, v117
	v_add_f32_e32 v112, v113, v112
	v_fmac_f32_e32 v117, v106, v116
	v_mul_f32_e32 v116, v105, v119
	v_add_f32_e32 v124, 0, v112
	ds_read_b128 v[112:115], v182 offset:18432
	v_fmac_f32_e32 v116, v104, v118
	v_add_f32_e32 v116, v117, v116
	v_add_f32_e32 v124, v124, v116
	ds_read_b128 v[116:119], v182 offset:19456
	s_waitcnt lgkmcnt(1)
	v_mul_f32_e32 v113, v103, v113
	v_fmac_f32_e32 v113, v102, v112
	v_mul_f32_e32 v112, v101, v115
	v_fmac_f32_e32 v112, v100, v114
	s_waitcnt lgkmcnt(0)
	v_mul_f32_e32 v117, v99, v117
	v_add_f32_e32 v112, v113, v112
	v_fmac_f32_e32 v117, v98, v116
	v_mul_f32_e32 v116, v97, v119
	v_add_f32_e32 v124, v124, v112
	ds_read_b128 v[112:115], v182 offset:20480
	v_fmac_f32_e32 v116, v96, v118
	v_add_f32_e32 v116, v117, v116
	v_add_f32_e32 v124, v124, v116
	ds_read_b128 v[116:119], v182 offset:21504
	s_waitcnt lgkmcnt(1)
	v_mul_f32_e32 v113, v111, v113
	v_fmac_f32_e32 v113, v110, v112
	v_mul_f32_e32 v112, v109, v115
	v_fmac_f32_e32 v112, v108, v114
	s_waitcnt lgkmcnt(0)
	v_mul_f32_e32 v117, v107, v117
	v_add_f32_e32 v112, v113, v112
	v_fmac_f32_e32 v117, v106, v116
	v_mul_f32_e32 v116, v105, v119
	v_add_f32_e32 v125, 0, v112
	ds_read_b128 v[112:115], v182 offset:22528
	v_fmac_f32_e32 v116, v104, v118
	v_add_f32_e32 v116, v117, v116
	v_add_f32_e32 v125, v125, v116
	ds_read_b128 v[116:119], v182 offset:23552
	s_waitcnt lgkmcnt(1)
	v_mul_f32_e32 v113, v103, v113
	v_fmac_f32_e32 v113, v102, v112
	v_mul_f32_e32 v112, v101, v115
	v_fmac_f32_e32 v112, v100, v114
	s_waitcnt lgkmcnt(0)
	v_mul_f32_e32 v117, v99, v117
	v_add_f32_e32 v112, v113, v112
	v_fmac_f32_e32 v117, v98, v116
	v_mul_f32_e32 v116, v97, v119
	v_add_f32_e32 v125, v125, v112
	ds_read_b128 v[112:115], v182 offset:24576
	v_fmac_f32_e32 v116, v96, v118
	v_add_f32_e32 v116, v117, v116
	v_add_f32_e32 v125, v125, v116
	ds_read_b128 v[116:119], v182 offset:25600
	s_waitcnt lgkmcnt(1)
	v_mul_f32_e32 v113, v111, v113
	v_fmac_f32_e32 v113, v110, v112
	v_mul_f32_e32 v112, v109, v115
	v_fmac_f32_e32 v112, v108, v114
	s_waitcnt lgkmcnt(0)
	v_mul_f32_e32 v117, v107, v117
	v_add_f32_e32 v112, v113, v112
	v_fmac_f32_e32 v117, v106, v116
	v_mul_f32_e32 v116, v105, v119
	v_add_f32_e32 v126, 0, v112
	ds_read_b128 v[112:115], v182 offset:26624
	v_fmac_f32_e32 v116, v104, v118
	v_add_f32_e32 v116, v117, v116
	v_add_f32_e32 v126, v126, v116
	ds_read_b128 v[116:119], v182 offset:27648
	s_waitcnt lgkmcnt(1)
	v_mul_f32_e32 v113, v103, v113
	v_fmac_f32_e32 v113, v102, v112
	v_mul_f32_e32 v112, v101, v115
	v_fmac_f32_e32 v112, v100, v114
	s_waitcnt lgkmcnt(0)
	v_mul_f32_e32 v117, v99, v117
	v_add_f32_e32 v112, v113, v112
	v_fmac_f32_e32 v117, v98, v116
	v_mul_f32_e32 v116, v97, v119
	v_add_f32_e32 v126, v126, v112
	ds_read_b128 v[112:115], v182 offset:28672
	v_fmac_f32_e32 v116, v96, v118
	v_add_f32_e32 v116, v117, v116
	v_add_f32_e32 v126, v126, v116
	ds_read_b128 v[116:119], v182 offset:29696
	s_waitcnt lgkmcnt(1)
	v_mul_f32_e32 v111, v111, v113
	v_mul_f32_e32 v109, v109, v115
	v_fmac_f32_e32 v111, v110, v112
	v_fmac_f32_e32 v109, v108, v114
	v_add_f32_e32 v108, v111, v109
	s_waitcnt lgkmcnt(0)
	v_mul_f32_e32 v111, v107, v117
	v_mul_f32_e32 v105, v105, v119
	v_fmac_f32_e32 v111, v106, v116
	v_fmac_f32_e32 v105, v104, v118
	v_add_f32_e32 v110, 0, v108
	v_add_f32_e32 v104, v111, v105
	ds_read_b128 v[106:109], v182 offset:30720
	v_add_f32_e32 v104, v110, v104
	ds_read_b128 v[110:113], v182 offset:31744
	s_waitcnt lgkmcnt(1)
	v_mul_f32_e32 v103, v103, v107
	v_mul_f32_e32 v101, v101, v109
	s_waitcnt lgkmcnt(0)
	v_mul_f32_e32 v99, v99, v111
	v_fmac_f32_e32 v99, v98, v110
	v_cndmask_b32_e32 v98, v120, v124, vcc
	ds_bpermute_b32 v98, v184, v98
	v_fmac_f32_e32 v103, v102, v106
	v_fmac_f32_e32 v101, v100, v108
	v_mul_f32_e32 v97, v97, v113
	v_add_f32_e32 v100, v103, v101
	v_fmac_f32_e32 v97, v96, v112
	v_add_f32_e32 v100, v104, v100
	v_add_f32_e32 v96, v99, v97
	v_cndmask_b32_e32 v97, v124, v120, vcc
	v_add_f32_e32 v96, v100, v96
	s_waitcnt lgkmcnt(0)
	v_add_f32_e32 v97, v97, v98
	v_cndmask_b32_e32 v98, v121, v125, vcc
	ds_bpermute_b32 v98, v184, v98
	v_cndmask_b32_e32 v100, v122, v126, vcc
	v_cndmask_b32_e32 v101, v123, v96, vcc
	ds_bpermute_b32 v100, v184, v100
	ds_bpermute_b32 v101, v184, v101
	v_cndmask_b32_e32 v99, v125, v121, vcc
	s_waitcnt lgkmcnt(2)
	v_add_f32_e32 v98, v99, v98
	v_cndmask_b32_e32 v99, v126, v122, vcc
	v_cndmask_b32_e32 v96, v96, v123, vcc
	s_waitcnt lgkmcnt(1)
	v_add_f32_e32 v99, v99, v100
	s_waitcnt lgkmcnt(0)
	v_add_f32_e32 v96, v96, v101
	v_cndmask_b32_e64 v100, v97, v99, s[4:5]
	v_cndmask_b32_e64 v101, v98, v96, s[4:5]
	ds_bpermute_b32 v100, v185, v100
	ds_bpermute_b32 v101, v185, v101
	v_cndmask_b32_e64 v97, v99, v97, s[4:5]
	v_cndmask_b32_e64 v96, v96, v98, s[4:5]
	s_waitcnt lgkmcnt(1)
	v_add_f32_e32 v97, v97, v100
	s_waitcnt lgkmcnt(0)
	v_add_f32_e32 v96, v96, v101
	v_cndmask_b32_e64 v98, v97, v96, s[6:7]
	ds_bpermute_b32 v98, v186, v98
	v_cndmask_b32_e64 v96, v96, v97, s[6:7]
	s_waitcnt lgkmcnt(0)
	v_add_f32_e32 v96, v96, v98
	ds_bpermute_b32 v97, v187, v96
	s_waitcnt lgkmcnt(0)
	v_add_f32_e32 v96, v96, v97
	ds_bpermute_b32 v97, v188, v96
	s_waitcnt lgkmcnt(0)
	v_add_f32_e32 v96, v96, v97
	ds_bpermute_b32 v97, v189, v96
	s_and_saveexec_b64 s[36:37], s[8:9]
	s_cbranch_execz .LBB0_96
	v_mov_b32_e32 v98, v216
	s_waitcnt lgkmcnt(0)
	v_add_f32_e32 v99, v96, v97
	s_ashr_i32 s0, s34, 31
	s_lshr_b32 s0, s0, 19
	s_add_i32 s0, s34, s0
	s_ashr_i32 s1, s0, 13
	s_and_b32 s0, s0, 0xffffe000
	v_lshl_or_b32 v96, s1, 3, v183
	s_sub_i32 s34, s34, s0
	v_ashrrev_i32_e32 v97, 31, v96
	v_lshlrev_b64 v[96:97], 15, v[96:97]
	s_ashr_i32 s35, s34, 31
	v_lshl_add_u64 v[96:97], s[12:13], 0, v[96:97]
	v_lshl_add_u64 v[96:97], s[34:35], 2, v[96:97]
	v_add_f32_e32 v98, v99, v98
	v_mul_f32_e64 v99, |v98|, s41
	v_exp_f32_e32 v112, v99
	v_min_f32_e32 v113, 0, v98
	v_add_f32_e32 v100, 1.0, v112
	v_add_f32_e32 v101, -1.0, v100
	v_frexp_mant_f32_e32 v102, v100
	v_cvt_f64_f32_e32 v[98:99], v100
	v_sub_f32_e32 v103, v101, v100
	v_frexp_exp_i32_f64_e32 v98, v[98:99]
	v_cmp_gt_f32_e64 s[0:1], s42, v102
	v_sub_f32_e32 v101, v112, v101
	v_add_f32_e32 v99, 1.0, v103
	v_subbrev_co_u32_e64 v98, s[0:1], 0, v98, s[0:1]
	v_add_f32_e32 v99, v101, v99
	v_sub_u32_e32 v101, 0, v98
	v_ldexp_f32 v100, v100, v101
	v_add_f32_e32 v102, -1.0, v100
	v_add_f32_e32 v103, 1.0, v100
	v_ldexp_f32 v99, v99, v101
	v_add_f32_e32 v101, 1.0, v102
	v_add_f32_e32 v104, -1.0, v103
	v_sub_f32_e32 v101, v100, v101
	v_sub_f32_e32 v100, v100, v104
	v_add_f32_e32 v104, v99, v101
	v_add_f32_e32 v99, v99, v100
	v_add_f32_e32 v106, v103, v99
	v_rcp_f32_e32 v107, v106
	v_add_f32_e32 v101, v102, v104
	v_sub_f32_e32 v102, v101, v102
	v_sub_f32_e32 v100, v106, v103
	v_mul_f32_e32 v109, v101, v107
	v_sub_f32_e32 v108, v104, v102
	v_mul_f32_e32 v102, v106, v109
	v_sub_f32_e32 v99, v99, v100
	v_fma_f32 v104, v109, v106, -v102
	v_fmac_f32_e32 v104, v109, v99
	v_add_f32_e32 v100, v102, v104
	v_sub_f32_e32 v103, v101, v100
	v_mov_b32_e32 v105, v100
	v_pk_add_f32 v[100:101], v[100:101], v[102:103] neg_lo:[0,1] neg_hi:[0,1]
	v_cvt_f32_i32_e32 v98, v98
	v_pk_add_f32 v[100:101], v[100:101], v[104:105] neg_lo:[0,1] neg_hi:[0,1]
	v_cmp_neq_f32_e64 s[0:1], s44, v112
	v_add_f32_e32 v101, v108, v101
	v_add_f32_e32 v100, v100, v101
	v_add_f32_e32 v101, v103, v100
	v_mul_f32_e32 v105, v107, v101
	v_mul_f32_e32 v102, v106, v105
	v_sub_f32_e32 v103, v103, v101
	v_add_f32_e32 v110, v109, v105
	v_fma_f32 v104, v105, v106, -v102
	v_add_f32_e32 v108, v100, v103
	v_sub_f32_e32 v100, v110, v109
	v_fmac_f32_e32 v104, v105, v99
	v_sub_f32_e32 v99, v105, v100
	v_add_f32_e32 v100, v102, v104
	v_sub_f32_e32 v103, v101, v100
	v_mov_b32_e32 v105, v100
	v_pk_add_f32 v[100:101], v[100:101], v[102:103] neg_lo:[0,1] neg_hi:[0,1]
	s_nop 0
	v_pk_add_f32 v[100:101], v[100:101], v[104:105] neg_lo:[0,1] neg_hi:[0,1]
	s_nop 0
	v_add_f32_e32 v101, v108, v101
	v_add_f32_e32 v100, v100, v101
	v_add_f32_e32 v100, v103, v100
	v_mul_f32_e32 v100, v107, v100
	v_add_f32_e32 v99, v99, v100
	v_add_f32_e32 v100, v110, v99
	v_mul_f32_e32 v102, v100, v100
	v_sub_f32_e32 v103, v100, v110
	v_fmamk_f32 v104, v102, 0x3e9b6dac, v195
	v_sub_f32_e32 v103, v99, v103
	v_mul_f32_e32 v99, v100, v102
	v_fmaak_f32 v147, v102, v104, 0x3f2aaada
	v_ldexp_f32 v105, v103, 1
	v_pk_mul_f32 v[102:103], v[98:99], v[146:147]
	v_ldexp_f32 v101, v100, 1
	v_fma_f32 v100, v98, s43, -v102
	v_fmac_f32_e32 v100, 0xb102e308, v98
	v_pk_add_f32 v[98:99], v[102:103], v[100:101]
	v_mov_b32_e32 v104, v102
	v_sub_f32_e32 v108, v99, v101
	v_pk_add_f32 v[106:107], v[98:99], v[102:103] neg_lo:[0,1] neg_hi:[0,1]
	v_sub_f32_e32 v102, v103, v108
	v_add_f32_e32 v105, v105, v102
	v_pk_add_f32 v[102:103], v[98:99], v[104:105]
	v_mov_b32_e32 v101, v98
	v_mov_b32_e32 v107, v103
	v_pk_add_f32 v[110:111], v[100:101], v[106:107] neg_lo:[0,1] neg_hi:[0,1]
	v_pk_add_f32 v[100:101], v[100:101], v[106:107]
	v_mov_b32_e32 v109, v98
	v_pk_add_f32 v[106:107], v[100:101], v[98:99] op_sel:[1,0] op_sel_hi:[0,1] neg_lo:[0,1] neg_hi:[0,1]
	v_mov_b32_e32 v108, v105
	v_mov_b32_e32 v104, v103
	v_mov_b32_e32 v105, v101
	v_pk_mov_b32 v[98:99], v[98:99], v[106:107] op_sel:[1,0]
	v_pk_add_f32 v[102:103], v[102:103], v[106:107] op_sel_hi:[1,0] neg_lo:[0,1] neg_hi:[0,1]
	v_pk_add_f32 v[98:99], v[104:105], v[98:99] neg_lo:[0,1] neg_hi:[0,1]
	v_mov_b32_e32 v102, v110
	v_pk_add_f32 v[98:99], v[108:109], v[98:99] neg_lo:[0,1] neg_hi:[0,1]
	v_mov_b32_e32 v111, v101
	v_pk_add_f32 v[102:103], v[102:103], v[98:99]
	s_nop 0
	v_pk_add_f32 v[104:105], v[102:103], v[102:103] op_sel:[0,1] op_sel_hi:[1,0]
	s_nop 0
	v_pk_add_f32 v[100:101], v[100:101], v[104:105] op_sel:[1,0] op_sel_hi:[0,1]
	v_mov_b32_e32 v103, v100
	v_mov_b32_e32 v99, v104
	v_pk_add_f32 v[104:105], v[102:103], v[110:111] neg_lo:[0,1] neg_hi:[0,1]
	s_nop 0
	v_sub_f32_e32 v101, v102, v104
	v_pk_add_f32 v[98:99], v[98:99], v[104:105] neg_lo:[0,1] neg_hi:[0,1]
	v_sub_f32_e32 v101, v110, v101
	v_add_f32_e32 v98, v98, v101
	v_add_f32_e32 v98, v98, v99
	v_add_f32_e32 v98, v100, v98
	v_cndmask_b32_e64 v98, v196, v98, s[0:1]
	v_cmp_ngt_f32_e64 s[0:1], -1.0, v112
	s_nop 1
	v_cndmask_b32_e64 v98, v197, v98, s[0:1]
	v_cmp_neq_f32_e64 s[0:1], -1.0, v112
	s_nop 1
	v_cndmask_b32_e64 v98, v198, v98, s[0:1]
	v_cmp_lt_f32_e64 s[0:1], |v112|, s45
	s_nop 1
	v_cndmask_b32_e64 v98, v98, v112, s[0:1]
	v_sub_f32_e32 v98, v113, v98
	global_store_dword v[96:97], v98, off
.LBB0_96:
	s_or_b64 exec, exec, s[36:37]
	v_add_f32_e32 v96, v201, v202
	v_fmamk_f32 v96, v96, 0x3a800000, v194
	v_rsq_f32_e32 v96, v96
	s_lshl_b64 s[0:1], s[30:31], 11
	v_lshl_add_u64 v[98:99], v[130:131], 0, s[0:1]
	s_waitcnt lgkmcnt(0)
	v_pk_mul_f32 v[94:95], v[94:95], v[96:97] op_sel_hi:[1,0]
	v_pk_mul_f32 v[100:101], v[92:93], v[96:97] op_sel_hi:[1,0]
	v_pk_fma_f32 v[92:93], v[152:153], v[94:95], v[148:149]
	v_pk_fma_f32 v[94:95], v[154:155], v[100:101], v[150:151]
	v_cvt_pk_bf16_f32 v101, v92, v93
	v_pk_mul_f32 v[90:91], v[90:91], v[96:97] op_sel_hi:[1,0]
	v_cvt_pk_bf16_f32 v100, v94, v95
	global_store_dwordx2 v[98:99], v[100:101], off
	v_pk_mul_f32 v[100:101], v[88:89], v[96:97] op_sel_hi:[1,0]
	v_pk_fma_f32 v[88:89], v[160:161], v[90:91], v[156:157]
	v_pk_fma_f32 v[90:91], v[162:163], v[100:101], v[158:159]
	v_cvt_pk_bf16_f32 v101, v88, v89
	v_pk_mul_f32 v[86:87], v[86:87], v[96:97] op_sel_hi:[1,0]
	v_cvt_pk_bf16_f32 v100, v90, v91
	global_store_dwordx2 v[98:99], v[100:101], off offset:512
	v_pk_mul_f32 v[100:101], v[84:85], v[96:97] op_sel_hi:[1,0]
	v_pk_mul_f32 v[82:83], v[82:83], v[96:97] op_sel_hi:[1,0]
	v_pk_mul_f32 v[96:97], v[80:81], v[96:97] op_sel_hi:[1,0]
	v_pk_fma_f32 v[84:85], v[168:169], v[86:87], v[164:165]
	v_pk_fma_f32 v[86:87], v[170:171], v[100:101], v[166:167]
	v_cvt_pk_bf16_f32 v101, v84, v85
	v_pk_fma_f32 v[80:81], v[176:177], v[82:83], v[172:173]
	v_cvt_pk_bf16_f32 v100, v86, v87
	global_store_dwordx2 v[98:99], v[100:101], off offset:1024
	v_pk_fma_f32 v[82:83], v[178:179], v[96:97], v[174:175]
	v_cvt_pk_bf16_f32 v97, v80, v81
	s_nop 0
	v_cvt_pk_bf16_f32 v96, v82, v83
	global_store_dwordx2 v[98:99], v[96:97], off offset:1536
	ds_read_b128 v[96:99], v182
	ds_read_b128 v[100:103], v182 offset:1024
	s_waitcnt lgkmcnt(1)
	v_mul_f32_e32 v97, v95, v97
	v_fmac_f32_e32 v97, v94, v96
	v_mul_f32_e32 v96, v93, v99
	v_fmac_f32_e32 v96, v92, v98
	s_waitcnt lgkmcnt(0)
	v_mul_f32_e32 v101, v91, v101
	v_add_f32_e32 v96, v97, v96
	v_fmac_f32_e32 v101, v90, v100
	v_mul_f32_e32 v100, v89, v103
	v_add_f32_e32 v104, 0, v96
	ds_read_b128 v[96:99], v182 offset:2048
	v_fmac_f32_e32 v100, v88, v102
	v_add_f32_e32 v100, v101, v100
	v_add_f32_e32 v104, v104, v100
	ds_read_b128 v[100:103], v182 offset:3072
	s_waitcnt lgkmcnt(1)
	v_mul_f32_e32 v97, v87, v97
	v_fmac_f32_e32 v97, v86, v96
	v_mul_f32_e32 v96, v85, v99
	v_fmac_f32_e32 v96, v84, v98
	s_waitcnt lgkmcnt(0)
	v_mul_f32_e32 v101, v83, v101
	v_add_f32_e32 v96, v97, v96
	v_fmac_f32_e32 v101, v82, v100
	v_mul_f32_e32 v100, v81, v103
	v_add_f32_e32 v104, v104, v96
	ds_read_b128 v[96:99], v182 offset:4096
	v_fmac_f32_e32 v100, v80, v102
	v_add_f32_e32 v100, v101, v100
	v_add_f32_e32 v104, v104, v100
	ds_read_b128 v[100:103], v182 offset:5120
	s_waitcnt lgkmcnt(1)
	v_mul_f32_e32 v97, v95, v97
	v_fmac_f32_e32 v97, v94, v96
	v_mul_f32_e32 v96, v93, v99
	v_fmac_f32_e32 v96, v92, v98
	s_waitcnt lgkmcnt(0)
	v_mul_f32_e32 v101, v91, v101
	v_add_f32_e32 v96, v97, v96
	v_fmac_f32_e32 v101, v90, v100
	v_mul_f32_e32 v100, v89, v103
	v_add_f32_e32 v105, 0, v96
	ds_read_b128 v[96:99], v182 offset:6144
	v_fmac_f32_e32 v100, v88, v102
	v_add_f32_e32 v100, v101, v100
	v_add_f32_e32 v105, v105, v100
	ds_read_b128 v[100:103], v182 offset:7168
	s_waitcnt lgkmcnt(1)
	v_mul_f32_e32 v97, v87, v97
	v_fmac_f32_e32 v97, v86, v96
	v_mul_f32_e32 v96, v85, v99
	v_fmac_f32_e32 v96, v84, v98
	s_waitcnt lgkmcnt(0)
	v_mul_f32_e32 v101, v83, v101
	v_add_f32_e32 v96, v97, v96
	v_fmac_f32_e32 v101, v82, v100
	v_mul_f32_e32 v100, v81, v103
	v_add_f32_e32 v105, v105, v96
	ds_read_b128 v[96:99], v182 offset:8192
	v_fmac_f32_e32 v100, v80, v102
	v_add_f32_e32 v100, v101, v100
	v_add_f32_e32 v105, v105, v100
	ds_read_b128 v[100:103], v182 offset:9216
	s_waitcnt lgkmcnt(1)
	v_mul_f32_e32 v97, v95, v97
	v_fmac_f32_e32 v97, v94, v96
	v_mul_f32_e32 v96, v93, v99
	v_fmac_f32_e32 v96, v92, v98
	s_waitcnt lgkmcnt(0)
	v_mul_f32_e32 v101, v91, v101
	v_add_f32_e32 v96, v97, v96
	v_fmac_f32_e32 v101, v90, v100
	v_mul_f32_e32 v100, v89, v103
	v_add_f32_e32 v106, 0, v96
	ds_read_b128 v[96:99], v182 offset:10240
	v_fmac_f32_e32 v100, v88, v102
	v_add_f32_e32 v100, v101, v100
	v_add_f32_e32 v106, v106, v100
	ds_read_b128 v[100:103], v182 offset:11264
	s_waitcnt lgkmcnt(1)
	v_mul_f32_e32 v97, v87, v97
	v_fmac_f32_e32 v97, v86, v96
	v_mul_f32_e32 v96, v85, v99
	v_fmac_f32_e32 v96, v84, v98
	s_waitcnt lgkmcnt(0)
	v_mul_f32_e32 v101, v83, v101
	v_add_f32_e32 v96, v97, v96
	v_fmac_f32_e32 v101, v82, v100
	v_mul_f32_e32 v100, v81, v103
	v_add_f32_e32 v106, v106, v96
	ds_read_b128 v[96:99], v182 offset:12288
	v_fmac_f32_e32 v100, v80, v102
	v_add_f32_e32 v100, v101, v100
	v_add_f32_e32 v106, v106, v100
	ds_read_b128 v[100:103], v182 offset:13312
	s_waitcnt lgkmcnt(1)
	v_mul_f32_e32 v97, v95, v97
	v_fmac_f32_e32 v97, v94, v96
	v_mul_f32_e32 v96, v93, v99
	v_fmac_f32_e32 v96, v92, v98
	s_waitcnt lgkmcnt(0)
	v_mul_f32_e32 v101, v91, v101
	v_add_f32_e32 v96, v97, v96
	v_fmac_f32_e32 v101, v90, v100
	v_mul_f32_e32 v100, v89, v103
	v_add_f32_e32 v107, 0, v96
	ds_read_b128 v[96:99], v182 offset:14336
	v_fmac_f32_e32 v100, v88, v102
	v_add_f32_e32 v100, v101, v100
	v_add_f32_e32 v107, v107, v100
	ds_read_b128 v[100:103], v182 offset:15360
	s_waitcnt lgkmcnt(1)
	v_mul_f32_e32 v97, v87, v97
	v_fmac_f32_e32 v97, v86, v96
	v_mul_f32_e32 v96, v85, v99
	v_fmac_f32_e32 v96, v84, v98
	s_waitcnt lgkmcnt(0)
	v_mul_f32_e32 v101, v83, v101
	v_add_f32_e32 v96, v97, v96
	v_fmac_f32_e32 v101, v82, v100
	v_mul_f32_e32 v100, v81, v103
	v_add_f32_e32 v107, v107, v96
	ds_read_b128 v[96:99], v182 offset:16384
	v_fmac_f32_e32 v100, v80, v102
	v_add_f32_e32 v100, v101, v100
	v_add_f32_e32 v107, v107, v100
	ds_read_b128 v[100:103], v182 offset:17408
	s_waitcnt lgkmcnt(1)
	v_mul_f32_e32 v97, v95, v97
	v_fmac_f32_e32 v97, v94, v96
	v_mul_f32_e32 v96, v93, v99
	v_fmac_f32_e32 v96, v92, v98
	s_waitcnt lgkmcnt(0)
	v_mul_f32_e32 v101, v91, v101
	v_add_f32_e32 v96, v97, v96
	v_fmac_f32_e32 v101, v90, v100
	v_mul_f32_e32 v100, v89, v103
	v_add_f32_e32 v108, 0, v96
	ds_read_b128 v[96:99], v182 offset:18432
	v_fmac_f32_e32 v100, v88, v102
	v_add_f32_e32 v100, v101, v100
	v_add_f32_e32 v108, v108, v100
	ds_read_b128 v[100:103], v182 offset:19456
	s_waitcnt lgkmcnt(1)
	v_mul_f32_e32 v97, v87, v97
	v_fmac_f32_e32 v97, v86, v96
	v_mul_f32_e32 v96, v85, v99
	v_fmac_f32_e32 v96, v84, v98
	s_waitcnt lgkmcnt(0)
	v_mul_f32_e32 v101, v83, v101
	v_add_f32_e32 v96, v97, v96
	v_fmac_f32_e32 v101, v82, v100
	v_mul_f32_e32 v100, v81, v103
	v_add_f32_e32 v108, v108, v96
	ds_read_b128 v[96:99], v182 offset:20480
	v_fmac_f32_e32 v100, v80, v102
	v_add_f32_e32 v100, v101, v100
	v_add_f32_e32 v108, v108, v100
	ds_read_b128 v[100:103], v182 offset:21504
	s_waitcnt lgkmcnt(1)
	v_mul_f32_e32 v97, v95, v97
	v_fmac_f32_e32 v97, v94, v96
	v_mul_f32_e32 v96, v93, v99
	v_fmac_f32_e32 v96, v92, v98
	s_waitcnt lgkmcnt(0)
	v_mul_f32_e32 v101, v91, v101
	v_add_f32_e32 v96, v97, v96
	v_fmac_f32_e32 v101, v90, v100
	v_mul_f32_e32 v100, v89, v103
	v_add_f32_e32 v109, 0, v96
	ds_read_b128 v[96:99], v182 offset:22528
	v_fmac_f32_e32 v100, v88, v102
	v_add_f32_e32 v100, v101, v100
	v_add_f32_e32 v109, v109, v100
	ds_read_b128 v[100:103], v182 offset:23552
	s_waitcnt lgkmcnt(1)
	v_mul_f32_e32 v97, v87, v97
	v_fmac_f32_e32 v97, v86, v96
	v_mul_f32_e32 v96, v85, v99
	v_fmac_f32_e32 v96, v84, v98
	s_waitcnt lgkmcnt(0)
	v_mul_f32_e32 v101, v83, v101
	v_add_f32_e32 v96, v97, v96
	v_fmac_f32_e32 v101, v82, v100
	v_mul_f32_e32 v100, v81, v103
	v_add_f32_e32 v109, v109, v96
	ds_read_b128 v[96:99], v182 offset:24576
	v_fmac_f32_e32 v100, v80, v102
	v_add_f32_e32 v100, v101, v100
	v_add_f32_e32 v109, v109, v100
	ds_read_b128 v[100:103], v182 offset:25600
	s_waitcnt lgkmcnt(1)
	v_mul_f32_e32 v97, v95, v97
	v_fmac_f32_e32 v97, v94, v96
	v_mul_f32_e32 v96, v93, v99
	v_fmac_f32_e32 v96, v92, v98
	s_waitcnt lgkmcnt(0)
	v_mul_f32_e32 v101, v91, v101
	v_add_f32_e32 v96, v97, v96
	v_fmac_f32_e32 v101, v90, v100
	v_mul_f32_e32 v100, v89, v103
	v_add_f32_e32 v110, 0, v96
	ds_read_b128 v[96:99], v182 offset:26624
	v_fmac_f32_e32 v100, v88, v102
	v_add_f32_e32 v100, v101, v100
	v_add_f32_e32 v110, v110, v100
	ds_read_b128 v[100:103], v182 offset:27648
	s_waitcnt lgkmcnt(1)
	v_mul_f32_e32 v97, v87, v97
	v_fmac_f32_e32 v97, v86, v96
	v_mul_f32_e32 v96, v85, v99
	v_fmac_f32_e32 v96, v84, v98
	s_waitcnt lgkmcnt(0)
	v_mul_f32_e32 v101, v83, v101
	v_add_f32_e32 v96, v97, v96
	v_fmac_f32_e32 v101, v82, v100
	v_mul_f32_e32 v100, v81, v103
	v_add_f32_e32 v110, v110, v96
	ds_read_b128 v[96:99], v182 offset:28672
	v_fmac_f32_e32 v100, v80, v102
	v_add_f32_e32 v100, v101, v100
	v_add_f32_e32 v110, v110, v100
	ds_read_b128 v[100:103], v182 offset:29696
	s_waitcnt lgkmcnt(1)
	v_mul_f32_e32 v95, v95, v97
	v_mul_f32_e32 v93, v93, v99
	v_fmac_f32_e32 v95, v94, v96
	v_fmac_f32_e32 v93, v92, v98
	v_add_f32_e32 v92, v95, v93
	s_waitcnt lgkmcnt(0)
	v_mul_f32_e32 v95, v91, v101
	v_mul_f32_e32 v89, v89, v103
	v_fmac_f32_e32 v95, v90, v100
	v_fmac_f32_e32 v89, v88, v102
	v_add_f32_e32 v94, 0, v92
	v_add_f32_e32 v88, v95, v89
	ds_read_b128 v[90:93], v182 offset:30720
	v_add_f32_e32 v88, v94, v88
	ds_read_b128 v[94:97], v182 offset:31744
	s_waitcnt lgkmcnt(1)
	v_mul_f32_e32 v87, v87, v91
	v_mul_f32_e32 v85, v85, v93
	s_waitcnt lgkmcnt(0)
	v_mul_f32_e32 v83, v83, v95
	v_fmac_f32_e32 v83, v82, v94
	v_cndmask_b32_e32 v82, v104, v108, vcc
	ds_bpermute_b32 v82, v184, v82
	v_fmac_f32_e32 v87, v86, v90
	v_fmac_f32_e32 v85, v84, v92
	v_mul_f32_e32 v81, v81, v97
	v_add_f32_e32 v84, v87, v85
	v_fmac_f32_e32 v81, v80, v96
	v_add_f32_e32 v84, v88, v84
	v_add_f32_e32 v80, v83, v81
	v_cndmask_b32_e32 v81, v108, v104, vcc
	v_add_f32_e32 v80, v84, v80
	s_waitcnt lgkmcnt(0)
	v_add_f32_e32 v81, v81, v82
	v_cndmask_b32_e32 v82, v105, v109, vcc
	ds_bpermute_b32 v82, v184, v82
	v_cndmask_b32_e32 v84, v106, v110, vcc
	v_cndmask_b32_e32 v85, v107, v80, vcc
	ds_bpermute_b32 v84, v184, v84
	ds_bpermute_b32 v85, v184, v85
	v_cndmask_b32_e32 v83, v109, v105, vcc
	s_waitcnt lgkmcnt(2)
	v_add_f32_e32 v82, v83, v82
	v_cndmask_b32_e32 v83, v110, v106, vcc
	v_cndmask_b32_e32 v80, v80, v107, vcc
	s_waitcnt lgkmcnt(1)
	v_add_f32_e32 v83, v83, v84
	s_waitcnt lgkmcnt(0)
	v_add_f32_e32 v80, v80, v85
	v_cndmask_b32_e64 v84, v81, v83, s[4:5]
	v_cndmask_b32_e64 v85, v82, v80, s[4:5]
	ds_bpermute_b32 v84, v185, v84
	ds_bpermute_b32 v85, v185, v85
	v_cndmask_b32_e64 v81, v83, v81, s[4:5]
	v_cndmask_b32_e64 v80, v80, v82, s[4:5]
	s_waitcnt lgkmcnt(1)
	v_add_f32_e32 v81, v81, v84
	s_waitcnt lgkmcnt(0)
	v_add_f32_e32 v80, v80, v85
	v_cndmask_b32_e64 v82, v81, v80, s[6:7]
	ds_bpermute_b32 v82, v186, v82
	v_cndmask_b32_e64 v80, v80, v81, s[6:7]
	s_waitcnt lgkmcnt(0)
	v_add_f32_e32 v80, v80, v82
	ds_bpermute_b32 v81, v187, v80
	s_waitcnt lgkmcnt(0)
	v_add_f32_e32 v80, v80, v81
	ds_bpermute_b32 v81, v188, v80
	s_waitcnt lgkmcnt(0)
	v_add_f32_e32 v80, v80, v81
	ds_bpermute_b32 v81, v189, v80
	s_and_saveexec_b64 s[34:35], s[8:9]
	s_cbranch_execz .LBB0_98
	v_mov_b32_e32 v82, v216
	s_waitcnt lgkmcnt(0)
	v_add_f32_e32 v83, v80, v81
	s_ashr_i32 s0, s30, 31
	s_lshr_b32 s0, s0, 19
	s_add_i32 s0, s30, s0
	s_ashr_i32 s1, s0, 13
	s_and_b32 s0, s0, 0xffffe000
	v_lshl_or_b32 v80, s1, 3, v183
	s_sub_i32 s30, s30, s0
	v_ashrrev_i32_e32 v81, 31, v80
	v_lshlrev_b64 v[80:81], 15, v[80:81]
	s_ashr_i32 s31, s30, 31
	v_lshl_add_u64 v[80:81], s[12:13], 0, v[80:81]
	v_lshl_add_u64 v[80:81], s[30:31], 2, v[80:81]
	v_add_f32_e32 v82, v83, v82
	v_mul_f32_e64 v83, |v82|, s41
	v_exp_f32_e32 v96, v83
	v_min_f32_e32 v97, 0, v82
	v_add_f32_e32 v84, 1.0, v96
	v_add_f32_e32 v85, -1.0, v84
	v_frexp_mant_f32_e32 v86, v84
	v_cvt_f64_f32_e32 v[82:83], v84
	v_sub_f32_e32 v87, v85, v84
	v_frexp_exp_i32_f64_e32 v82, v[82:83]
	v_cmp_gt_f32_e64 s[0:1], s42, v86
	v_sub_f32_e32 v85, v96, v85
	v_add_f32_e32 v83, 1.0, v87
	v_subbrev_co_u32_e64 v82, s[0:1], 0, v82, s[0:1]
	v_add_f32_e32 v83, v85, v83
	v_sub_u32_e32 v85, 0, v82
	v_ldexp_f32 v84, v84, v85
	v_add_f32_e32 v86, -1.0, v84
	v_add_f32_e32 v87, 1.0, v84
	v_ldexp_f32 v83, v83, v85
	v_add_f32_e32 v85, 1.0, v86
	v_add_f32_e32 v88, -1.0, v87
	v_sub_f32_e32 v85, v84, v85
	v_sub_f32_e32 v84, v84, v88
	v_add_f32_e32 v88, v83, v85
	v_add_f32_e32 v83, v83, v84
	v_add_f32_e32 v90, v87, v83
	v_rcp_f32_e32 v91, v90
	v_add_f32_e32 v85, v86, v88
	v_sub_f32_e32 v86, v85, v86
	v_sub_f32_e32 v84, v90, v87
	v_mul_f32_e32 v93, v85, v91
	v_sub_f32_e32 v92, v88, v86
	v_mul_f32_e32 v86, v90, v93
	v_sub_f32_e32 v83, v83, v84
	v_fma_f32 v88, v93, v90, -v86
	v_fmac_f32_e32 v88, v93, v83
	v_add_f32_e32 v84, v86, v88
	v_sub_f32_e32 v87, v85, v84
	v_mov_b32_e32 v89, v84
	v_pk_add_f32 v[84:85], v[84:85], v[86:87] neg_lo:[0,1] neg_hi:[0,1]
	v_cvt_f32_i32_e32 v82, v82
	v_pk_add_f32 v[84:85], v[84:85], v[88:89] neg_lo:[0,1] neg_hi:[0,1]
	v_cmp_neq_f32_e64 s[0:1], s44, v96
	v_add_f32_e32 v85, v92, v85
	v_add_f32_e32 v84, v84, v85
	v_add_f32_e32 v85, v87, v84
	v_mul_f32_e32 v89, v91, v85
	v_mul_f32_e32 v86, v90, v89
	v_sub_f32_e32 v87, v87, v85
	v_add_f32_e32 v94, v93, v89
	v_fma_f32 v88, v89, v90, -v86
	v_add_f32_e32 v92, v84, v87
	v_sub_f32_e32 v84, v94, v93
	v_fmac_f32_e32 v88, v89, v83
	v_sub_f32_e32 v83, v89, v84
	v_add_f32_e32 v84, v86, v88
	v_sub_f32_e32 v87, v85, v84
	v_mov_b32_e32 v89, v84
	v_pk_add_f32 v[84:85], v[84:85], v[86:87] neg_lo:[0,1] neg_hi:[0,1]
	s_nop 0
	v_pk_add_f32 v[84:85], v[84:85], v[88:89] neg_lo:[0,1] neg_hi:[0,1]
	s_nop 0
	v_add_f32_e32 v85, v92, v85
	v_add_f32_e32 v84, v84, v85
	v_add_f32_e32 v84, v87, v84
	v_mul_f32_e32 v84, v91, v84
	v_add_f32_e32 v83, v83, v84
	v_add_f32_e32 v84, v94, v83
	v_mul_f32_e32 v86, v84, v84
	v_sub_f32_e32 v87, v84, v94
	v_fmamk_f32 v88, v86, 0x3e9b6dac, v195
	v_sub_f32_e32 v87, v83, v87
	v_mul_f32_e32 v83, v84, v86
	v_fmaak_f32 v147, v86, v88, 0x3f2aaada
	v_ldexp_f32 v89, v87, 1
	v_pk_mul_f32 v[86:87], v[82:83], v[146:147]
	v_ldexp_f32 v85, v84, 1
	v_fma_f32 v84, v82, s43, -v86
	v_fmac_f32_e32 v84, 0xb102e308, v82
	v_pk_add_f32 v[82:83], v[86:87], v[84:85]
	v_mov_b32_e32 v88, v86
	v_sub_f32_e32 v92, v83, v85
	v_pk_add_f32 v[90:91], v[82:83], v[86:87] neg_lo:[0,1] neg_hi:[0,1]
	v_sub_f32_e32 v86, v87, v92
	v_add_f32_e32 v89, v89, v86
	v_pk_add_f32 v[86:87], v[82:83], v[88:89]
	v_mov_b32_e32 v85, v82
	v_mov_b32_e32 v91, v87
	v_pk_add_f32 v[94:95], v[84:85], v[90:91] neg_lo:[0,1] neg_hi:[0,1]
	v_pk_add_f32 v[84:85], v[84:85], v[90:91]
	v_mov_b32_e32 v93, v82
	v_pk_add_f32 v[90:91], v[84:85], v[82:83] op_sel:[1,0] op_sel_hi:[0,1] neg_lo:[0,1] neg_hi:[0,1]
	v_mov_b32_e32 v92, v89
	v_mov_b32_e32 v88, v87
	v_mov_b32_e32 v89, v85
	v_pk_mov_b32 v[82:83], v[82:83], v[90:91] op_sel:[1,0]
	v_pk_add_f32 v[86:87], v[86:87], v[90:91] op_sel_hi:[1,0] neg_lo:[0,1] neg_hi:[0,1]
	v_pk_add_f32 v[82:83], v[88:89], v[82:83] neg_lo:[0,1] neg_hi:[0,1]
	v_mov_b32_e32 v86, v94
	v_pk_add_f32 v[82:83], v[92:93], v[82:83] neg_lo:[0,1] neg_hi:[0,1]
	v_mov_b32_e32 v95, v85
	v_pk_add_f32 v[86:87], v[86:87], v[82:83]
	s_nop 0
	v_pk_add_f32 v[88:89], v[86:87], v[86:87] op_sel:[0,1] op_sel_hi:[1,0]
	s_nop 0
	v_pk_add_f32 v[84:85], v[84:85], v[88:89] op_sel:[1,0] op_sel_hi:[0,1]
	v_mov_b32_e32 v87, v84
	v_mov_b32_e32 v83, v88
	v_pk_add_f32 v[88:89], v[86:87], v[94:95] neg_lo:[0,1] neg_hi:[0,1]
	s_nop 0
	v_sub_f32_e32 v85, v86, v88
	v_pk_add_f32 v[82:83], v[82:83], v[88:89] neg_lo:[0,1] neg_hi:[0,1]
	v_sub_f32_e32 v85, v94, v85
	v_add_f32_e32 v82, v82, v85
	v_add_f32_e32 v82, v82, v83
	v_add_f32_e32 v82, v84, v82
	v_cndmask_b32_e64 v82, v196, v82, s[0:1]
	v_cmp_ngt_f32_e64 s[0:1], -1.0, v96
	s_nop 1
	v_cndmask_b32_e64 v82, v197, v82, s[0:1]
	v_cmp_neq_f32_e64 s[0:1], -1.0, v96
	s_nop 1
	v_cndmask_b32_e64 v82, v198, v82, s[0:1]
	v_cmp_lt_f32_e64 s[0:1], |v96|, s45
	s_nop 1
	v_cndmask_b32_e64 v82, v82, v96, s[0:1]
	v_sub_f32_e32 v82, v97, v82
	global_store_dword v[80:81], v82, off
.LBB0_98:
	s_or_b64 exec, exec, s[34:35]
	v_add_f32_e32 v80, v199, v200
	v_fmamk_f32 v80, v80, 0x3a800000, v194
	v_rsq_f32_e32 v80, v80
	s_lshl_b64 s[0:1], s[28:29], 11
	v_lshl_add_u64 v[82:83], v[130:131], 0, s[0:1]
	s_waitcnt lgkmcnt(0)
	v_pk_mul_f32 v[78:79], v[78:79], v[80:81] op_sel_hi:[1,0]
	v_pk_mul_f32 v[84:85], v[76:77], v[80:81] op_sel_hi:[1,0]
	v_pk_fma_f32 v[76:77], v[152:153], v[78:79], v[148:149]
	v_pk_fma_f32 v[78:79], v[154:155], v[84:85], v[150:151]
	v_cvt_pk_bf16_f32 v85, v76, v77
	v_pk_mul_f32 v[74:75], v[74:75], v[80:81] op_sel_hi:[1,0]
	v_cvt_pk_bf16_f32 v84, v78, v79
	global_store_dwordx2 v[82:83], v[84:85], off
	v_pk_mul_f32 v[84:85], v[72:73], v[80:81] op_sel_hi:[1,0]
	v_pk_fma_f32 v[72:73], v[160:161], v[74:75], v[156:157]
	v_pk_fma_f32 v[74:75], v[162:163], v[84:85], v[158:159]
	v_cvt_pk_bf16_f32 v85, v72, v73
	v_pk_mul_f32 v[70:71], v[70:71], v[80:81] op_sel_hi:[1,0]
	v_cvt_pk_bf16_f32 v84, v74, v75
	global_store_dwordx2 v[82:83], v[84:85], off offset:512
	v_pk_mul_f32 v[84:85], v[68:69], v[80:81] op_sel_hi:[1,0]
	v_pk_mul_f32 v[66:67], v[66:67], v[80:81] op_sel_hi:[1,0]
	v_pk_mul_f32 v[80:81], v[64:65], v[80:81] op_sel_hi:[1,0]
	v_pk_fma_f32 v[68:69], v[168:169], v[70:71], v[164:165]
	v_pk_fma_f32 v[70:71], v[170:171], v[84:85], v[166:167]
	v_cvt_pk_bf16_f32 v85, v68, v69
	v_pk_fma_f32 v[64:65], v[176:177], v[66:67], v[172:173]
	v_cvt_pk_bf16_f32 v84, v70, v71
	global_store_dwordx2 v[82:83], v[84:85], off offset:1024
	v_pk_fma_f32 v[66:67], v[178:179], v[80:81], v[174:175]
	v_cvt_pk_bf16_f32 v81, v64, v65
	s_nop 0
	v_cvt_pk_bf16_f32 v80, v66, v67
	global_store_dwordx2 v[82:83], v[80:81], off offset:1536
	ds_read_b128 v[80:83], v182
	ds_read_b128 v[84:87], v182 offset:1024
	s_waitcnt lgkmcnt(1)
	v_mul_f32_e32 v81, v79, v81
	v_fmac_f32_e32 v81, v78, v80
	v_mul_f32_e32 v80, v77, v83
	v_fmac_f32_e32 v80, v76, v82
	s_waitcnt lgkmcnt(0)
	v_mul_f32_e32 v85, v75, v85
	v_add_f32_e32 v80, v81, v80
	v_fmac_f32_e32 v85, v74, v84
	v_mul_f32_e32 v84, v73, v87
	v_add_f32_e32 v88, 0, v80
	ds_read_b128 v[80:83], v182 offset:2048
	v_fmac_f32_e32 v84, v72, v86
	v_add_f32_e32 v84, v85, v84
	v_add_f32_e32 v88, v88, v84
	ds_read_b128 v[84:87], v182 offset:3072
	s_waitcnt lgkmcnt(1)
	v_mul_f32_e32 v81, v71, v81
	v_fmac_f32_e32 v81, v70, v80
	v_mul_f32_e32 v80, v69, v83
	v_fmac_f32_e32 v80, v68, v82
	s_waitcnt lgkmcnt(0)
	v_mul_f32_e32 v85, v67, v85
	v_add_f32_e32 v80, v81, v80
	v_fmac_f32_e32 v85, v66, v84
	v_mul_f32_e32 v84, v65, v87
	v_add_f32_e32 v88, v88, v80
	ds_read_b128 v[80:83], v182 offset:4096
	v_fmac_f32_e32 v84, v64, v86
	v_add_f32_e32 v84, v85, v84
	v_add_f32_e32 v88, v88, v84
	ds_read_b128 v[84:87], v182 offset:5120
	s_waitcnt lgkmcnt(1)
	v_mul_f32_e32 v81, v79, v81
	v_fmac_f32_e32 v81, v78, v80
	v_mul_f32_e32 v80, v77, v83
	v_fmac_f32_e32 v80, v76, v82
	s_waitcnt lgkmcnt(0)
	v_mul_f32_e32 v85, v75, v85
	v_add_f32_e32 v80, v81, v80
	v_fmac_f32_e32 v85, v74, v84
	v_mul_f32_e32 v84, v73, v87
	v_add_f32_e32 v89, 0, v80
	ds_read_b128 v[80:83], v182 offset:6144
	v_fmac_f32_e32 v84, v72, v86
	v_add_f32_e32 v84, v85, v84
	v_add_f32_e32 v89, v89, v84
	ds_read_b128 v[84:87], v182 offset:7168
	s_waitcnt lgkmcnt(1)
	v_mul_f32_e32 v81, v71, v81
	v_fmac_f32_e32 v81, v70, v80
	v_mul_f32_e32 v80, v69, v83
	v_fmac_f32_e32 v80, v68, v82
	s_waitcnt lgkmcnt(0)
	v_mul_f32_e32 v85, v67, v85
	v_add_f32_e32 v80, v81, v80
	v_fmac_f32_e32 v85, v66, v84
	v_mul_f32_e32 v84, v65, v87
	v_add_f32_e32 v89, v89, v80
	ds_read_b128 v[80:83], v182 offset:8192
	v_fmac_f32_e32 v84, v64, v86
	v_add_f32_e32 v84, v85, v84
	v_add_f32_e32 v89, v89, v84
	ds_read_b128 v[84:87], v182 offset:9216
	s_waitcnt lgkmcnt(1)
	v_mul_f32_e32 v81, v79, v81
	v_fmac_f32_e32 v81, v78, v80
	v_mul_f32_e32 v80, v77, v83
	v_fmac_f32_e32 v80, v76, v82
	s_waitcnt lgkmcnt(0)
	v_mul_f32_e32 v85, v75, v85
	v_add_f32_e32 v80, v81, v80
	v_fmac_f32_e32 v85, v74, v84
	v_mul_f32_e32 v84, v73, v87
	v_add_f32_e32 v90, 0, v80
	ds_read_b128 v[80:83], v182 offset:10240
	v_fmac_f32_e32 v84, v72, v86
	v_add_f32_e32 v84, v85, v84
	v_add_f32_e32 v90, v90, v84
	ds_read_b128 v[84:87], v182 offset:11264
	s_waitcnt lgkmcnt(1)
	v_mul_f32_e32 v81, v71, v81
	v_fmac_f32_e32 v81, v70, v80
	v_mul_f32_e32 v80, v69, v83
	v_fmac_f32_e32 v80, v68, v82
	s_waitcnt lgkmcnt(0)
	v_mul_f32_e32 v85, v67, v85
	v_add_f32_e32 v80, v81, v80
	v_fmac_f32_e32 v85, v66, v84
	v_mul_f32_e32 v84, v65, v87
	v_add_f32_e32 v90, v90, v80
	ds_read_b128 v[80:83], v182 offset:12288
	v_fmac_f32_e32 v84, v64, v86
	v_add_f32_e32 v84, v85, v84
	v_add_f32_e32 v90, v90, v84
	ds_read_b128 v[84:87], v182 offset:13312
	s_waitcnt lgkmcnt(1)
	v_mul_f32_e32 v81, v79, v81
	v_fmac_f32_e32 v81, v78, v80
	v_mul_f32_e32 v80, v77, v83
	v_fmac_f32_e32 v80, v76, v82
	s_waitcnt lgkmcnt(0)
	v_mul_f32_e32 v85, v75, v85
	v_add_f32_e32 v80, v81, v80
	v_fmac_f32_e32 v85, v74, v84
	v_mul_f32_e32 v84, v73, v87
	v_add_f32_e32 v91, 0, v80
	ds_read_b128 v[80:83], v182 offset:14336
	v_fmac_f32_e32 v84, v72, v86
	v_add_f32_e32 v84, v85, v84
	v_add_f32_e32 v91, v91, v84
	ds_read_b128 v[84:87], v182 offset:15360
	s_waitcnt lgkmcnt(1)
	v_mul_f32_e32 v81, v71, v81
	v_fmac_f32_e32 v81, v70, v80
	v_mul_f32_e32 v80, v69, v83
	v_fmac_f32_e32 v80, v68, v82
	s_waitcnt lgkmcnt(0)
	v_mul_f32_e32 v85, v67, v85
	v_add_f32_e32 v80, v81, v80
	v_fmac_f32_e32 v85, v66, v84
	v_mul_f32_e32 v84, v65, v87
	v_add_f32_e32 v91, v91, v80
	ds_read_b128 v[80:83], v182 offset:16384
	v_fmac_f32_e32 v84, v64, v86
	v_add_f32_e32 v84, v85, v84
	v_add_f32_e32 v91, v91, v84
	ds_read_b128 v[84:87], v182 offset:17408
	s_waitcnt lgkmcnt(1)
	v_mul_f32_e32 v81, v79, v81
	v_fmac_f32_e32 v81, v78, v80
	v_mul_f32_e32 v80, v77, v83
	v_fmac_f32_e32 v80, v76, v82
	s_waitcnt lgkmcnt(0)
	v_mul_f32_e32 v85, v75, v85
	v_add_f32_e32 v80, v81, v80
	v_fmac_f32_e32 v85, v74, v84
	v_mul_f32_e32 v84, v73, v87
	v_add_f32_e32 v92, 0, v80
	ds_read_b128 v[80:83], v182 offset:18432
	v_fmac_f32_e32 v84, v72, v86
	v_add_f32_e32 v84, v85, v84
	v_add_f32_e32 v92, v92, v84
	ds_read_b128 v[84:87], v182 offset:19456
	s_waitcnt lgkmcnt(1)
	v_mul_f32_e32 v81, v71, v81
	v_fmac_f32_e32 v81, v70, v80
	v_mul_f32_e32 v80, v69, v83
	v_fmac_f32_e32 v80, v68, v82
	s_waitcnt lgkmcnt(0)
	v_mul_f32_e32 v85, v67, v85
	v_add_f32_e32 v80, v81, v80
	v_fmac_f32_e32 v85, v66, v84
	v_mul_f32_e32 v84, v65, v87
	v_add_f32_e32 v92, v92, v80
	ds_read_b128 v[80:83], v182 offset:20480
	v_fmac_f32_e32 v84, v64, v86
	v_add_f32_e32 v84, v85, v84
	v_add_f32_e32 v92, v92, v84
	ds_read_b128 v[84:87], v182 offset:21504
	s_waitcnt lgkmcnt(1)
	v_mul_f32_e32 v81, v79, v81
	v_fmac_f32_e32 v81, v78, v80
	v_mul_f32_e32 v80, v77, v83
	v_fmac_f32_e32 v80, v76, v82
	s_waitcnt lgkmcnt(0)
	v_mul_f32_e32 v85, v75, v85
	v_add_f32_e32 v80, v81, v80
	v_fmac_f32_e32 v85, v74, v84
	v_mul_f32_e32 v84, v73, v87
	v_add_f32_e32 v93, 0, v80
	ds_read_b128 v[80:83], v182 offset:22528
	v_fmac_f32_e32 v84, v72, v86
	v_add_f32_e32 v84, v85, v84
	v_add_f32_e32 v93, v93, v84
	ds_read_b128 v[84:87], v182 offset:23552
	s_waitcnt lgkmcnt(1)
	v_mul_f32_e32 v81, v71, v81
	v_fmac_f32_e32 v81, v70, v80
	v_mul_f32_e32 v80, v69, v83
	v_fmac_f32_e32 v80, v68, v82
	s_waitcnt lgkmcnt(0)
	v_mul_f32_e32 v85, v67, v85
	v_add_f32_e32 v80, v81, v80
	v_fmac_f32_e32 v85, v66, v84
	v_mul_f32_e32 v84, v65, v87
	v_add_f32_e32 v93, v93, v80
	ds_read_b128 v[80:83], v182 offset:24576
	v_fmac_f32_e32 v84, v64, v86
	v_add_f32_e32 v84, v85, v84
	v_add_f32_e32 v93, v93, v84
	ds_read_b128 v[84:87], v182 offset:25600
	s_waitcnt lgkmcnt(1)
	v_mul_f32_e32 v81, v79, v81
	v_fmac_f32_e32 v81, v78, v80
	v_mul_f32_e32 v80, v77, v83
	v_fmac_f32_e32 v80, v76, v82
	s_waitcnt lgkmcnt(0)
	v_mul_f32_e32 v85, v75, v85
	v_add_f32_e32 v80, v81, v80
	v_fmac_f32_e32 v85, v74, v84
	v_mul_f32_e32 v84, v73, v87
	v_add_f32_e32 v94, 0, v80
	ds_read_b128 v[80:83], v182 offset:26624
	v_fmac_f32_e32 v84, v72, v86
	v_add_f32_e32 v84, v85, v84
	v_add_f32_e32 v94, v94, v84
	ds_read_b128 v[84:87], v182 offset:27648
	s_waitcnt lgkmcnt(1)
	v_mul_f32_e32 v81, v71, v81
	v_fmac_f32_e32 v81, v70, v80
	v_mul_f32_e32 v80, v69, v83
	v_fmac_f32_e32 v80, v68, v82
	s_waitcnt lgkmcnt(0)
	v_mul_f32_e32 v85, v67, v85
	v_add_f32_e32 v80, v81, v80
	v_fmac_f32_e32 v85, v66, v84
	v_mul_f32_e32 v84, v65, v87
	v_add_f32_e32 v94, v94, v80
	ds_read_b128 v[80:83], v182 offset:28672
	v_fmac_f32_e32 v84, v64, v86
	v_add_f32_e32 v84, v85, v84
	v_add_f32_e32 v94, v94, v84
	ds_read_b128 v[84:87], v182 offset:29696
	s_waitcnt lgkmcnt(1)
	v_mul_f32_e32 v79, v79, v81
	v_mul_f32_e32 v77, v77, v83
	v_fmac_f32_e32 v79, v78, v80
	v_fmac_f32_e32 v77, v76, v82
	v_add_f32_e32 v76, v79, v77
	s_waitcnt lgkmcnt(0)
	v_mul_f32_e32 v79, v75, v85
	v_mul_f32_e32 v73, v73, v87
	v_fmac_f32_e32 v79, v74, v84
	v_fmac_f32_e32 v73, v72, v86
	v_add_f32_e32 v78, 0, v76
	v_add_f32_e32 v72, v79, v73
	ds_read_b128 v[74:77], v182 offset:30720
	v_add_f32_e32 v72, v78, v72
	ds_read_b128 v[78:81], v182 offset:31744
	s_waitcnt lgkmcnt(1)
	v_mul_f32_e32 v71, v71, v75
	v_mul_f32_e32 v69, v69, v77
	s_waitcnt lgkmcnt(0)
	v_mul_f32_e32 v67, v67, v79
	v_fmac_f32_e32 v67, v66, v78
	v_cndmask_b32_e32 v66, v88, v92, vcc
	ds_bpermute_b32 v66, v184, v66
	v_fmac_f32_e32 v71, v70, v74
	v_fmac_f32_e32 v69, v68, v76
	v_mul_f32_e32 v65, v65, v81
	v_add_f32_e32 v68, v71, v69
	v_fmac_f32_e32 v65, v64, v80
	v_add_f32_e32 v68, v72, v68
	v_add_f32_e32 v64, v67, v65
	v_cndmask_b32_e32 v65, v92, v88, vcc
	v_add_f32_e32 v64, v68, v64
	s_waitcnt lgkmcnt(0)
	v_add_f32_e32 v65, v65, v66
	v_cndmask_b32_e32 v66, v89, v93, vcc
	ds_bpermute_b32 v66, v184, v66
	v_cndmask_b32_e32 v68, v90, v94, vcc
	v_cndmask_b32_e32 v69, v91, v64, vcc
	ds_bpermute_b32 v68, v184, v68
	ds_bpermute_b32 v69, v184, v69
	v_cndmask_b32_e32 v67, v93, v89, vcc
	s_waitcnt lgkmcnt(2)
	v_add_f32_e32 v66, v67, v66
	v_cndmask_b32_e32 v67, v94, v90, vcc
	v_cndmask_b32_e32 v64, v64, v91, vcc
	s_waitcnt lgkmcnt(1)
	v_add_f32_e32 v67, v67, v68
	s_waitcnt lgkmcnt(0)
	v_add_f32_e32 v64, v64, v69
	v_cndmask_b32_e64 v68, v65, v67, s[4:5]
	v_cndmask_b32_e64 v69, v66, v64, s[4:5]
	ds_bpermute_b32 v68, v185, v68
	ds_bpermute_b32 v69, v185, v69
	v_cndmask_b32_e64 v65, v67, v65, s[4:5]
	v_cndmask_b32_e64 v64, v64, v66, s[4:5]
	s_waitcnt lgkmcnt(1)
	v_add_f32_e32 v65, v65, v68
	s_waitcnt lgkmcnt(0)
	v_add_f32_e32 v64, v64, v69
	v_cndmask_b32_e64 v66, v65, v64, s[6:7]
	ds_bpermute_b32 v66, v186, v66
	v_cndmask_b32_e64 v64, v64, v65, s[6:7]
	s_waitcnt lgkmcnt(0)
	v_add_f32_e32 v64, v64, v66
	ds_bpermute_b32 v65, v187, v64
	s_waitcnt lgkmcnt(0)
	v_add_f32_e32 v64, v64, v65
	ds_bpermute_b32 v65, v188, v64
	s_waitcnt lgkmcnt(0)
	v_add_f32_e32 v64, v64, v65
	ds_bpermute_b32 v65, v189, v64
	s_and_saveexec_b64 s[30:31], s[8:9]
	s_cbranch_execz .LBB0_100
	v_mov_b32_e32 v66, v216
	s_waitcnt lgkmcnt(0)
	v_add_f32_e32 v67, v64, v65
	s_ashr_i32 s0, s28, 31
	s_lshr_b32 s0, s0, 19
	s_add_i32 s0, s28, s0
	s_ashr_i32 s1, s0, 13
	s_and_b32 s0, s0, 0xffffe000
	v_lshl_or_b32 v64, s1, 3, v183
	s_sub_i32 s28, s28, s0
	v_ashrrev_i32_e32 v65, 31, v64
	v_lshlrev_b64 v[64:65], 15, v[64:65]
	s_ashr_i32 s29, s28, 31
	v_lshl_add_u64 v[64:65], s[12:13], 0, v[64:65]
	v_lshl_add_u64 v[64:65], s[28:29], 2, v[64:65]
	v_add_f32_e32 v66, v67, v66
	v_mul_f32_e64 v67, |v66|, s41
	v_exp_f32_e32 v80, v67
	v_min_f32_e32 v81, 0, v66
	v_add_f32_e32 v68, 1.0, v80
	v_add_f32_e32 v69, -1.0, v68
	v_frexp_mant_f32_e32 v70, v68
	v_cvt_f64_f32_e32 v[66:67], v68
	v_sub_f32_e32 v71, v69, v68
	v_frexp_exp_i32_f64_e32 v66, v[66:67]
	v_cmp_gt_f32_e64 s[0:1], s42, v70
	v_sub_f32_e32 v69, v80, v69
	v_add_f32_e32 v67, 1.0, v71
	v_subbrev_co_u32_e64 v66, s[0:1], 0, v66, s[0:1]
	v_add_f32_e32 v67, v69, v67
	v_sub_u32_e32 v69, 0, v66
	v_ldexp_f32 v68, v68, v69
	v_add_f32_e32 v70, -1.0, v68
	v_add_f32_e32 v71, 1.0, v68
	v_ldexp_f32 v67, v67, v69
	v_add_f32_e32 v69, 1.0, v70
	v_add_f32_e32 v72, -1.0, v71
	v_sub_f32_e32 v69, v68, v69
	v_sub_f32_e32 v68, v68, v72
	v_add_f32_e32 v72, v67, v69
	v_add_f32_e32 v67, v67, v68
	v_add_f32_e32 v74, v71, v67
	v_rcp_f32_e32 v75, v74
	v_add_f32_e32 v69, v70, v72
	v_sub_f32_e32 v70, v69, v70
	v_sub_f32_e32 v68, v74, v71
	v_mul_f32_e32 v77, v69, v75
	v_sub_f32_e32 v76, v72, v70
	v_mul_f32_e32 v70, v74, v77
	v_sub_f32_e32 v67, v67, v68
	v_fma_f32 v72, v77, v74, -v70
	v_fmac_f32_e32 v72, v77, v67
	v_add_f32_e32 v68, v70, v72
	v_sub_f32_e32 v71, v69, v68
	v_mov_b32_e32 v73, v68
	v_pk_add_f32 v[68:69], v[68:69], v[70:71] neg_lo:[0,1] neg_hi:[0,1]
	v_cvt_f32_i32_e32 v66, v66
	v_pk_add_f32 v[68:69], v[68:69], v[72:73] neg_lo:[0,1] neg_hi:[0,1]
	v_cmp_neq_f32_e64 s[0:1], s44, v80
	v_add_f32_e32 v69, v76, v69
	v_add_f32_e32 v68, v68, v69
	v_add_f32_e32 v69, v71, v68
	v_mul_f32_e32 v73, v75, v69
	v_mul_f32_e32 v70, v74, v73
	v_sub_f32_e32 v71, v71, v69
	v_add_f32_e32 v78, v77, v73
	v_fma_f32 v72, v73, v74, -v70
	v_add_f32_e32 v76, v68, v71
	v_sub_f32_e32 v68, v78, v77
	v_fmac_f32_e32 v72, v73, v67
	v_sub_f32_e32 v67, v73, v68
	v_add_f32_e32 v68, v70, v72
	v_sub_f32_e32 v71, v69, v68
	v_mov_b32_e32 v73, v68
	v_pk_add_f32 v[68:69], v[68:69], v[70:71] neg_lo:[0,1] neg_hi:[0,1]
	s_nop 0
	v_pk_add_f32 v[68:69], v[68:69], v[72:73] neg_lo:[0,1] neg_hi:[0,1]
	s_nop 0
	v_add_f32_e32 v69, v76, v69
	v_add_f32_e32 v68, v68, v69
	v_add_f32_e32 v68, v71, v68
	v_mul_f32_e32 v68, v75, v68
	v_add_f32_e32 v67, v67, v68
	v_add_f32_e32 v68, v78, v67
	v_mul_f32_e32 v70, v68, v68
	v_sub_f32_e32 v71, v68, v78
	v_fmamk_f32 v72, v70, 0x3e9b6dac, v195
	v_sub_f32_e32 v71, v67, v71
	v_mul_f32_e32 v67, v68, v70
	v_fmaak_f32 v147, v70, v72, 0x3f2aaada
	v_ldexp_f32 v73, v71, 1
	v_pk_mul_f32 v[70:71], v[66:67], v[146:147]
	v_ldexp_f32 v69, v68, 1
	v_fma_f32 v68, v66, s43, -v70
	v_fmac_f32_e32 v68, 0xb102e308, v66
	v_pk_add_f32 v[66:67], v[70:71], v[68:69]
	v_mov_b32_e32 v72, v70
	v_sub_f32_e32 v76, v67, v69
	v_pk_add_f32 v[74:75], v[66:67], v[70:71] neg_lo:[0,1] neg_hi:[0,1]
	v_sub_f32_e32 v70, v71, v76
	v_add_f32_e32 v73, v73, v70
	v_pk_add_f32 v[70:71], v[66:67], v[72:73]
	v_mov_b32_e32 v69, v66
	v_mov_b32_e32 v75, v71
	v_pk_add_f32 v[78:79], v[68:69], v[74:75] neg_lo:[0,1] neg_hi:[0,1]
	v_pk_add_f32 v[68:69], v[68:69], v[74:75]
	v_mov_b32_e32 v77, v66
	v_pk_add_f32 v[74:75], v[68:69], v[66:67] op_sel:[1,0] op_sel_hi:[0,1] neg_lo:[0,1] neg_hi:[0,1]
	v_mov_b32_e32 v76, v73
	v_mov_b32_e32 v72, v71
	v_mov_b32_e32 v73, v69
	v_pk_mov_b32 v[66:67], v[66:67], v[74:75] op_sel:[1,0]
	v_pk_add_f32 v[70:71], v[70:71], v[74:75] op_sel_hi:[1,0] neg_lo:[0,1] neg_hi:[0,1]
	v_pk_add_f32 v[66:67], v[72:73], v[66:67] neg_lo:[0,1] neg_hi:[0,1]
	v_mov_b32_e32 v70, v78
	v_pk_add_f32 v[66:67], v[76:77], v[66:67] neg_lo:[0,1] neg_hi:[0,1]
	v_mov_b32_e32 v79, v69
	v_pk_add_f32 v[70:71], v[70:71], v[66:67]
	s_nop 0
	v_pk_add_f32 v[72:73], v[70:71], v[70:71] op_sel:[0,1] op_sel_hi:[1,0]
	s_nop 0
	v_pk_add_f32 v[68:69], v[68:69], v[72:73] op_sel:[1,0] op_sel_hi:[0,1]
	v_mov_b32_e32 v71, v68
	v_mov_b32_e32 v67, v72
	v_pk_add_f32 v[72:73], v[70:71], v[78:79] neg_lo:[0,1] neg_hi:[0,1]
	s_nop 0
	v_sub_f32_e32 v69, v70, v72
	v_pk_add_f32 v[66:67], v[66:67], v[72:73] neg_lo:[0,1] neg_hi:[0,1]
	v_sub_f32_e32 v69, v78, v69
	v_add_f32_e32 v66, v66, v69
	v_add_f32_e32 v66, v66, v67
	v_add_f32_e32 v66, v68, v66
	v_cndmask_b32_e64 v66, v196, v66, s[0:1]
	v_cmp_ngt_f32_e64 s[0:1], -1.0, v80
	s_nop 1
	v_cndmask_b32_e64 v66, v197, v66, s[0:1]
	v_cmp_neq_f32_e64 s[0:1], -1.0, v80
	s_nop 1
	v_cndmask_b32_e64 v66, v198, v66, s[0:1]
	v_cmp_lt_f32_e64 s[0:1], |v80|, s45
	s_nop 1
	v_cndmask_b32_e64 v66, v66, v80, s[0:1]
	v_sub_f32_e32 v66, v81, v66
	global_store_dword v[64:65], v66, off
.LBB0_100:
	s_or_b64 exec, exec, s[30:31]
	s_waitcnt vmcnt(31) lgkmcnt(0)
	v_pk_mul_f32 v[64:65], v[62:63], v[62:63]
	v_pk_mul_f32 v[66:67], v[60:61], v[60:61]
	s_lshl_b64 s[0:1], s[26:27], 11
	v_pk_mov_b32 v[68:69], v[66:67], v[64:65] op_sel:[1,0]
	v_mov_b32_e32 v67, v65
	v_pk_add_f32 v[64:65], v[68:69], v[66:67]
	s_waitcnt vmcnt(30)
	v_pk_mul_f32 v[66:67], v[58:59], v[58:59]
	v_pk_mul_f32 v[68:69], v[56:57], v[56:57]
	v_pk_add_f32 v[64:65], v[64:65], v[64:65] op_sel:[0,1] op_sel_hi:[1,0]
	v_pk_mov_b32 v[70:71], v[68:69], v[66:67] op_sel:[1,0]
	v_mov_b32_e32 v69, v67
	v_pk_add_f32 v[66:67], v[70:71], v[68:69]
	s_waitcnt vmcnt(28)
	v_mul_f32_e32 v68, v48, v48
	v_mul_f32_e32 v69, v49, v49
	v_pk_add_f32 v[66:67], v[66:67], v[66:67] op_sel:[0,1] op_sel_hi:[1,0]
	v_mov_b32_e32 v65, v68
	v_mov_b32_e32 v67, v69
	v_pk_add_f32 v[64:65], v[64:65], v[66:67]
	v_mul_f32_e32 v66, v53, v53
	v_mul_f32_e32 v68, v55, v55
	v_mul_f32_e32 v70, v50, v50
	v_mul_f32_e32 v71, v51, v51
	v_pk_fma_f32 v[66:67], v[52:53], v[52:53], v[66:67] op_sel_hi:[1,1,0]
	v_pk_fma_f32 v[68:69], v[54:55], v[54:55], v[68:69] op_sel_hi:[1,1,0]
	v_mov_b32_e32 v67, v70
	v_mov_b32_e32 v69, v71
	v_pk_add_f32 v[66:67], v[66:67], v[68:69]
	s_waitcnt vmcnt(22)
	v_mul_f32_e32 v68, v27, v27
	v_pk_add_f32 v[64:65], v[64:65], v[66:67]
	v_mul_f32_e32 v66, v47, v47
	v_add_f32_e32 v64, v64, v65
	v_mul_f32_e32 v65, v45, v45
	v_fmac_f32_e32 v65, v44, v44
	v_fmac_f32_e32 v66, v46, v46
	v_add_f32_e32 v65, v65, v66
	v_mul_f32_e32 v66, v41, v41
	v_mul_f32_e32 v67, v43, v43
	v_fmac_f32_e32 v66, v40, v40
	v_fmac_f32_e32 v67, v42, v42
	v_add_f32_e32 v66, v66, v67
	v_add_f32_e32 v65, v65, v66
	v_mul_f32_e32 v66, v37, v37
	v_mul_f32_e32 v67, v39, v39
	v_fmac_f32_e32 v66, v36, v36
	v_fmac_f32_e32 v67, v38, v38
	v_add_f32_e32 v66, v66, v67
	v_add_f32_e32 v65, v65, v66
	v_mul_f32_e32 v66, v33, v33
	v_mul_f32_e32 v67, v35, v35
	v_fmac_f32_e32 v66, v32, v32
	v_fmac_f32_e32 v67, v34, v34
	v_add_f32_e32 v66, v66, v67
	v_add_f32_e32 v65, v65, v66
	v_mul_f32_e32 v66, v29, v29
	v_mul_f32_e32 v67, v31, v31
	v_fmac_f32_e32 v66, v28, v28
	v_fmac_f32_e32 v67, v30, v30
	v_add_f32_e32 v66, v66, v67
	v_mul_f32_e32 v67, v25, v25
	v_fmac_f32_e32 v67, v24, v24
	v_fmac_f32_e32 v68, v26, v26
	v_add_f32_e32 v67, v67, v68
	v_add_f32_e32 v66, v66, v67
	s_waitcnt vmcnt(21)
	v_mul_f32_e32 v67, v21, v21
	v_mul_f32_e32 v68, v23, v23
	v_fmac_f32_e32 v67, v20, v20
	v_fmac_f32_e32 v68, v22, v22
	v_add_f32_e32 v67, v67, v68
	v_add_f32_e32 v66, v66, v67
	s_waitcnt vmcnt(20)
	v_mul_f32_e32 v67, v17, v17
	v_mul_f32_e32 v68, v19, v19
	v_fmac_f32_e32 v67, v16, v16
	v_fmac_f32_e32 v68, v18, v18
	v_add_f32_e32 v67, v67, v68
	v_add_f32_e32 v66, v66, v67
	s_waitcnt vmcnt(19)
	v_mul_f32_e32 v67, v13, v13
	v_mul_f32_e32 v68, v15, v15
	v_fmac_f32_e32 v67, v12, v12
	v_fmac_f32_e32 v68, v14, v14
	v_add_f32_e32 v67, v67, v68
	s_waitcnt vmcnt(18)
	v_mul_f32_e32 v68, v9, v9
	v_mul_f32_e32 v69, v11, v11
	v_fmac_f32_e32 v68, v8, v8
	v_fmac_f32_e32 v69, v10, v10
	v_add_f32_e32 v68, v68, v69
	v_add_f32_e32 v67, v67, v68
	s_waitcnt vmcnt(17)
	v_mul_f32_e32 v68, v5, v5
	v_mul_f32_e32 v69, v7, v7
	v_fmac_f32_e32 v68, v4, v4
	v_fmac_f32_e32 v69, v6, v6
	v_add_f32_e32 v68, v68, v69
	ds_bpermute_b32 v69, v184, v64
	v_add_f32_e32 v67, v67, v68
	s_waitcnt vmcnt(16)
	v_mul_f32_e32 v68, v1, v1
	v_mul_f32_e32 v70, v3, v3
	v_fmac_f32_e32 v68, v0, v0
	s_waitcnt lgkmcnt(0)
	v_add_f32_e32 v64, v64, v69
	ds_bpermute_b32 v69, v185, v64
	v_fmac_f32_e32 v70, v2, v2
	v_add_f32_e32 v68, v68, v70
	v_add_f32_e32 v67, v67, v68
	ds_bpermute_b32 v71, v184, v65
	s_waitcnt lgkmcnt(1)
	v_add_f32_e32 v64, v64, v69
	ds_bpermute_b32 v68, v186, v64
	ds_bpermute_b32 v69, v184, v66
	ds_bpermute_b32 v70, v184, v67
	s_waitcnt lgkmcnt(3)
	v_add_f32_e32 v65, v65, v71
	ds_bpermute_b32 v71, v185, v65
	s_waitcnt lgkmcnt(3)
	v_add_f32_e32 v64, v64, v68
	ds_bpermute_b32 v68, v187, v64
	s_waitcnt lgkmcnt(3)
	v_add_f32_e32 v66, v66, v69
	ds_bpermute_b32 v69, v185, v66
	s_waitcnt lgkmcnt(2)
	v_add_f32_e32 v65, v65, v71
	v_add_f32_e32 v67, v67, v70
	s_waitcnt lgkmcnt(1)
	v_add_f32_e32 v64, v64, v68
	ds_bpermute_b32 v68, v188, v64
	s_waitcnt lgkmcnt(1)
	v_add_f32_e32 v66, v66, v69
	ds_bpermute_b32 v71, v186, v66
	ds_bpermute_b32 v70, v186, v65
	ds_bpermute_b32 v69, v185, v67
	s_waitcnt lgkmcnt(3)
	v_add_f32_e32 v68, v64, v68
	ds_bpermute_b32 v72, v189, v68
	s_waitcnt lgkmcnt(3)
	v_add_f32_e32 v64, v66, v71
	s_waitcnt lgkmcnt(2)
	v_add_f32_e32 v65, v65, v70
	s_waitcnt lgkmcnt(1)
	v_add_f32_e32 v73, v67, v69
	ds_bpermute_b32 v74, v186, v73
	s_waitcnt lgkmcnt(1)
	v_add_f32_e32 v66, v68, v72
	v_fmamk_f32 v66, v66, 0x3a800000, v194
	v_rsq_f32_e32 v66, v66
	v_lshl_add_u64 v[68:69], v[130:131], 0, s[0:1]
	ds_bpermute_b32 v72, v187, v65
	s_waitcnt lgkmcnt(1)
	v_add_f32_e32 v74, v73, v74
	v_pk_mul_f32 v[70:71], v[60:61], v[66:67] op_sel_hi:[1,0]
	v_pk_mul_f32 v[60:61], v[62:63], v[66:67] op_sel_hi:[1,0]
	v_pk_fma_f32 v[62:63], v[154:155], v[70:71], v[150:151]
	v_pk_fma_f32 v[60:61], v[152:153], v[60:61], v[148:149]
	v_cvt_pk_bf16_f32 v70, v62, v63
	s_waitcnt lgkmcnt(0)
	v_add_f32_e32 v65, v65, v72
	v_cvt_pk_bf16_f32 v71, v60, v61
	global_store_dwordx2 v[68:69], v[70:71], off
	v_pk_mul_f32 v[70:71], v[56:57], v[66:67] op_sel_hi:[1,0]
	v_pk_mul_f32 v[56:57], v[58:59], v[66:67] op_sel_hi:[1,0]
	v_pk_fma_f32 v[58:59], v[162:163], v[70:71], v[158:159]
	v_pk_fma_f32 v[56:57], v[160:161], v[56:57], v[156:157]
	v_cvt_pk_bf16_f32 v70, v58, v59
	ds_bpermute_b32 v75, v187, v64
	v_cvt_pk_bf16_f32 v71, v56, v57
	global_store_dwordx2 v[68:69], v[70:71], off offset:512
	v_pk_mul_f32 v[70:71], v[52:53], v[66:67] op_sel_hi:[1,0]
	v_pk_mul_f32 v[52:53], v[54:55], v[66:67] op_sel_hi:[1,0]
	v_pk_fma_f32 v[54:55], v[170:171], v[70:71], v[166:167]
	v_pk_fma_f32 v[52:53], v[168:169], v[52:53], v[164:165]
	v_cvt_pk_bf16_f32 v70, v54, v55
	s_nop 0
	v_cvt_pk_bf16_f32 v71, v52, v53
	global_store_dwordx2 v[68:69], v[70:71], off offset:1024
	v_pk_mul_f32 v[70:71], v[48:49], v[66:67] op_sel_hi:[1,0]
	v_pk_mul_f32 v[48:49], v[50:51], v[66:67] op_sel_hi:[1,0]
	v_pk_fma_f32 v[50:51], v[178:179], v[70:71], v[174:175]
	v_pk_fma_f32 v[48:49], v[176:177], v[48:49], v[172:173]
	v_cvt_pk_bf16_f32 v66, v50, v51
	s_nop 0
	v_cvt_pk_bf16_f32 v67, v48, v49
	global_store_dwordx2 v[68:69], v[66:67], off offset:1536
	ds_read_b128 v[66:69], v182
	ds_read_b128 v[70:73], v182 offset:1024
	s_waitcnt lgkmcnt(1)
	v_mul_f32_e32 v67, v63, v67
	v_fmac_f32_e32 v67, v62, v66
	v_mul_f32_e32 v66, v61, v69
	v_fmac_f32_e32 v66, v60, v68
	s_waitcnt lgkmcnt(0)
	v_mul_f32_e32 v71, v59, v71
	v_add_f32_e32 v66, v67, v66
	v_fmac_f32_e32 v71, v58, v70
	v_mul_f32_e32 v70, v57, v73
	v_add_f32_e32 v76, 0, v66
	ds_read_b128 v[66:69], v182 offset:2048
	v_fmac_f32_e32 v70, v56, v72
	v_add_f32_e32 v70, v71, v70
	v_add_f32_e32 v76, v76, v70
	ds_read_b128 v[70:73], v182 offset:3072
	s_waitcnt lgkmcnt(1)
	v_mul_f32_e32 v67, v55, v67
	v_fmac_f32_e32 v67, v54, v66
	v_mul_f32_e32 v66, v53, v69
	v_fmac_f32_e32 v66, v52, v68
	s_waitcnt lgkmcnt(0)
	v_mul_f32_e32 v71, v51, v71
	v_add_f32_e32 v66, v67, v66
	v_fmac_f32_e32 v71, v50, v70
	v_mul_f32_e32 v70, v49, v73
	v_add_f32_e32 v76, v76, v66
	ds_read_b128 v[66:69], v182 offset:4096
	v_fmac_f32_e32 v70, v48, v72
	v_add_f32_e32 v70, v71, v70
	v_add_f32_e32 v76, v76, v70
	ds_read_b128 v[70:73], v182 offset:5120
	s_waitcnt lgkmcnt(1)
	v_mul_f32_e32 v67, v63, v67
	v_fmac_f32_e32 v67, v62, v66
	v_mul_f32_e32 v66, v61, v69
	v_fmac_f32_e32 v66, v60, v68
	s_waitcnt lgkmcnt(0)
	v_mul_f32_e32 v71, v59, v71
	v_add_f32_e32 v66, v67, v66
	v_fmac_f32_e32 v71, v58, v70
	v_mul_f32_e32 v70, v57, v73
	v_add_f32_e32 v77, 0, v66
	ds_read_b128 v[66:69], v182 offset:6144
	v_fmac_f32_e32 v70, v56, v72
	v_add_f32_e32 v70, v71, v70
	v_add_f32_e32 v77, v77, v70
	ds_read_b128 v[70:73], v182 offset:7168
	s_waitcnt lgkmcnt(1)
	v_mul_f32_e32 v67, v55, v67
	v_fmac_f32_e32 v67, v54, v66
	v_mul_f32_e32 v66, v53, v69
	v_fmac_f32_e32 v66, v52, v68
	s_waitcnt lgkmcnt(0)
	v_mul_f32_e32 v71, v51, v71
	v_add_f32_e32 v66, v67, v66
	v_fmac_f32_e32 v71, v50, v70
	v_mul_f32_e32 v70, v49, v73
	v_add_f32_e32 v77, v77, v66
	ds_read_b128 v[66:69], v182 offset:8192
	v_fmac_f32_e32 v70, v48, v72
	v_add_f32_e32 v70, v71, v70
	v_add_f32_e32 v77, v77, v70
	ds_read_b128 v[70:73], v182 offset:9216
	s_waitcnt lgkmcnt(1)
	v_mul_f32_e32 v67, v63, v67
	v_fmac_f32_e32 v67, v62, v66
	v_mul_f32_e32 v66, v61, v69
	v_fmac_f32_e32 v66, v60, v68
	s_waitcnt lgkmcnt(0)
	v_mul_f32_e32 v71, v59, v71
	v_add_f32_e32 v66, v67, v66
	v_fmac_f32_e32 v71, v58, v70
	v_mul_f32_e32 v70, v57, v73
	v_add_f32_e32 v78, 0, v66
	ds_read_b128 v[66:69], v182 offset:10240
	v_fmac_f32_e32 v70, v56, v72
	v_add_f32_e32 v70, v71, v70
	v_add_f32_e32 v78, v78, v70
	ds_read_b128 v[70:73], v182 offset:11264
	s_waitcnt lgkmcnt(1)
	v_mul_f32_e32 v67, v55, v67
	v_fmac_f32_e32 v67, v54, v66
	v_mul_f32_e32 v66, v53, v69
	v_fmac_f32_e32 v66, v52, v68
	s_waitcnt lgkmcnt(0)
	v_mul_f32_e32 v71, v51, v71
	v_add_f32_e32 v66, v67, v66
	v_fmac_f32_e32 v71, v50, v70
	v_mul_f32_e32 v70, v49, v73
	v_add_f32_e32 v78, v78, v66
	ds_read_b128 v[66:69], v182 offset:12288
	v_fmac_f32_e32 v70, v48, v72
	v_add_f32_e32 v70, v71, v70
	v_add_f32_e32 v78, v78, v70
	ds_read_b128 v[70:73], v182 offset:13312
	s_waitcnt lgkmcnt(1)
	v_mul_f32_e32 v67, v63, v67
	v_fmac_f32_e32 v67, v62, v66
	v_mul_f32_e32 v66, v61, v69
	v_fmac_f32_e32 v66, v60, v68
	s_waitcnt lgkmcnt(0)
	v_mul_f32_e32 v71, v59, v71
	v_add_f32_e32 v66, v67, v66
	v_fmac_f32_e32 v71, v58, v70
	v_mul_f32_e32 v70, v57, v73
	v_add_f32_e32 v79, 0, v66
	ds_read_b128 v[66:69], v182 offset:14336
	v_fmac_f32_e32 v70, v56, v72
	v_add_f32_e32 v70, v71, v70
	v_add_f32_e32 v79, v79, v70
	ds_read_b128 v[70:73], v182 offset:15360
	s_waitcnt lgkmcnt(1)
	v_mul_f32_e32 v67, v55, v67
	v_fmac_f32_e32 v67, v54, v66
	v_mul_f32_e32 v66, v53, v69
	v_fmac_f32_e32 v66, v52, v68
	s_waitcnt lgkmcnt(0)
	v_mul_f32_e32 v71, v51, v71
	v_add_f32_e32 v66, v67, v66
	v_fmac_f32_e32 v71, v50, v70
	v_mul_f32_e32 v70, v49, v73
	v_add_f32_e32 v79, v79, v66
	ds_read_b128 v[66:69], v182 offset:16384
	v_fmac_f32_e32 v70, v48, v72
	v_add_f32_e32 v70, v71, v70
	v_add_f32_e32 v79, v79, v70
	ds_read_b128 v[70:73], v182 offset:17408
	s_waitcnt lgkmcnt(1)
	v_mul_f32_e32 v67, v63, v67
	v_fmac_f32_e32 v67, v62, v66
	v_mul_f32_e32 v66, v61, v69
	v_fmac_f32_e32 v66, v60, v68
	s_waitcnt lgkmcnt(0)
	v_mul_f32_e32 v71, v59, v71
	v_add_f32_e32 v66, v67, v66
	v_fmac_f32_e32 v71, v58, v70
	v_mul_f32_e32 v70, v57, v73
	v_add_f32_e32 v80, 0, v66
	ds_read_b128 v[66:69], v182 offset:18432
	v_fmac_f32_e32 v70, v56, v72
	v_add_f32_e32 v70, v71, v70
	v_add_f32_e32 v80, v80, v70
	ds_read_b128 v[70:73], v182 offset:19456
	s_waitcnt lgkmcnt(1)
	v_mul_f32_e32 v67, v55, v67
	v_fmac_f32_e32 v67, v54, v66
	v_mul_f32_e32 v66, v53, v69
	v_fmac_f32_e32 v66, v52, v68
	s_waitcnt lgkmcnt(0)
	v_mul_f32_e32 v71, v51, v71
	v_add_f32_e32 v66, v67, v66
	v_fmac_f32_e32 v71, v50, v70
	v_mul_f32_e32 v70, v49, v73
	v_add_f32_e32 v80, v80, v66
	ds_read_b128 v[66:69], v182 offset:20480
	v_fmac_f32_e32 v70, v48, v72
	v_add_f32_e32 v70, v71, v70
	v_add_f32_e32 v80, v80, v70
	ds_read_b128 v[70:73], v182 offset:21504
	s_waitcnt lgkmcnt(1)
	v_mul_f32_e32 v67, v63, v67
	v_fmac_f32_e32 v67, v62, v66
	v_mul_f32_e32 v66, v61, v69
	v_fmac_f32_e32 v66, v60, v68
	s_waitcnt lgkmcnt(0)
	v_mul_f32_e32 v71, v59, v71
	v_add_f32_e32 v66, v67, v66
	v_fmac_f32_e32 v71, v58, v70
	v_mul_f32_e32 v70, v57, v73
	v_add_f32_e32 v81, 0, v66
	ds_read_b128 v[66:69], v182 offset:22528
	v_fmac_f32_e32 v70, v56, v72
	v_add_f32_e32 v70, v71, v70
	v_add_f32_e32 v81, v81, v70
	ds_read_b128 v[70:73], v182 offset:23552
	s_waitcnt lgkmcnt(1)
	v_mul_f32_e32 v67, v55, v67
	v_fmac_f32_e32 v67, v54, v66
	v_mul_f32_e32 v66, v53, v69
	v_fmac_f32_e32 v66, v52, v68
	s_waitcnt lgkmcnt(0)
	v_mul_f32_e32 v71, v51, v71
	v_add_f32_e32 v66, v67, v66
	v_fmac_f32_e32 v71, v50, v70
	v_mul_f32_e32 v70, v49, v73
	v_add_f32_e32 v81, v81, v66
	ds_read_b128 v[66:69], v182 offset:24576
	v_fmac_f32_e32 v70, v48, v72
	v_add_f32_e32 v70, v71, v70
	v_add_f32_e32 v81, v81, v70
	ds_read_b128 v[70:73], v182 offset:25600
	s_waitcnt lgkmcnt(1)
	v_mul_f32_e32 v67, v63, v67
	v_fmac_f32_e32 v67, v62, v66
	v_mul_f32_e32 v66, v61, v69
	v_fmac_f32_e32 v66, v60, v68
	s_waitcnt lgkmcnt(0)
	v_mul_f32_e32 v71, v59, v71
	v_add_f32_e32 v66, v67, v66
	v_fmac_f32_e32 v71, v58, v70
	v_mul_f32_e32 v70, v57, v73
	v_add_f32_e32 v82, 0, v66
	ds_read_b128 v[66:69], v182 offset:26624
	v_fmac_f32_e32 v70, v56, v72
	v_add_f32_e32 v70, v71, v70
	v_add_f32_e32 v82, v82, v70
	ds_read_b128 v[70:73], v182 offset:27648
	s_waitcnt lgkmcnt(1)
	v_mul_f32_e32 v67, v55, v67
	v_fmac_f32_e32 v67, v54, v66
	v_mul_f32_e32 v66, v53, v69
	v_fmac_f32_e32 v66, v52, v68
	s_waitcnt lgkmcnt(0)
	v_mul_f32_e32 v71, v51, v71
	v_add_f32_e32 v66, v67, v66
	v_fmac_f32_e32 v71, v50, v70
	v_mul_f32_e32 v70, v49, v73
	v_add_f32_e32 v82, v82, v66
	ds_read_b128 v[66:69], v182 offset:28672
	v_fmac_f32_e32 v70, v48, v72
	v_add_f32_e32 v70, v71, v70
	v_add_f32_e32 v82, v82, v70
	ds_read_b128 v[70:73], v182 offset:29696
	s_waitcnt lgkmcnt(1)
	v_mul_f32_e32 v63, v63, v67
	v_mul_f32_e32 v61, v61, v69
	v_fmac_f32_e32 v63, v62, v66
	v_fmac_f32_e32 v61, v60, v68
	v_add_f32_e32 v60, v63, v61
	s_waitcnt lgkmcnt(0)
	v_mul_f32_e32 v63, v59, v71
	v_add_f32_e32 v62, 0, v60
	v_fmac_f32_e32 v63, v58, v70
	ds_read_b128 v[58:61], v182 offset:30720
	ds_read_b128 v[66:69], v182 offset:31744
	v_mul_f32_e32 v57, v57, v73
	v_fmac_f32_e32 v57, v56, v72
	v_add_f32_e32 v56, v63, v57
	s_waitcnt lgkmcnt(1)
	v_mul_f32_e32 v55, v55, v59
	s_waitcnt lgkmcnt(0)
	v_mul_f32_e32 v51, v51, v67
	v_fmac_f32_e32 v51, v50, v66
	v_cndmask_b32_e32 v50, v76, v80, vcc
	ds_bpermute_b32 v50, v184, v50
	v_mul_f32_e32 v53, v53, v61
	v_fmac_f32_e32 v55, v54, v58
	v_fmac_f32_e32 v53, v52, v60
	v_mul_f32_e32 v49, v49, v69
	v_add_f32_e32 v56, v62, v56
	v_add_f32_e32 v52, v55, v53
	v_fmac_f32_e32 v49, v48, v68
	v_add_f32_e32 v52, v56, v52
	v_add_f32_e32 v48, v51, v49
	v_cndmask_b32_e32 v49, v80, v76, vcc
	v_add_f32_e32 v48, v52, v48
	s_waitcnt lgkmcnt(0)
	v_add_f32_e32 v49, v49, v50
	v_cndmask_b32_e32 v50, v77, v81, vcc
	ds_bpermute_b32 v50, v184, v50
	v_cndmask_b32_e32 v52, v78, v82, vcc
	v_cndmask_b32_e32 v53, v79, v48, vcc
	ds_bpermute_b32 v52, v184, v52
	ds_bpermute_b32 v53, v184, v53
	v_cndmask_b32_e32 v51, v81, v77, vcc
	s_waitcnt lgkmcnt(2)
	v_add_f32_e32 v50, v51, v50
	v_cndmask_b32_e32 v51, v82, v78, vcc
	v_cndmask_b32_e32 v48, v48, v79, vcc
	s_waitcnt lgkmcnt(1)
	v_add_f32_e32 v51, v51, v52
	s_waitcnt lgkmcnt(0)
	v_add_f32_e32 v48, v48, v53
	v_cndmask_b32_e64 v52, v49, v51, s[4:5]
	v_cndmask_b32_e64 v53, v50, v48, s[4:5]
	ds_bpermute_b32 v52, v185, v52
	ds_bpermute_b32 v53, v185, v53
	v_cndmask_b32_e64 v49, v51, v49, s[4:5]
	v_cndmask_b32_e64 v48, v48, v50, s[4:5]
	v_add_f32_e32 v54, v64, v75
	s_waitcnt lgkmcnt(1)
	v_add_f32_e32 v49, v49, v52
	s_waitcnt lgkmcnt(0)
	v_add_f32_e32 v48, v48, v53
	v_cndmask_b32_e64 v50, v49, v48, s[6:7]
	ds_bpermute_b32 v50, v186, v50
	v_cndmask_b32_e64 v48, v48, v49, s[6:7]
	ds_bpermute_b32 v51, v187, v74
	ds_bpermute_b32 v53, v188, v54
	ds_bpermute_b32 v52, v188, v65
	s_waitcnt lgkmcnt(3)
	v_add_f32_e32 v48, v48, v50
	ds_bpermute_b32 v49, v187, v48
	s_waitcnt lgkmcnt(3)
	v_add_f32_e32 v51, v74, v51
	s_waitcnt lgkmcnt(2)
	v_add_f32_e32 v50, v54, v53
	ds_bpermute_b32 v55, v188, v51
	s_waitcnt lgkmcnt(2)
	v_add_f32_e32 v52, v65, v52
	s_waitcnt lgkmcnt(1)
	v_add_f32_e32 v54, v48, v49
	ds_bpermute_b32 v56, v188, v54
	ds_bpermute_b32 v53, v189, v52
	s_waitcnt lgkmcnt(2)
	v_add_f32_e32 v48, v51, v55
	ds_bpermute_b32 v51, v189, v50
	ds_bpermute_b32 v49, v189, v48
	s_waitcnt lgkmcnt(3)
	v_add_f32_e32 v54, v54, v56
	ds_bpermute_b32 v55, v189, v54
	s_and_saveexec_b64 s[28:29], s[8:9]
	s_cbranch_execz .LBB0_102
	v_mov_b32_e32 v56, v216
	s_waitcnt lgkmcnt(0)
	v_add_f32_e32 v57, v54, v55
	s_ashr_i32 s0, s26, 31
	s_lshr_b32 s0, s0, 19
	s_add_i32 s0, s26, s0
	s_ashr_i32 s1, s0, 13
	s_and_b32 s0, s0, 0xffffe000
	v_lshl_or_b32 v54, s1, 3, v183
	s_sub_i32 s26, s26, s0
	v_ashrrev_i32_e32 v55, 31, v54
	v_lshlrev_b64 v[54:55], 15, v[54:55]
	s_ashr_i32 s27, s26, 31
	v_lshl_add_u64 v[54:55], s[12:13], 0, v[54:55]
	v_lshl_add_u64 v[54:55], s[26:27], 2, v[54:55]
	v_add_f32_e32 v56, v57, v56
	v_mul_f32_e64 v57, |v56|, s41
	v_exp_f32_e32 v70, v57
	v_min_f32_e32 v71, 0, v56
	v_add_f32_e32 v58, 1.0, v70
	v_add_f32_e32 v59, -1.0, v58
	v_frexp_mant_f32_e32 v60, v58
	v_cvt_f64_f32_e32 v[56:57], v58
	v_sub_f32_e32 v61, v59, v58
	v_frexp_exp_i32_f64_e32 v56, v[56:57]
	v_cmp_gt_f32_e64 s[0:1], s42, v60
	v_sub_f32_e32 v59, v70, v59
	v_add_f32_e32 v57, 1.0, v61
	v_subbrev_co_u32_e64 v56, s[0:1], 0, v56, s[0:1]
	v_add_f32_e32 v57, v59, v57
	v_sub_u32_e32 v59, 0, v56
	v_ldexp_f32 v58, v58, v59
	v_add_f32_e32 v60, -1.0, v58
	v_add_f32_e32 v61, 1.0, v58
	v_ldexp_f32 v57, v57, v59
	v_add_f32_e32 v59, 1.0, v60
	v_add_f32_e32 v62, -1.0, v61
	v_sub_f32_e32 v59, v58, v59
	v_sub_f32_e32 v58, v58, v62
	v_add_f32_e32 v62, v57, v59
	v_add_f32_e32 v57, v57, v58
	v_add_f32_e32 v64, v61, v57
	v_rcp_f32_e32 v65, v64
	v_add_f32_e32 v59, v60, v62
	v_sub_f32_e32 v60, v59, v60
	v_sub_f32_e32 v58, v64, v61
	v_mul_f32_e32 v67, v59, v65
	v_sub_f32_e32 v66, v62, v60
	v_mul_f32_e32 v60, v64, v67
	v_sub_f32_e32 v57, v57, v58
	v_fma_f32 v62, v67, v64, -v60
	v_fmac_f32_e32 v62, v67, v57
	v_add_f32_e32 v58, v60, v62
	v_sub_f32_e32 v61, v59, v58
	v_mov_b32_e32 v63, v58
	v_pk_add_f32 v[58:59], v[58:59], v[60:61] neg_lo:[0,1] neg_hi:[0,1]
	v_cvt_f32_i32_e32 v56, v56
	v_pk_add_f32 v[58:59], v[58:59], v[62:63] neg_lo:[0,1] neg_hi:[0,1]
	v_cmp_neq_f32_e64 s[0:1], s44, v70
	v_add_f32_e32 v59, v66, v59
	v_add_f32_e32 v58, v58, v59
	v_add_f32_e32 v59, v61, v58
	v_mul_f32_e32 v63, v65, v59
	v_mul_f32_e32 v60, v64, v63
	v_sub_f32_e32 v61, v61, v59
	v_add_f32_e32 v68, v67, v63
	v_fma_f32 v62, v63, v64, -v60
	v_add_f32_e32 v66, v58, v61
	v_sub_f32_e32 v58, v68, v67
	v_fmac_f32_e32 v62, v63, v57
	v_sub_f32_e32 v57, v63, v58
	v_add_f32_e32 v58, v60, v62
	v_sub_f32_e32 v61, v59, v58
	v_mov_b32_e32 v63, v58
	v_pk_add_f32 v[58:59], v[58:59], v[60:61] neg_lo:[0,1] neg_hi:[0,1]
	s_nop 0
	v_pk_add_f32 v[58:59], v[58:59], v[62:63] neg_lo:[0,1] neg_hi:[0,1]
	s_nop 0
	v_add_f32_e32 v59, v66, v59
	v_add_f32_e32 v58, v58, v59
	v_add_f32_e32 v58, v61, v58
	v_mul_f32_e32 v58, v65, v58
	v_add_f32_e32 v57, v57, v58
	v_add_f32_e32 v58, v68, v57
	v_mul_f32_e32 v60, v58, v58
	v_sub_f32_e32 v61, v58, v68
	v_fmamk_f32 v62, v60, 0x3e9b6dac, v195
	v_sub_f32_e32 v61, v57, v61
	v_mul_f32_e32 v57, v58, v60
	v_fmaak_f32 v147, v60, v62, 0x3f2aaada
	v_ldexp_f32 v63, v61, 1
	v_pk_mul_f32 v[60:61], v[56:57], v[146:147]
	v_ldexp_f32 v59, v58, 1
	v_fma_f32 v58, v56, s43, -v60
	v_fmac_f32_e32 v58, 0xb102e308, v56
	v_pk_add_f32 v[56:57], v[60:61], v[58:59]
	v_mov_b32_e32 v62, v60
	v_sub_f32_e32 v66, v57, v59
	v_pk_add_f32 v[64:65], v[56:57], v[60:61] neg_lo:[0,1] neg_hi:[0,1]
	v_sub_f32_e32 v60, v61, v66
	v_add_f32_e32 v63, v63, v60
	v_pk_add_f32 v[60:61], v[56:57], v[62:63]
	v_mov_b32_e32 v59, v56
	v_mov_b32_e32 v65, v61
	v_pk_add_f32 v[68:69], v[58:59], v[64:65] neg_lo:[0,1] neg_hi:[0,1]
	v_pk_add_f32 v[58:59], v[58:59], v[64:65]
	v_mov_b32_e32 v67, v56
	v_pk_add_f32 v[64:65], v[58:59], v[56:57] op_sel:[1,0] op_sel_hi:[0,1] neg_lo:[0,1] neg_hi:[0,1]
	v_mov_b32_e32 v66, v63
	v_mov_b32_e32 v62, v61
	v_mov_b32_e32 v63, v59
	v_pk_mov_b32 v[56:57], v[56:57], v[64:65] op_sel:[1,0]
	v_pk_add_f32 v[60:61], v[60:61], v[64:65] op_sel_hi:[1,0] neg_lo:[0,1] neg_hi:[0,1]
	v_pk_add_f32 v[56:57], v[62:63], v[56:57] neg_lo:[0,1] neg_hi:[0,1]
	v_mov_b32_e32 v60, v68
	v_pk_add_f32 v[56:57], v[66:67], v[56:57] neg_lo:[0,1] neg_hi:[0,1]
	v_mov_b32_e32 v69, v59
	v_pk_add_f32 v[60:61], v[60:61], v[56:57]
	s_nop 0
	v_pk_add_f32 v[62:63], v[60:61], v[60:61] op_sel:[0,1] op_sel_hi:[1,0]
	s_nop 0
	v_pk_add_f32 v[58:59], v[58:59], v[62:63] op_sel:[1,0] op_sel_hi:[0,1]
	v_mov_b32_e32 v61, v58
	v_mov_b32_e32 v57, v62
	v_pk_add_f32 v[62:63], v[60:61], v[68:69] neg_lo:[0,1] neg_hi:[0,1]
	s_nop 0
	v_sub_f32_e32 v59, v60, v62
	v_pk_add_f32 v[56:57], v[56:57], v[62:63] neg_lo:[0,1] neg_hi:[0,1]
	v_sub_f32_e32 v59, v68, v59
	v_add_f32_e32 v56, v56, v59
	v_add_f32_e32 v56, v56, v57
	v_add_f32_e32 v56, v58, v56
	v_cndmask_b32_e64 v56, v196, v56, s[0:1]
	v_cmp_ngt_f32_e64 s[0:1], -1.0, v70
	s_nop 1
	v_cndmask_b32_e64 v56, v197, v56, s[0:1]
	v_cmp_neq_f32_e64 s[0:1], -1.0, v70
	s_nop 1
	v_cndmask_b32_e64 v56, v198, v56, s[0:1]
	v_cmp_lt_f32_e64 s[0:1], |v70|, s45
	s_nop 1
	v_cndmask_b32_e64 v56, v56, v70, s[0:1]
	v_sub_f32_e32 v56, v71, v56
	global_store_dword v[54:55], v56, off
.LBB0_102:
	s_or_b64 exec, exec, s[28:29]
	s_waitcnt lgkmcnt(3)
	v_add_f32_e32 v52, v52, v53
	v_fmamk_f32 v52, v52, 0x3a800000, v194
	v_rsq_f32_e32 v52, v52
	s_lshl_b64 s[0:1], s[24:25], 11
	s_waitcnt lgkmcnt(0)
	v_lshl_add_u64 v[54:55], v[130:131], 0, s[0:1]
	v_pk_mul_f32 v[46:47], v[46:47], v[52:53] op_sel_hi:[1,0]
	v_pk_mul_f32 v[56:57], v[44:45], v[52:53] op_sel_hi:[1,0]
	v_pk_fma_f32 v[44:45], v[152:153], v[46:47], v[148:149]
	v_pk_fma_f32 v[46:47], v[154:155], v[56:57], v[150:151]
	v_cvt_pk_bf16_f32 v57, v44, v45
	v_pk_mul_f32 v[42:43], v[42:43], v[52:53] op_sel_hi:[1,0]
	v_cvt_pk_bf16_f32 v56, v46, v47
	global_store_dwordx2 v[54:55], v[56:57], off
	v_pk_mul_f32 v[56:57], v[40:41], v[52:53] op_sel_hi:[1,0]
	v_pk_fma_f32 v[40:41], v[160:161], v[42:43], v[156:157]
	v_pk_fma_f32 v[42:43], v[162:163], v[56:57], v[158:159]
	v_cvt_pk_bf16_f32 v57, v40, v41
	v_pk_mul_f32 v[38:39], v[38:39], v[52:53] op_sel_hi:[1,0]
	v_cvt_pk_bf16_f32 v56, v42, v43
	global_store_dwordx2 v[54:55], v[56:57], off offset:512
	v_pk_mul_f32 v[56:57], v[36:37], v[52:53] op_sel_hi:[1,0]
	v_pk_mul_f32 v[34:35], v[34:35], v[52:53] op_sel_hi:[1,0]
	v_pk_mul_f32 v[52:53], v[32:33], v[52:53] op_sel_hi:[1,0]
	v_pk_fma_f32 v[36:37], v[168:169], v[38:39], v[164:165]
	v_pk_fma_f32 v[38:39], v[170:171], v[56:57], v[166:167]
	v_cvt_pk_bf16_f32 v57, v36, v37
	v_pk_fma_f32 v[32:33], v[176:177], v[34:35], v[172:173]
	v_cvt_pk_bf16_f32 v56, v38, v39
	global_store_dwordx2 v[54:55], v[56:57], off offset:1024
	v_pk_fma_f32 v[34:35], v[178:179], v[52:53], v[174:175]
	v_cvt_pk_bf16_f32 v53, v32, v33
	s_nop 0
	v_cvt_pk_bf16_f32 v52, v34, v35
	global_store_dwordx2 v[54:55], v[52:53], off offset:1536
	ds_read_b128 v[52:55], v182
	ds_read_b128 v[56:59], v182 offset:1024
	s_waitcnt lgkmcnt(1)
	v_mul_f32_e32 v53, v47, v53
	v_fmac_f32_e32 v53, v46, v52
	v_mul_f32_e32 v52, v45, v55
	v_fmac_f32_e32 v52, v44, v54
	s_waitcnt lgkmcnt(0)
	v_mul_f32_e32 v57, v43, v57
	v_add_f32_e32 v52, v53, v52
	v_fmac_f32_e32 v57, v42, v56
	v_mul_f32_e32 v56, v41, v59
	v_add_f32_e32 v60, 0, v52
	ds_read_b128 v[52:55], v182 offset:2048
	v_fmac_f32_e32 v56, v40, v58
	v_add_f32_e32 v56, v57, v56
	v_add_f32_e32 v60, v60, v56
	ds_read_b128 v[56:59], v182 offset:3072
	s_waitcnt lgkmcnt(1)
	v_mul_f32_e32 v53, v39, v53
	v_fmac_f32_e32 v53, v38, v52
	v_mul_f32_e32 v52, v37, v55
	v_fmac_f32_e32 v52, v36, v54
	s_waitcnt lgkmcnt(0)
	v_mul_f32_e32 v57, v35, v57
	v_add_f32_e32 v52, v53, v52
	v_fmac_f32_e32 v57, v34, v56
	v_mul_f32_e32 v56, v33, v59
	v_add_f32_e32 v60, v60, v52
	ds_read_b128 v[52:55], v182 offset:4096
	v_fmac_f32_e32 v56, v32, v58
	v_add_f32_e32 v56, v57, v56
	v_add_f32_e32 v60, v60, v56
	ds_read_b128 v[56:59], v182 offset:5120
	s_waitcnt lgkmcnt(1)
	v_mul_f32_e32 v53, v47, v53
	v_fmac_f32_e32 v53, v46, v52
	v_mul_f32_e32 v52, v45, v55
	v_fmac_f32_e32 v52, v44, v54
	s_waitcnt lgkmcnt(0)
	v_mul_f32_e32 v57, v43, v57
	v_add_f32_e32 v52, v53, v52
	v_fmac_f32_e32 v57, v42, v56
	v_mul_f32_e32 v56, v41, v59
	v_add_f32_e32 v61, 0, v52
	ds_read_b128 v[52:55], v182 offset:6144
	v_fmac_f32_e32 v56, v40, v58
	v_add_f32_e32 v56, v57, v56
	v_add_f32_e32 v61, v61, v56
	ds_read_b128 v[56:59], v182 offset:7168
	s_waitcnt lgkmcnt(1)
	v_mul_f32_e32 v53, v39, v53
	v_fmac_f32_e32 v53, v38, v52
	v_mul_f32_e32 v52, v37, v55
	v_fmac_f32_e32 v52, v36, v54
	s_waitcnt lgkmcnt(0)
	v_mul_f32_e32 v57, v35, v57
	v_add_f32_e32 v52, v53, v52
	v_fmac_f32_e32 v57, v34, v56
	v_mul_f32_e32 v56, v33, v59
	v_add_f32_e32 v61, v61, v52
	ds_read_b128 v[52:55], v182 offset:8192
	v_fmac_f32_e32 v56, v32, v58
	v_add_f32_e32 v56, v57, v56
	v_add_f32_e32 v61, v61, v56
	ds_read_b128 v[56:59], v182 offset:9216
	s_waitcnt lgkmcnt(1)
	v_mul_f32_e32 v53, v47, v53
	v_fmac_f32_e32 v53, v46, v52
	v_mul_f32_e32 v52, v45, v55
	v_fmac_f32_e32 v52, v44, v54
	s_waitcnt lgkmcnt(0)
	v_mul_f32_e32 v57, v43, v57
	v_add_f32_e32 v52, v53, v52
	v_fmac_f32_e32 v57, v42, v56
	v_mul_f32_e32 v56, v41, v59
	v_add_f32_e32 v62, 0, v52
	ds_read_b128 v[52:55], v182 offset:10240
	v_fmac_f32_e32 v56, v40, v58
	v_add_f32_e32 v56, v57, v56
	v_add_f32_e32 v62, v62, v56
	ds_read_b128 v[56:59], v182 offset:11264
	s_waitcnt lgkmcnt(1)
	v_mul_f32_e32 v53, v39, v53
	v_fmac_f32_e32 v53, v38, v52
	v_mul_f32_e32 v52, v37, v55
	v_fmac_f32_e32 v52, v36, v54
	s_waitcnt lgkmcnt(0)
	v_mul_f32_e32 v57, v35, v57
	v_add_f32_e32 v52, v53, v52
	v_fmac_f32_e32 v57, v34, v56
	v_mul_f32_e32 v56, v33, v59
	v_add_f32_e32 v62, v62, v52
	ds_read_b128 v[52:55], v182 offset:12288
	v_fmac_f32_e32 v56, v32, v58
	v_add_f32_e32 v56, v57, v56
	v_add_f32_e32 v62, v62, v56
	ds_read_b128 v[56:59], v182 offset:13312
	s_waitcnt lgkmcnt(1)
	v_mul_f32_e32 v53, v47, v53
	v_fmac_f32_e32 v53, v46, v52
	v_mul_f32_e32 v52, v45, v55
	v_fmac_f32_e32 v52, v44, v54
	s_waitcnt lgkmcnt(0)
	v_mul_f32_e32 v57, v43, v57
	v_add_f32_e32 v52, v53, v52
	v_fmac_f32_e32 v57, v42, v56
	v_mul_f32_e32 v56, v41, v59
	v_add_f32_e32 v63, 0, v52
	ds_read_b128 v[52:55], v182 offset:14336
	v_fmac_f32_e32 v56, v40, v58
	v_add_f32_e32 v56, v57, v56
	v_add_f32_e32 v63, v63, v56
	ds_read_b128 v[56:59], v182 offset:15360
	s_waitcnt lgkmcnt(1)
	v_mul_f32_e32 v53, v39, v53
	v_fmac_f32_e32 v53, v38, v52
	v_mul_f32_e32 v52, v37, v55
	v_fmac_f32_e32 v52, v36, v54
	s_waitcnt lgkmcnt(0)
	v_mul_f32_e32 v57, v35, v57
	v_add_f32_e32 v52, v53, v52
	v_fmac_f32_e32 v57, v34, v56
	v_mul_f32_e32 v56, v33, v59
	v_add_f32_e32 v63, v63, v52
	ds_read_b128 v[52:55], v182 offset:16384
	v_fmac_f32_e32 v56, v32, v58
	v_add_f32_e32 v56, v57, v56
	v_add_f32_e32 v63, v63, v56
	ds_read_b128 v[56:59], v182 offset:17408
	s_waitcnt lgkmcnt(1)
	v_mul_f32_e32 v53, v47, v53
	v_fmac_f32_e32 v53, v46, v52
	v_mul_f32_e32 v52, v45, v55
	v_fmac_f32_e32 v52, v44, v54
	s_waitcnt lgkmcnt(0)
	v_mul_f32_e32 v57, v43, v57
	v_add_f32_e32 v52, v53, v52
	v_fmac_f32_e32 v57, v42, v56
	v_mul_f32_e32 v56, v41, v59
	v_add_f32_e32 v64, 0, v52
	ds_read_b128 v[52:55], v182 offset:18432
	v_fmac_f32_e32 v56, v40, v58
	v_add_f32_e32 v56, v57, v56
	v_add_f32_e32 v64, v64, v56
	ds_read_b128 v[56:59], v182 offset:19456
	s_waitcnt lgkmcnt(1)
	v_mul_f32_e32 v53, v39, v53
	v_fmac_f32_e32 v53, v38, v52
	v_mul_f32_e32 v52, v37, v55
	v_fmac_f32_e32 v52, v36, v54
	s_waitcnt lgkmcnt(0)
	v_mul_f32_e32 v57, v35, v57
	v_add_f32_e32 v52, v53, v52
	v_fmac_f32_e32 v57, v34, v56
	v_mul_f32_e32 v56, v33, v59
	v_add_f32_e32 v64, v64, v52
	ds_read_b128 v[52:55], v182 offset:20480
	v_fmac_f32_e32 v56, v32, v58
	v_add_f32_e32 v56, v57, v56
	v_add_f32_e32 v64, v64, v56
	ds_read_b128 v[56:59], v182 offset:21504
	s_waitcnt lgkmcnt(1)
	v_mul_f32_e32 v53, v47, v53
	v_fmac_f32_e32 v53, v46, v52
	v_mul_f32_e32 v52, v45, v55
	v_fmac_f32_e32 v52, v44, v54
	s_waitcnt lgkmcnt(0)
	v_mul_f32_e32 v57, v43, v57
	v_add_f32_e32 v52, v53, v52
	v_fmac_f32_e32 v57, v42, v56
	v_mul_f32_e32 v56, v41, v59
	v_add_f32_e32 v65, 0, v52
	ds_read_b128 v[52:55], v182 offset:22528
	v_fmac_f32_e32 v56, v40, v58
	v_add_f32_e32 v56, v57, v56
	v_add_f32_e32 v65, v65, v56
	ds_read_b128 v[56:59], v182 offset:23552
	s_waitcnt lgkmcnt(1)
	v_mul_f32_e32 v53, v39, v53
	v_fmac_f32_e32 v53, v38, v52
	v_mul_f32_e32 v52, v37, v55
	v_fmac_f32_e32 v52, v36, v54
	s_waitcnt lgkmcnt(0)
	v_mul_f32_e32 v57, v35, v57
	v_add_f32_e32 v52, v53, v52
	v_fmac_f32_e32 v57, v34, v56
	v_mul_f32_e32 v56, v33, v59
	v_add_f32_e32 v65, v65, v52
	ds_read_b128 v[52:55], v182 offset:24576
	v_fmac_f32_e32 v56, v32, v58
	v_add_f32_e32 v56, v57, v56
	v_add_f32_e32 v65, v65, v56
	ds_read_b128 v[56:59], v182 offset:25600
	s_waitcnt lgkmcnt(1)
	v_mul_f32_e32 v53, v47, v53
	v_fmac_f32_e32 v53, v46, v52
	v_mul_f32_e32 v52, v45, v55
	v_fmac_f32_e32 v52, v44, v54
	s_waitcnt lgkmcnt(0)
	v_mul_f32_e32 v57, v43, v57
	v_add_f32_e32 v52, v53, v52
	v_fmac_f32_e32 v57, v42, v56
	v_mul_f32_e32 v56, v41, v59
	v_add_f32_e32 v66, 0, v52
	ds_read_b128 v[52:55], v182 offset:26624
	v_fmac_f32_e32 v56, v40, v58
	v_add_f32_e32 v56, v57, v56
	v_add_f32_e32 v66, v66, v56
	ds_read_b128 v[56:59], v182 offset:27648
	s_waitcnt lgkmcnt(1)
	v_mul_f32_e32 v53, v39, v53
	v_fmac_f32_e32 v53, v38, v52
	v_mul_f32_e32 v52, v37, v55
	v_fmac_f32_e32 v52, v36, v54
	s_waitcnt lgkmcnt(0)
	v_mul_f32_e32 v57, v35, v57
	v_add_f32_e32 v52, v53, v52
	v_fmac_f32_e32 v57, v34, v56
	v_mul_f32_e32 v56, v33, v59
	v_add_f32_e32 v66, v66, v52
	ds_read_b128 v[52:55], v182 offset:28672
	v_fmac_f32_e32 v56, v32, v58
	v_add_f32_e32 v56, v57, v56
	v_add_f32_e32 v66, v66, v56
	ds_read_b128 v[56:59], v182 offset:29696
	s_waitcnt lgkmcnt(1)
	v_mul_f32_e32 v47, v47, v53
	v_mul_f32_e32 v45, v45, v55
	v_fmac_f32_e32 v47, v46, v52
	v_fmac_f32_e32 v45, v44, v54
	v_add_f32_e32 v44, v47, v45
	s_waitcnt lgkmcnt(0)
	v_mul_f32_e32 v47, v43, v57
	v_add_f32_e32 v46, 0, v44
	v_fmac_f32_e32 v47, v42, v56
	ds_read_b128 v[42:45], v182 offset:30720
	ds_read_b128 v[52:55], v182 offset:31744
	v_mul_f32_e32 v41, v41, v59
	v_fmac_f32_e32 v41, v40, v58
	v_add_f32_e32 v40, v47, v41
	s_waitcnt lgkmcnt(1)
	v_mul_f32_e32 v39, v39, v43
	s_waitcnt lgkmcnt(0)
	v_mul_f32_e32 v35, v35, v53
	v_fmac_f32_e32 v35, v34, v52
	v_cndmask_b32_e32 v34, v60, v64, vcc
	ds_bpermute_b32 v34, v184, v34
	v_mul_f32_e32 v37, v37, v45
	v_fmac_f32_e32 v39, v38, v42
	v_fmac_f32_e32 v37, v36, v44
	v_mul_f32_e32 v33, v33, v55
	v_add_f32_e32 v40, v46, v40
	v_add_f32_e32 v36, v39, v37
	v_fmac_f32_e32 v33, v32, v54
	v_add_f32_e32 v36, v40, v36
	v_add_f32_e32 v32, v35, v33
	v_cndmask_b32_e32 v33, v64, v60, vcc
	v_add_f32_e32 v32, v36, v32
	s_waitcnt lgkmcnt(0)
	v_add_f32_e32 v33, v33, v34
	v_cndmask_b32_e32 v34, v61, v65, vcc
	ds_bpermute_b32 v34, v184, v34
	v_cndmask_b32_e32 v36, v62, v66, vcc
	v_cndmask_b32_e32 v37, v63, v32, vcc
	ds_bpermute_b32 v36, v184, v36
	ds_bpermute_b32 v37, v184, v37
	v_cndmask_b32_e32 v35, v65, v61, vcc
	s_waitcnt lgkmcnt(2)
	v_add_f32_e32 v34, v35, v34
	v_cndmask_b32_e32 v35, v66, v62, vcc
	v_cndmask_b32_e32 v32, v32, v63, vcc
	s_waitcnt lgkmcnt(1)
	v_add_f32_e32 v35, v35, v36
	s_waitcnt lgkmcnt(0)
	v_add_f32_e32 v32, v32, v37
	v_cndmask_b32_e64 v36, v33, v35, s[4:5]
	v_cndmask_b32_e64 v37, v34, v32, s[4:5]
	ds_bpermute_b32 v36, v185, v36
	ds_bpermute_b32 v37, v185, v37
	v_cndmask_b32_e64 v33, v35, v33, s[4:5]
	v_cndmask_b32_e64 v32, v32, v34, s[4:5]
	s_waitcnt lgkmcnt(1)
	v_add_f32_e32 v33, v33, v36
	s_waitcnt lgkmcnt(0)
	v_add_f32_e32 v32, v32, v37
	v_cndmask_b32_e64 v34, v33, v32, s[6:7]
	ds_bpermute_b32 v34, v186, v34
	v_cndmask_b32_e64 v32, v32, v33, s[6:7]
	s_waitcnt lgkmcnt(0)
	v_add_f32_e32 v32, v32, v34
	ds_bpermute_b32 v33, v187, v32
	s_waitcnt lgkmcnt(0)
	v_add_f32_e32 v32, v32, v33
	ds_bpermute_b32 v33, v188, v32
	s_waitcnt lgkmcnt(0)
	v_add_f32_e32 v32, v32, v33
	ds_bpermute_b32 v33, v189, v32
	s_and_saveexec_b64 s[26:27], s[8:9]
	s_cbranch_execz .LBB0_104
	v_mov_b32_e32 v34, v216
	s_waitcnt lgkmcnt(0)
	v_add_f32_e32 v35, v32, v33
	s_ashr_i32 s0, s24, 31
	s_lshr_b32 s0, s0, 19
	s_add_i32 s0, s24, s0
	s_ashr_i32 s1, s0, 13
	s_and_b32 s0, s0, 0xffffe000
	v_lshl_or_b32 v32, s1, 3, v183
	s_sub_i32 s24, s24, s0
	v_ashrrev_i32_e32 v33, 31, v32
	v_lshlrev_b64 v[32:33], 15, v[32:33]
	s_ashr_i32 s25, s24, 31
	v_lshl_add_u64 v[32:33], s[12:13], 0, v[32:33]
	v_lshl_add_u64 v[32:33], s[24:25], 2, v[32:33]
	v_add_f32_e32 v34, v35, v34
	v_mul_f32_e64 v35, |v34|, s41
	v_exp_f32_e32 v52, v35
	v_min_f32_e32 v53, 0, v34
	v_add_f32_e32 v36, 1.0, v52
	v_add_f32_e32 v37, -1.0, v36
	v_frexp_mant_f32_e32 v38, v36
	v_cvt_f64_f32_e32 v[34:35], v36
	v_sub_f32_e32 v39, v37, v36
	v_frexp_exp_i32_f64_e32 v34, v[34:35]
	v_cmp_gt_f32_e64 s[0:1], s42, v38
	v_sub_f32_e32 v37, v52, v37
	v_add_f32_e32 v35, 1.0, v39
	v_subbrev_co_u32_e64 v34, s[0:1], 0, v34, s[0:1]
	v_add_f32_e32 v35, v37, v35
	v_sub_u32_e32 v37, 0, v34
	v_ldexp_f32 v36, v36, v37
	v_add_f32_e32 v38, -1.0, v36
	v_add_f32_e32 v39, 1.0, v36
	v_ldexp_f32 v35, v35, v37
	v_add_f32_e32 v37, 1.0, v38
	v_add_f32_e32 v40, -1.0, v39
	v_sub_f32_e32 v37, v36, v37
	v_sub_f32_e32 v36, v36, v40
	v_add_f32_e32 v40, v35, v37
	v_add_f32_e32 v35, v35, v36
	v_add_f32_e32 v42, v39, v35
	v_rcp_f32_e32 v43, v42
	v_add_f32_e32 v37, v38, v40
	v_sub_f32_e32 v38, v37, v38
	v_sub_f32_e32 v36, v42, v39
	v_mul_f32_e32 v45, v37, v43
	v_sub_f32_e32 v44, v40, v38
	v_mul_f32_e32 v38, v42, v45
	v_sub_f32_e32 v35, v35, v36
	v_fma_f32 v40, v45, v42, -v38
	v_fmac_f32_e32 v40, v45, v35
	v_add_f32_e32 v36, v38, v40
	v_sub_f32_e32 v39, v37, v36
	v_mov_b32_e32 v41, v36
	v_pk_add_f32 v[36:37], v[36:37], v[38:39] neg_lo:[0,1] neg_hi:[0,1]
	v_cvt_f32_i32_e32 v34, v34
	v_pk_add_f32 v[36:37], v[36:37], v[40:41] neg_lo:[0,1] neg_hi:[0,1]
	v_cmp_neq_f32_e64 s[0:1], s44, v52
	v_add_f32_e32 v37, v44, v37
	v_add_f32_e32 v36, v36, v37
	v_add_f32_e32 v37, v39, v36
	v_mul_f32_e32 v41, v43, v37
	v_mul_f32_e32 v38, v42, v41
	v_sub_f32_e32 v39, v39, v37
	v_add_f32_e32 v46, v45, v41
	v_fma_f32 v40, v41, v42, -v38
	v_add_f32_e32 v44, v36, v39
	v_sub_f32_e32 v36, v46, v45
	v_fmac_f32_e32 v40, v41, v35
	v_sub_f32_e32 v35, v41, v36
	v_add_f32_e32 v36, v38, v40
	v_sub_f32_e32 v39, v37, v36
	v_mov_b32_e32 v41, v36
	v_pk_add_f32 v[36:37], v[36:37], v[38:39] neg_lo:[0,1] neg_hi:[0,1]
	s_nop 0
	v_pk_add_f32 v[36:37], v[36:37], v[40:41] neg_lo:[0,1] neg_hi:[0,1]
	s_nop 0
	v_add_f32_e32 v37, v44, v37
	v_add_f32_e32 v36, v36, v37
	v_add_f32_e32 v36, v39, v36
	v_mul_f32_e32 v36, v43, v36
	v_add_f32_e32 v35, v35, v36
	v_add_f32_e32 v36, v46, v35
	v_mul_f32_e32 v38, v36, v36
	v_sub_f32_e32 v39, v36, v46
	v_fmamk_f32 v40, v38, 0x3e9b6dac, v195
	v_sub_f32_e32 v39, v35, v39
	v_mul_f32_e32 v35, v36, v38
	v_fmaak_f32 v147, v38, v40, 0x3f2aaada
	v_ldexp_f32 v41, v39, 1
	v_pk_mul_f32 v[38:39], v[34:35], v[146:147]
	v_ldexp_f32 v37, v36, 1
	v_fma_f32 v36, v34, s43, -v38
	v_fmac_f32_e32 v36, 0xb102e308, v34
	v_pk_add_f32 v[34:35], v[38:39], v[36:37]
	v_mov_b32_e32 v40, v38
	v_sub_f32_e32 v44, v35, v37
	v_pk_add_f32 v[42:43], v[34:35], v[38:39] neg_lo:[0,1] neg_hi:[0,1]
	v_sub_f32_e32 v38, v39, v44
	v_add_f32_e32 v41, v41, v38
	v_pk_add_f32 v[38:39], v[34:35], v[40:41]
	v_mov_b32_e32 v37, v34
	v_mov_b32_e32 v43, v39
	v_pk_add_f32 v[46:47], v[36:37], v[42:43] neg_lo:[0,1] neg_hi:[0,1]
	v_pk_add_f32 v[36:37], v[36:37], v[42:43]
	v_mov_b32_e32 v45, v34
	v_pk_add_f32 v[42:43], v[36:37], v[34:35] op_sel:[1,0] op_sel_hi:[0,1] neg_lo:[0,1] neg_hi:[0,1]
	v_mov_b32_e32 v44, v41
	v_mov_b32_e32 v40, v39
	v_mov_b32_e32 v41, v37
	v_pk_mov_b32 v[34:35], v[34:35], v[42:43] op_sel:[1,0]
	v_pk_add_f32 v[38:39], v[38:39], v[42:43] op_sel_hi:[1,0] neg_lo:[0,1] neg_hi:[0,1]
	v_pk_add_f32 v[34:35], v[40:41], v[34:35] neg_lo:[0,1] neg_hi:[0,1]
	v_mov_b32_e32 v38, v46
	v_pk_add_f32 v[34:35], v[44:45], v[34:35] neg_lo:[0,1] neg_hi:[0,1]
	v_mov_b32_e32 v47, v37
	v_pk_add_f32 v[38:39], v[38:39], v[34:35]
	s_nop 0
	v_pk_add_f32 v[40:41], v[38:39], v[38:39] op_sel:[0,1] op_sel_hi:[1,0]
	s_nop 0
	v_pk_add_f32 v[36:37], v[36:37], v[40:41] op_sel:[1,0] op_sel_hi:[0,1]
	v_mov_b32_e32 v39, v36
	v_mov_b32_e32 v35, v40
	v_pk_add_f32 v[40:41], v[38:39], v[46:47] neg_lo:[0,1] neg_hi:[0,1]
	s_nop 0
	v_sub_f32_e32 v37, v38, v40
	v_pk_add_f32 v[34:35], v[34:35], v[40:41] neg_lo:[0,1] neg_hi:[0,1]
	v_sub_f32_e32 v37, v46, v37
	v_add_f32_e32 v34, v34, v37
	v_add_f32_e32 v34, v34, v35
	v_add_f32_e32 v34, v36, v34
	v_cndmask_b32_e64 v34, v196, v34, s[0:1]
	v_cmp_ngt_f32_e64 s[0:1], -1.0, v52
	s_nop 1
	v_cndmask_b32_e64 v34, v197, v34, s[0:1]
	v_cmp_neq_f32_e64 s[0:1], -1.0, v52
	s_nop 1
	v_cndmask_b32_e64 v34, v198, v34, s[0:1]
	v_cmp_lt_f32_e64 s[0:1], |v52|, s45
	s_nop 1
	v_cndmask_b32_e64 v34, v34, v52, s[0:1]
	v_sub_f32_e32 v34, v53, v34
	global_store_dword v[32:33], v34, off
.LBB0_104:
	s_or_b64 exec, exec, s[26:27]
	v_add_f32_e32 v32, v50, v51
	v_fmamk_f32 v32, v32, 0x3a800000, v194
	v_rsq_f32_e32 v32, v32
	s_lshl_b64 s[0:1], s[22:23], 11
	v_lshl_add_u64 v[34:35], v[130:131], 0, s[0:1]
	s_waitcnt lgkmcnt(0)
	v_pk_mul_f32 v[30:31], v[30:31], v[32:33] op_sel_hi:[1,0]
	v_pk_mul_f32 v[36:37], v[28:29], v[32:33] op_sel_hi:[1,0]
	v_pk_fma_f32 v[28:29], v[152:153], v[30:31], v[148:149]
	v_pk_fma_f32 v[30:31], v[154:155], v[36:37], v[150:151]
	v_cvt_pk_bf16_f32 v37, v28, v29
	v_pk_mul_f32 v[26:27], v[26:27], v[32:33] op_sel_hi:[1,0]
	v_cvt_pk_bf16_f32 v36, v30, v31
	global_store_dwordx2 v[34:35], v[36:37], off
	v_pk_mul_f32 v[36:37], v[24:25], v[32:33] op_sel_hi:[1,0]
	v_pk_fma_f32 v[24:25], v[160:161], v[26:27], v[156:157]
	v_pk_fma_f32 v[26:27], v[162:163], v[36:37], v[158:159]
	v_cvt_pk_bf16_f32 v37, v24, v25
	v_pk_mul_f32 v[22:23], v[22:23], v[32:33] op_sel_hi:[1,0]
	v_cvt_pk_bf16_f32 v36, v26, v27
	global_store_dwordx2 v[34:35], v[36:37], off offset:512
	v_pk_mul_f32 v[36:37], v[20:21], v[32:33] op_sel_hi:[1,0]
	v_pk_mul_f32 v[18:19], v[18:19], v[32:33] op_sel_hi:[1,0]
	v_pk_mul_f32 v[32:33], v[16:17], v[32:33] op_sel_hi:[1,0]
	v_pk_fma_f32 v[20:21], v[168:169], v[22:23], v[164:165]
	v_pk_fma_f32 v[22:23], v[170:171], v[36:37], v[166:167]
	v_cvt_pk_bf16_f32 v37, v20, v21
	v_pk_fma_f32 v[16:17], v[176:177], v[18:19], v[172:173]
	v_cvt_pk_bf16_f32 v36, v22, v23
	global_store_dwordx2 v[34:35], v[36:37], off offset:1024
	v_pk_fma_f32 v[18:19], v[178:179], v[32:33], v[174:175]
	v_cvt_pk_bf16_f32 v33, v16, v17
	s_nop 0
	v_cvt_pk_bf16_f32 v32, v18, v19
	global_store_dwordx2 v[34:35], v[32:33], off offset:1536
	ds_read_b128 v[32:35], v182
	ds_read_b128 v[36:39], v182 offset:1024
	s_waitcnt lgkmcnt(1)
	v_mul_f32_e32 v33, v31, v33
	v_fmac_f32_e32 v33, v30, v32
	v_mul_f32_e32 v32, v29, v35
	v_fmac_f32_e32 v32, v28, v34
	s_waitcnt lgkmcnt(0)
	v_mul_f32_e32 v37, v27, v37
	v_add_f32_e32 v32, v33, v32
	v_fmac_f32_e32 v37, v26, v36
	v_mul_f32_e32 v36, v25, v39
	v_add_f32_e32 v40, 0, v32
	ds_read_b128 v[32:35], v182 offset:2048
	v_fmac_f32_e32 v36, v24, v38
	v_add_f32_e32 v36, v37, v36
	v_add_f32_e32 v40, v40, v36
	ds_read_b128 v[36:39], v182 offset:3072
	s_waitcnt lgkmcnt(1)
	v_mul_f32_e32 v33, v23, v33
	v_fmac_f32_e32 v33, v22, v32
	v_mul_f32_e32 v32, v21, v35
	v_fmac_f32_e32 v32, v20, v34
	s_waitcnt lgkmcnt(0)
	v_mul_f32_e32 v37, v19, v37
	v_add_f32_e32 v32, v33, v32
	v_fmac_f32_e32 v37, v18, v36
	v_mul_f32_e32 v36, v17, v39
	v_add_f32_e32 v40, v40, v32
	ds_read_b128 v[32:35], v182 offset:4096
	v_fmac_f32_e32 v36, v16, v38
	v_add_f32_e32 v36, v37, v36
	v_add_f32_e32 v40, v40, v36
	ds_read_b128 v[36:39], v182 offset:5120
	s_waitcnt lgkmcnt(1)
	v_mul_f32_e32 v33, v31, v33
	v_fmac_f32_e32 v33, v30, v32
	v_mul_f32_e32 v32, v29, v35
	v_fmac_f32_e32 v32, v28, v34
	s_waitcnt lgkmcnt(0)
	v_mul_f32_e32 v37, v27, v37
	v_add_f32_e32 v32, v33, v32
	v_fmac_f32_e32 v37, v26, v36
	v_mul_f32_e32 v36, v25, v39
	v_add_f32_e32 v41, 0, v32
	ds_read_b128 v[32:35], v182 offset:6144
	v_fmac_f32_e32 v36, v24, v38
	v_add_f32_e32 v36, v37, v36
	v_add_f32_e32 v41, v41, v36
	ds_read_b128 v[36:39], v182 offset:7168
	s_waitcnt lgkmcnt(1)
	v_mul_f32_e32 v33, v23, v33
	v_fmac_f32_e32 v33, v22, v32
	v_mul_f32_e32 v32, v21, v35
	v_fmac_f32_e32 v32, v20, v34
	s_waitcnt lgkmcnt(0)
	v_mul_f32_e32 v37, v19, v37
	v_add_f32_e32 v32, v33, v32
	v_fmac_f32_e32 v37, v18, v36
	v_mul_f32_e32 v36, v17, v39
	v_add_f32_e32 v41, v41, v32
	ds_read_b128 v[32:35], v182 offset:8192
	v_fmac_f32_e32 v36, v16, v38
	v_add_f32_e32 v36, v37, v36
	v_add_f32_e32 v41, v41, v36
	ds_read_b128 v[36:39], v182 offset:9216
	s_waitcnt lgkmcnt(1)
	v_mul_f32_e32 v33, v31, v33
	v_fmac_f32_e32 v33, v30, v32
	v_mul_f32_e32 v32, v29, v35
	v_fmac_f32_e32 v32, v28, v34
	s_waitcnt lgkmcnt(0)
	v_mul_f32_e32 v37, v27, v37
	v_add_f32_e32 v32, v33, v32
	v_fmac_f32_e32 v37, v26, v36
	v_mul_f32_e32 v36, v25, v39
	v_add_f32_e32 v42, 0, v32
	ds_read_b128 v[32:35], v182 offset:10240
	v_fmac_f32_e32 v36, v24, v38
	v_add_f32_e32 v36, v37, v36
	v_add_f32_e32 v42, v42, v36
	ds_read_b128 v[36:39], v182 offset:11264
	s_waitcnt lgkmcnt(1)
	v_mul_f32_e32 v33, v23, v33
	v_fmac_f32_e32 v33, v22, v32
	v_mul_f32_e32 v32, v21, v35
	v_fmac_f32_e32 v32, v20, v34
	s_waitcnt lgkmcnt(0)
	v_mul_f32_e32 v37, v19, v37
	v_add_f32_e32 v32, v33, v32
	v_fmac_f32_e32 v37, v18, v36
	v_mul_f32_e32 v36, v17, v39
	v_add_f32_e32 v42, v42, v32
	ds_read_b128 v[32:35], v182 offset:12288
	v_fmac_f32_e32 v36, v16, v38
	v_add_f32_e32 v36, v37, v36
	v_add_f32_e32 v42, v42, v36
	ds_read_b128 v[36:39], v182 offset:13312
	s_waitcnt lgkmcnt(1)
	v_mul_f32_e32 v33, v31, v33
	v_fmac_f32_e32 v33, v30, v32
	v_mul_f32_e32 v32, v29, v35
	v_fmac_f32_e32 v32, v28, v34
	s_waitcnt lgkmcnt(0)
	v_mul_f32_e32 v37, v27, v37
	v_add_f32_e32 v32, v33, v32
	v_fmac_f32_e32 v37, v26, v36
	v_mul_f32_e32 v36, v25, v39
	v_add_f32_e32 v43, 0, v32
	ds_read_b128 v[32:35], v182 offset:14336
	v_fmac_f32_e32 v36, v24, v38
	v_add_f32_e32 v36, v37, v36
	v_add_f32_e32 v43, v43, v36
	ds_read_b128 v[36:39], v182 offset:15360
	s_waitcnt lgkmcnt(1)
	v_mul_f32_e32 v33, v23, v33
	v_fmac_f32_e32 v33, v22, v32
	v_mul_f32_e32 v32, v21, v35
	v_fmac_f32_e32 v32, v20, v34
	s_waitcnt lgkmcnt(0)
	v_mul_f32_e32 v37, v19, v37
	v_add_f32_e32 v32, v33, v32
	v_fmac_f32_e32 v37, v18, v36
	v_mul_f32_e32 v36, v17, v39
	v_add_f32_e32 v43, v43, v32
	ds_read_b128 v[32:35], v182 offset:16384
	v_fmac_f32_e32 v36, v16, v38
	v_add_f32_e32 v36, v37, v36
	v_add_f32_e32 v43, v43, v36
	ds_read_b128 v[36:39], v182 offset:17408
	s_waitcnt lgkmcnt(1)
	v_mul_f32_e32 v33, v31, v33
	v_fmac_f32_e32 v33, v30, v32
	v_mul_f32_e32 v32, v29, v35
	v_fmac_f32_e32 v32, v28, v34
	s_waitcnt lgkmcnt(0)
	v_mul_f32_e32 v37, v27, v37
	v_add_f32_e32 v32, v33, v32
	v_fmac_f32_e32 v37, v26, v36
	v_mul_f32_e32 v36, v25, v39
	v_add_f32_e32 v44, 0, v32
	ds_read_b128 v[32:35], v182 offset:18432
	v_fmac_f32_e32 v36, v24, v38
	v_add_f32_e32 v36, v37, v36
	v_add_f32_e32 v44, v44, v36
	ds_read_b128 v[36:39], v182 offset:19456
	s_waitcnt lgkmcnt(1)
	v_mul_f32_e32 v33, v23, v33
	v_fmac_f32_e32 v33, v22, v32
	v_mul_f32_e32 v32, v21, v35
	v_fmac_f32_e32 v32, v20, v34
	s_waitcnt lgkmcnt(0)
	v_mul_f32_e32 v37, v19, v37
	v_add_f32_e32 v32, v33, v32
	v_fmac_f32_e32 v37, v18, v36
	v_mul_f32_e32 v36, v17, v39
	v_add_f32_e32 v44, v44, v32
	ds_read_b128 v[32:35], v182 offset:20480
	v_fmac_f32_e32 v36, v16, v38
	v_add_f32_e32 v36, v37, v36
	v_add_f32_e32 v44, v44, v36
	ds_read_b128 v[36:39], v182 offset:21504
	s_waitcnt lgkmcnt(1)
	v_mul_f32_e32 v33, v31, v33
	v_fmac_f32_e32 v33, v30, v32
	v_mul_f32_e32 v32, v29, v35
	v_fmac_f32_e32 v32, v28, v34
	s_waitcnt lgkmcnt(0)
	v_mul_f32_e32 v37, v27, v37
	v_add_f32_e32 v32, v33, v32
	v_fmac_f32_e32 v37, v26, v36
	v_mul_f32_e32 v36, v25, v39
	v_add_f32_e32 v45, 0, v32
	ds_read_b128 v[32:35], v182 offset:22528
	v_fmac_f32_e32 v36, v24, v38
	v_add_f32_e32 v36, v37, v36
	v_add_f32_e32 v45, v45, v36
	ds_read_b128 v[36:39], v182 offset:23552
	s_waitcnt lgkmcnt(1)
	v_mul_f32_e32 v33, v23, v33
	v_fmac_f32_e32 v33, v22, v32
	v_mul_f32_e32 v32, v21, v35
	v_fmac_f32_e32 v32, v20, v34
	s_waitcnt lgkmcnt(0)
	v_mul_f32_e32 v37, v19, v37
	v_add_f32_e32 v32, v33, v32
	v_fmac_f32_e32 v37, v18, v36
	v_mul_f32_e32 v36, v17, v39
	v_add_f32_e32 v45, v45, v32
	ds_read_b128 v[32:35], v182 offset:24576
	v_fmac_f32_e32 v36, v16, v38
	v_add_f32_e32 v36, v37, v36
	v_add_f32_e32 v45, v45, v36
	ds_read_b128 v[36:39], v182 offset:25600
	s_waitcnt lgkmcnt(1)
	v_mul_f32_e32 v33, v31, v33
	v_fmac_f32_e32 v33, v30, v32
	v_mul_f32_e32 v32, v29, v35
	v_fmac_f32_e32 v32, v28, v34
	s_waitcnt lgkmcnt(0)
	v_mul_f32_e32 v37, v27, v37
	v_add_f32_e32 v32, v33, v32
	v_fmac_f32_e32 v37, v26, v36
	v_mul_f32_e32 v36, v25, v39
	v_add_f32_e32 v46, 0, v32
	ds_read_b128 v[32:35], v182 offset:26624
	v_fmac_f32_e32 v36, v24, v38
	v_add_f32_e32 v36, v37, v36
	v_add_f32_e32 v46, v46, v36
	ds_read_b128 v[36:39], v182 offset:27648
	s_waitcnt lgkmcnt(1)
	v_mul_f32_e32 v33, v23, v33
	v_fmac_f32_e32 v33, v22, v32
	v_mul_f32_e32 v32, v21, v35
	v_fmac_f32_e32 v32, v20, v34
	s_waitcnt lgkmcnt(0)
	v_mul_f32_e32 v37, v19, v37
	v_add_f32_e32 v32, v33, v32
	v_fmac_f32_e32 v37, v18, v36
	v_mul_f32_e32 v36, v17, v39
	v_add_f32_e32 v46, v46, v32
	ds_read_b128 v[32:35], v182 offset:28672
	v_fmac_f32_e32 v36, v16, v38
	v_add_f32_e32 v36, v37, v36
	v_add_f32_e32 v46, v46, v36
	ds_read_b128 v[36:39], v182 offset:29696
	s_waitcnt lgkmcnt(1)
	v_mul_f32_e32 v31, v31, v33
	v_mul_f32_e32 v29, v29, v35
	v_fmac_f32_e32 v31, v30, v32
	v_fmac_f32_e32 v29, v28, v34
	v_add_f32_e32 v28, v31, v29
	s_waitcnt lgkmcnt(0)
	v_mul_f32_e32 v31, v27, v37
	v_mul_f32_e32 v25, v25, v39
	v_fmac_f32_e32 v31, v26, v36
	v_fmac_f32_e32 v25, v24, v38
	v_add_f32_e32 v30, 0, v28
	v_add_f32_e32 v24, v31, v25
	ds_read_b128 v[26:29], v182 offset:30720
	v_add_f32_e32 v24, v30, v24
	ds_read_b128 v[30:33], v182 offset:31744
	s_waitcnt lgkmcnt(1)
	v_mul_f32_e32 v23, v23, v27
	v_mul_f32_e32 v21, v21, v29
	s_waitcnt lgkmcnt(0)
	v_mul_f32_e32 v19, v19, v31
	v_fmac_f32_e32 v19, v18, v30
	v_cndmask_b32_e32 v18, v40, v44, vcc
	ds_bpermute_b32 v18, v184, v18
	v_fmac_f32_e32 v23, v22, v26
	v_fmac_f32_e32 v21, v20, v28
	v_mul_f32_e32 v17, v17, v33
	v_add_f32_e32 v20, v23, v21
	v_fmac_f32_e32 v17, v16, v32
	v_add_f32_e32 v20, v24, v20
	v_add_f32_e32 v16, v19, v17
	v_cndmask_b32_e32 v17, v44, v40, vcc
	v_add_f32_e32 v16, v20, v16
	s_waitcnt lgkmcnt(0)
	v_add_f32_e32 v17, v17, v18
	v_cndmask_b32_e32 v18, v41, v45, vcc
	ds_bpermute_b32 v18, v184, v18
	v_cndmask_b32_e32 v20, v42, v46, vcc
	v_cndmask_b32_e32 v21, v43, v16, vcc
	ds_bpermute_b32 v20, v184, v20
	ds_bpermute_b32 v21, v184, v21
	v_cndmask_b32_e32 v19, v45, v41, vcc
	s_waitcnt lgkmcnt(2)
	v_add_f32_e32 v18, v19, v18
	v_cndmask_b32_e32 v19, v46, v42, vcc
	v_cndmask_b32_e32 v16, v16, v43, vcc
	s_waitcnt lgkmcnt(1)
	v_add_f32_e32 v19, v19, v20
	s_waitcnt lgkmcnt(0)
	v_add_f32_e32 v16, v16, v21
	v_cndmask_b32_e64 v20, v17, v19, s[4:5]
	v_cndmask_b32_e64 v21, v18, v16, s[4:5]
	ds_bpermute_b32 v20, v185, v20
	ds_bpermute_b32 v21, v185, v21
	v_cndmask_b32_e64 v17, v19, v17, s[4:5]
	v_cndmask_b32_e64 v16, v16, v18, s[4:5]
	s_waitcnt lgkmcnt(1)
	v_add_f32_e32 v17, v17, v20
	s_waitcnt lgkmcnt(0)
	v_add_f32_e32 v16, v16, v21
	v_cndmask_b32_e64 v18, v17, v16, s[6:7]
	ds_bpermute_b32 v18, v186, v18
	v_cndmask_b32_e64 v16, v16, v17, s[6:7]
	s_waitcnt lgkmcnt(0)
	v_add_f32_e32 v16, v16, v18
	ds_bpermute_b32 v17, v187, v16
	s_waitcnt lgkmcnt(0)
	v_add_f32_e32 v16, v16, v17
	ds_bpermute_b32 v17, v188, v16
	s_waitcnt lgkmcnt(0)
	v_add_f32_e32 v16, v16, v17
	ds_bpermute_b32 v17, v189, v16
	s_and_saveexec_b64 s[24:25], s[8:9]
	s_cbranch_execz .LBB0_106
	v_mov_b32_e32 v18, v216
	s_waitcnt lgkmcnt(0)
	v_add_f32_e32 v19, v16, v17
	s_ashr_i32 s0, s22, 31
	s_lshr_b32 s0, s0, 19
	s_add_i32 s0, s22, s0
	s_ashr_i32 s1, s0, 13
	s_and_b32 s0, s0, 0xffffe000
	v_lshl_or_b32 v16, s1, 3, v183
	s_sub_i32 s22, s22, s0
	v_ashrrev_i32_e32 v17, 31, v16
	v_lshlrev_b64 v[16:17], 15, v[16:17]
	s_ashr_i32 s23, s22, 31
	v_lshl_add_u64 v[16:17], s[12:13], 0, v[16:17]
	v_lshl_add_u64 v[16:17], s[22:23], 2, v[16:17]
	v_add_f32_e32 v18, v19, v18
	v_mul_f32_e64 v19, |v18|, s41
	v_exp_f32_e32 v32, v19
	v_min_f32_e32 v33, 0, v18
	v_add_f32_e32 v20, 1.0, v32
	v_add_f32_e32 v21, -1.0, v20
	v_frexp_mant_f32_e32 v22, v20
	v_cvt_f64_f32_e32 v[18:19], v20
	v_sub_f32_e32 v23, v21, v20
	v_frexp_exp_i32_f64_e32 v18, v[18:19]
	v_cmp_gt_f32_e64 s[0:1], s42, v22
	v_sub_f32_e32 v21, v32, v21
	v_add_f32_e32 v19, 1.0, v23
	v_subbrev_co_u32_e64 v18, s[0:1], 0, v18, s[0:1]
	v_add_f32_e32 v19, v21, v19
	v_sub_u32_e32 v21, 0, v18
	v_ldexp_f32 v20, v20, v21
	v_add_f32_e32 v22, -1.0, v20
	v_add_f32_e32 v23, 1.0, v20
	v_ldexp_f32 v19, v19, v21
	v_add_f32_e32 v21, 1.0, v22
	v_add_f32_e32 v24, -1.0, v23
	v_sub_f32_e32 v21, v20, v21
	v_sub_f32_e32 v20, v20, v24
	v_add_f32_e32 v24, v19, v21
	v_add_f32_e32 v19, v19, v20
	v_add_f32_e32 v26, v23, v19
	v_rcp_f32_e32 v27, v26
	v_add_f32_e32 v21, v22, v24
	v_sub_f32_e32 v22, v21, v22
	v_sub_f32_e32 v20, v26, v23
	v_mul_f32_e32 v29, v21, v27
	v_sub_f32_e32 v28, v24, v22
	v_mul_f32_e32 v22, v26, v29
	v_sub_f32_e32 v19, v19, v20
	v_fma_f32 v24, v29, v26, -v22
	v_fmac_f32_e32 v24, v29, v19
	v_add_f32_e32 v20, v22, v24
	v_sub_f32_e32 v23, v21, v20
	v_mov_b32_e32 v25, v20
	v_pk_add_f32 v[20:21], v[20:21], v[22:23] neg_lo:[0,1] neg_hi:[0,1]
	v_cvt_f32_i32_e32 v18, v18
	v_pk_add_f32 v[20:21], v[20:21], v[24:25] neg_lo:[0,1] neg_hi:[0,1]
	v_cmp_neq_f32_e64 s[0:1], s44, v32
	v_add_f32_e32 v21, v28, v21
	v_add_f32_e32 v20, v20, v21
	v_add_f32_e32 v21, v23, v20
	v_mul_f32_e32 v25, v27, v21
	v_mul_f32_e32 v22, v26, v25
	v_sub_f32_e32 v23, v23, v21
	v_add_f32_e32 v30, v29, v25
	v_fma_f32 v24, v25, v26, -v22
	v_add_f32_e32 v28, v20, v23
	v_sub_f32_e32 v20, v30, v29
	v_fmac_f32_e32 v24, v25, v19
	v_sub_f32_e32 v19, v25, v20
	v_add_f32_e32 v20, v22, v24
	v_sub_f32_e32 v23, v21, v20
	v_mov_b32_e32 v25, v20
	v_pk_add_f32 v[20:21], v[20:21], v[22:23] neg_lo:[0,1] neg_hi:[0,1]
	s_nop 0
	v_pk_add_f32 v[20:21], v[20:21], v[24:25] neg_lo:[0,1] neg_hi:[0,1]
	s_nop 0
	v_add_f32_e32 v21, v28, v21
	v_add_f32_e32 v20, v20, v21
	v_add_f32_e32 v20, v23, v20
	v_mul_f32_e32 v20, v27, v20
	v_add_f32_e32 v19, v19, v20
	v_add_f32_e32 v20, v30, v19
	v_mul_f32_e32 v22, v20, v20
	v_sub_f32_e32 v23, v20, v30
	v_fmamk_f32 v24, v22, 0x3e9b6dac, v195
	v_sub_f32_e32 v23, v19, v23
	v_mul_f32_e32 v19, v20, v22
	v_fmaak_f32 v147, v22, v24, 0x3f2aaada
	v_ldexp_f32 v25, v23, 1
	v_pk_mul_f32 v[22:23], v[18:19], v[146:147]
	v_ldexp_f32 v21, v20, 1
	v_fma_f32 v20, v18, s43, -v22
	v_fmac_f32_e32 v20, 0xb102e308, v18
	v_pk_add_f32 v[18:19], v[22:23], v[20:21]
	v_mov_b32_e32 v24, v22
	v_sub_f32_e32 v28, v19, v21
	v_pk_add_f32 v[26:27], v[18:19], v[22:23] neg_lo:[0,1] neg_hi:[0,1]
	v_sub_f32_e32 v22, v23, v28
	v_add_f32_e32 v25, v25, v22
	v_pk_add_f32 v[22:23], v[18:19], v[24:25]
	v_mov_b32_e32 v21, v18
	v_mov_b32_e32 v27, v23
	v_pk_add_f32 v[30:31], v[20:21], v[26:27] neg_lo:[0,1] neg_hi:[0,1]
	v_pk_add_f32 v[20:21], v[20:21], v[26:27]
	v_mov_b32_e32 v29, v18
	v_pk_add_f32 v[26:27], v[20:21], v[18:19] op_sel:[1,0] op_sel_hi:[0,1] neg_lo:[0,1] neg_hi:[0,1]
	v_mov_b32_e32 v28, v25
	v_mov_b32_e32 v24, v23
	v_mov_b32_e32 v25, v21
	v_pk_mov_b32 v[18:19], v[18:19], v[26:27] op_sel:[1,0]
	v_pk_add_f32 v[22:23], v[22:23], v[26:27] op_sel_hi:[1,0] neg_lo:[0,1] neg_hi:[0,1]
	v_pk_add_f32 v[18:19], v[24:25], v[18:19] neg_lo:[0,1] neg_hi:[0,1]
	v_mov_b32_e32 v22, v30
	v_pk_add_f32 v[18:19], v[28:29], v[18:19] neg_lo:[0,1] neg_hi:[0,1]
	v_mov_b32_e32 v31, v21
	v_pk_add_f32 v[22:23], v[22:23], v[18:19]
	s_nop 0
	v_pk_add_f32 v[24:25], v[22:23], v[22:23] op_sel:[0,1] op_sel_hi:[1,0]
	s_nop 0
	v_pk_add_f32 v[20:21], v[20:21], v[24:25] op_sel:[1,0] op_sel_hi:[0,1]
	v_mov_b32_e32 v23, v20
	v_mov_b32_e32 v19, v24
	v_pk_add_f32 v[24:25], v[22:23], v[30:31] neg_lo:[0,1] neg_hi:[0,1]
	s_nop 0
	v_sub_f32_e32 v21, v22, v24
	v_pk_add_f32 v[18:19], v[18:19], v[24:25] neg_lo:[0,1] neg_hi:[0,1]
	v_sub_f32_e32 v21, v30, v21
	v_add_f32_e32 v18, v18, v21
	v_add_f32_e32 v18, v18, v19
	v_add_f32_e32 v18, v20, v18
	v_cndmask_b32_e64 v18, v196, v18, s[0:1]
	v_cmp_ngt_f32_e64 s[0:1], -1.0, v32
	s_nop 1
	v_cndmask_b32_e64 v18, v197, v18, s[0:1]
	v_cmp_neq_f32_e64 s[0:1], -1.0, v32
	s_nop 1
	v_cndmask_b32_e64 v18, v198, v18, s[0:1]
	v_cmp_lt_f32_e64 s[0:1], |v32|, s45
	s_nop 1
	v_cndmask_b32_e64 v18, v18, v32, s[0:1]
	v_sub_f32_e32 v18, v33, v18
	global_store_dword v[16:17], v18, off
.LBB0_106:
	s_or_b64 exec, exec, s[24:25]
	v_add_f32_e32 v16, v48, v49
	v_fmamk_f32 v16, v16, 0x3a800000, v194
	v_rsq_f32_e32 v16, v16
	s_lshl_b64 s[0:1], s[20:21], 11
	v_lshl_add_u64 v[18:19], v[130:131], 0, s[0:1]
	s_waitcnt lgkmcnt(0)
	v_pk_mul_f32 v[14:15], v[14:15], v[16:17] op_sel_hi:[1,0]
	v_pk_mul_f32 v[20:21], v[12:13], v[16:17] op_sel_hi:[1,0]
	v_pk_fma_f32 v[12:13], v[152:153], v[14:15], v[148:149]
	v_pk_fma_f32 v[14:15], v[154:155], v[20:21], v[150:151]
	v_cvt_pk_bf16_f32 v21, v12, v13
	v_pk_mul_f32 v[10:11], v[10:11], v[16:17] op_sel_hi:[1,0]
	v_cvt_pk_bf16_f32 v20, v14, v15
	global_store_dwordx2 v[18:19], v[20:21], off
	v_pk_mul_f32 v[20:21], v[8:9], v[16:17] op_sel_hi:[1,0]
	v_pk_fma_f32 v[8:9], v[160:161], v[10:11], v[156:157]
	v_pk_fma_f32 v[10:11], v[162:163], v[20:21], v[158:159]
	v_cvt_pk_bf16_f32 v21, v8, v9
	v_pk_mul_f32 v[6:7], v[6:7], v[16:17] op_sel_hi:[1,0]
	v_cvt_pk_bf16_f32 v20, v10, v11
	global_store_dwordx2 v[18:19], v[20:21], off offset:512
	v_pk_mul_f32 v[20:21], v[4:5], v[16:17] op_sel_hi:[1,0]
	v_pk_mul_f32 v[2:3], v[2:3], v[16:17] op_sel_hi:[1,0]
	v_pk_mul_f32 v[16:17], v[0:1], v[16:17] op_sel_hi:[1,0]
	v_pk_fma_f32 v[4:5], v[168:169], v[6:7], v[164:165]
	v_pk_fma_f32 v[6:7], v[170:171], v[20:21], v[166:167]
	v_cvt_pk_bf16_f32 v21, v4, v5
	v_pk_fma_f32 v[0:1], v[176:177], v[2:3], v[172:173]
	v_cvt_pk_bf16_f32 v20, v6, v7
	global_store_dwordx2 v[18:19], v[20:21], off offset:1024
	v_pk_fma_f32 v[2:3], v[178:179], v[16:17], v[174:175]
	v_cvt_pk_bf16_f32 v17, v0, v1
	s_nop 0
	v_cvt_pk_bf16_f32 v16, v2, v3
	global_store_dwordx2 v[18:19], v[16:17], off offset:1536
	ds_read_b128 v[16:19], v182
	ds_read_b128 v[20:23], v182 offset:1024
	s_waitcnt lgkmcnt(1)
	v_mul_f32_e32 v17, v15, v17
	v_fmac_f32_e32 v17, v14, v16
	v_mul_f32_e32 v16, v13, v19
	v_fmac_f32_e32 v16, v12, v18
	s_waitcnt lgkmcnt(0)
	v_mul_f32_e32 v21, v11, v21
	v_add_f32_e32 v16, v17, v16
	v_fmac_f32_e32 v21, v10, v20
	v_mul_f32_e32 v20, v9, v23
	v_add_f32_e32 v24, 0, v16
	ds_read_b128 v[16:19], v182 offset:2048
	v_fmac_f32_e32 v20, v8, v22
	v_add_f32_e32 v20, v21, v20
	v_add_f32_e32 v24, v24, v20
	ds_read_b128 v[20:23], v182 offset:3072
	s_waitcnt lgkmcnt(1)
	v_mul_f32_e32 v17, v7, v17
	v_fmac_f32_e32 v17, v6, v16
	v_mul_f32_e32 v16, v5, v19
	v_fmac_f32_e32 v16, v4, v18
	s_waitcnt lgkmcnt(0)
	v_mul_f32_e32 v21, v3, v21
	v_add_f32_e32 v16, v17, v16
	v_fmac_f32_e32 v21, v2, v20
	v_mul_f32_e32 v20, v1, v23
	v_add_f32_e32 v24, v24, v16
	ds_read_b128 v[16:19], v182 offset:4096
	v_fmac_f32_e32 v20, v0, v22
	v_add_f32_e32 v20, v21, v20
	v_add_f32_e32 v24, v24, v20
	ds_read_b128 v[20:23], v182 offset:5120
	s_waitcnt lgkmcnt(1)
	v_mul_f32_e32 v17, v15, v17
	v_fmac_f32_e32 v17, v14, v16
	v_mul_f32_e32 v16, v13, v19
	v_fmac_f32_e32 v16, v12, v18
	s_waitcnt lgkmcnt(0)
	v_mul_f32_e32 v21, v11, v21
	v_add_f32_e32 v16, v17, v16
	v_fmac_f32_e32 v21, v10, v20
	v_mul_f32_e32 v20, v9, v23
	v_add_f32_e32 v25, 0, v16
	ds_read_b128 v[16:19], v182 offset:6144
	v_fmac_f32_e32 v20, v8, v22
	v_add_f32_e32 v20, v21, v20
	v_add_f32_e32 v25, v25, v20
	ds_read_b128 v[20:23], v182 offset:7168
	s_waitcnt lgkmcnt(1)
	v_mul_f32_e32 v17, v7, v17
	v_fmac_f32_e32 v17, v6, v16
	v_mul_f32_e32 v16, v5, v19
	v_fmac_f32_e32 v16, v4, v18
	s_waitcnt lgkmcnt(0)
	v_mul_f32_e32 v21, v3, v21
	v_add_f32_e32 v16, v17, v16
	v_fmac_f32_e32 v21, v2, v20
	v_mul_f32_e32 v20, v1, v23
	v_add_f32_e32 v25, v25, v16
	ds_read_b128 v[16:19], v182 offset:8192
	v_fmac_f32_e32 v20, v0, v22
	v_add_f32_e32 v20, v21, v20
	v_add_f32_e32 v25, v25, v20
	ds_read_b128 v[20:23], v182 offset:9216
	s_waitcnt lgkmcnt(1)
	v_mul_f32_e32 v17, v15, v17
	v_fmac_f32_e32 v17, v14, v16
	v_mul_f32_e32 v16, v13, v19
	v_fmac_f32_e32 v16, v12, v18
	s_waitcnt lgkmcnt(0)
	v_mul_f32_e32 v21, v11, v21
	v_add_f32_e32 v16, v17, v16
	v_fmac_f32_e32 v21, v10, v20
	v_mul_f32_e32 v20, v9, v23
	v_add_f32_e32 v26, 0, v16
	ds_read_b128 v[16:19], v182 offset:10240
	v_fmac_f32_e32 v20, v8, v22
	v_add_f32_e32 v20, v21, v20
	v_add_f32_e32 v26, v26, v20
	ds_read_b128 v[20:23], v182 offset:11264
	s_waitcnt lgkmcnt(1)
	v_mul_f32_e32 v17, v7, v17
	v_fmac_f32_e32 v17, v6, v16
	v_mul_f32_e32 v16, v5, v19
	v_fmac_f32_e32 v16, v4, v18
	s_waitcnt lgkmcnt(0)
	v_mul_f32_e32 v21, v3, v21
	v_add_f32_e32 v16, v17, v16
	v_fmac_f32_e32 v21, v2, v20
	v_mul_f32_e32 v20, v1, v23
	v_add_f32_e32 v26, v26, v16
	ds_read_b128 v[16:19], v182 offset:12288
	v_fmac_f32_e32 v20, v0, v22
	v_add_f32_e32 v20, v21, v20
	v_add_f32_e32 v26, v26, v20
	ds_read_b128 v[20:23], v182 offset:13312
	s_waitcnt lgkmcnt(1)
	v_mul_f32_e32 v17, v15, v17
	v_fmac_f32_e32 v17, v14, v16
	v_mul_f32_e32 v16, v13, v19
	v_fmac_f32_e32 v16, v12, v18
	s_waitcnt lgkmcnt(0)
	v_mul_f32_e32 v21, v11, v21
	v_add_f32_e32 v16, v17, v16
	v_fmac_f32_e32 v21, v10, v20
	v_mul_f32_e32 v20, v9, v23
	v_add_f32_e32 v27, 0, v16
	ds_read_b128 v[16:19], v182 offset:14336
	v_fmac_f32_e32 v20, v8, v22
	v_add_f32_e32 v20, v21, v20
	v_add_f32_e32 v27, v27, v20
	ds_read_b128 v[20:23], v182 offset:15360
	s_waitcnt lgkmcnt(1)
	v_mul_f32_e32 v17, v7, v17
	v_fmac_f32_e32 v17, v6, v16
	v_mul_f32_e32 v16, v5, v19
	v_fmac_f32_e32 v16, v4, v18
	s_waitcnt lgkmcnt(0)
	v_mul_f32_e32 v21, v3, v21
	v_add_f32_e32 v16, v17, v16
	v_fmac_f32_e32 v21, v2, v20
	v_mul_f32_e32 v20, v1, v23
	v_add_f32_e32 v27, v27, v16
	ds_read_b128 v[16:19], v182 offset:16384
	v_fmac_f32_e32 v20, v0, v22
	v_add_f32_e32 v20, v21, v20
	v_add_f32_e32 v27, v27, v20
	ds_read_b128 v[20:23], v182 offset:17408
	s_waitcnt lgkmcnt(1)
	v_mul_f32_e32 v17, v15, v17
	v_fmac_f32_e32 v17, v14, v16
	v_mul_f32_e32 v16, v13, v19
	v_fmac_f32_e32 v16, v12, v18
	s_waitcnt lgkmcnt(0)
	v_mul_f32_e32 v21, v11, v21
	v_add_f32_e32 v16, v17, v16
	v_fmac_f32_e32 v21, v10, v20
	v_mul_f32_e32 v20, v9, v23
	v_add_f32_e32 v28, 0, v16
	ds_read_b128 v[16:19], v182 offset:18432
	v_fmac_f32_e32 v20, v8, v22
	v_add_f32_e32 v20, v21, v20
	v_add_f32_e32 v28, v28, v20
	ds_read_b128 v[20:23], v182 offset:19456
	s_waitcnt lgkmcnt(1)
	v_mul_f32_e32 v17, v7, v17
	v_fmac_f32_e32 v17, v6, v16
	v_mul_f32_e32 v16, v5, v19
	v_fmac_f32_e32 v16, v4, v18
	s_waitcnt lgkmcnt(0)
	v_mul_f32_e32 v21, v3, v21
	v_add_f32_e32 v16, v17, v16
	v_fmac_f32_e32 v21, v2, v20
	v_mul_f32_e32 v20, v1, v23
	v_add_f32_e32 v28, v28, v16
	ds_read_b128 v[16:19], v182 offset:20480
	v_fmac_f32_e32 v20, v0, v22
	v_add_f32_e32 v20, v21, v20
	v_add_f32_e32 v28, v28, v20
	ds_read_b128 v[20:23], v182 offset:21504
	s_waitcnt lgkmcnt(1)
	v_mul_f32_e32 v17, v15, v17
	v_fmac_f32_e32 v17, v14, v16
	v_mul_f32_e32 v16, v13, v19
	v_fmac_f32_e32 v16, v12, v18
	s_waitcnt lgkmcnt(0)
	v_mul_f32_e32 v21, v11, v21
	v_add_f32_e32 v16, v17, v16
	v_fmac_f32_e32 v21, v10, v20
	v_mul_f32_e32 v20, v9, v23
	v_add_f32_e32 v29, 0, v16
	ds_read_b128 v[16:19], v182 offset:22528
	v_fmac_f32_e32 v20, v8, v22
	v_add_f32_e32 v20, v21, v20
	v_add_f32_e32 v29, v29, v20
	ds_read_b128 v[20:23], v182 offset:23552
	s_waitcnt lgkmcnt(1)
	v_mul_f32_e32 v17, v7, v17
	v_fmac_f32_e32 v17, v6, v16
	v_mul_f32_e32 v16, v5, v19
	v_fmac_f32_e32 v16, v4, v18
	s_waitcnt lgkmcnt(0)
	v_mul_f32_e32 v21, v3, v21
	v_add_f32_e32 v16, v17, v16
	v_fmac_f32_e32 v21, v2, v20
	v_mul_f32_e32 v20, v1, v23
	v_add_f32_e32 v29, v29, v16
	ds_read_b128 v[16:19], v182 offset:24576
	v_fmac_f32_e32 v20, v0, v22
	v_add_f32_e32 v20, v21, v20
	v_add_f32_e32 v29, v29, v20
	ds_read_b128 v[20:23], v182 offset:25600
	s_waitcnt lgkmcnt(1)
	v_mul_f32_e32 v17, v15, v17
	v_fmac_f32_e32 v17, v14, v16
	v_mul_f32_e32 v16, v13, v19
	v_fmac_f32_e32 v16, v12, v18
	s_waitcnt lgkmcnt(0)
	v_mul_f32_e32 v21, v11, v21
	v_add_f32_e32 v16, v17, v16
	v_fmac_f32_e32 v21, v10, v20
	v_mul_f32_e32 v20, v9, v23
	v_add_f32_e32 v30, 0, v16
	ds_read_b128 v[16:19], v182 offset:26624
	v_fmac_f32_e32 v20, v8, v22
	v_add_f32_e32 v20, v21, v20
	v_add_f32_e32 v30, v30, v20
	ds_read_b128 v[20:23], v182 offset:27648
	s_waitcnt lgkmcnt(1)
	v_mul_f32_e32 v17, v7, v17
	v_fmac_f32_e32 v17, v6, v16
	v_mul_f32_e32 v16, v5, v19
	v_fmac_f32_e32 v16, v4, v18
	s_waitcnt lgkmcnt(0)
	v_mul_f32_e32 v21, v3, v21
	v_add_f32_e32 v16, v17, v16
	v_fmac_f32_e32 v21, v2, v20
	v_mul_f32_e32 v20, v1, v23
	v_add_f32_e32 v30, v30, v16
	ds_read_b128 v[16:19], v182 offset:28672
	v_fmac_f32_e32 v20, v0, v22
	v_add_f32_e32 v20, v21, v20
	v_add_f32_e32 v30, v30, v20
	ds_read_b128 v[20:23], v182 offset:29696
	s_waitcnt lgkmcnt(1)
	v_mul_f32_e32 v15, v15, v17
	v_mul_f32_e32 v13, v13, v19
	v_fmac_f32_e32 v15, v14, v16
	v_fmac_f32_e32 v13, v12, v18
	v_add_f32_e32 v12, v15, v13
	s_waitcnt lgkmcnt(0)
	v_mul_f32_e32 v15, v11, v21
	v_mul_f32_e32 v9, v9, v23
	v_fmac_f32_e32 v15, v10, v20
	v_fmac_f32_e32 v9, v8, v22
	v_add_f32_e32 v14, 0, v12
	v_add_f32_e32 v8, v15, v9
	ds_read_b128 v[10:13], v182 offset:30720
	v_add_f32_e32 v8, v14, v8
	ds_read_b128 v[14:17], v182 offset:31744
	s_waitcnt lgkmcnt(1)
	v_mul_f32_e32 v7, v7, v11
	v_mul_f32_e32 v5, v5, v13
	s_waitcnt lgkmcnt(0)
	v_mul_f32_e32 v3, v3, v15
	v_fmac_f32_e32 v3, v2, v14
	v_cndmask_b32_e32 v2, v24, v28, vcc
	ds_bpermute_b32 v2, v184, v2
	v_fmac_f32_e32 v7, v6, v10
	v_fmac_f32_e32 v5, v4, v12
	v_mul_f32_e32 v1, v1, v17
	v_add_f32_e32 v4, v7, v5
	v_fmac_f32_e32 v1, v0, v16
	v_add_f32_e32 v4, v8, v4
	v_add_f32_e32 v0, v3, v1
	v_cndmask_b32_e32 v1, v28, v24, vcc
	v_add_f32_e32 v0, v4, v0
	s_waitcnt lgkmcnt(0)
	v_add_f32_e32 v1, v1, v2
	v_cndmask_b32_e32 v2, v25, v29, vcc
	ds_bpermute_b32 v2, v184, v2
	v_cndmask_b32_e32 v4, v26, v30, vcc
	v_cndmask_b32_e32 v5, v27, v0, vcc
	ds_bpermute_b32 v4, v184, v4
	ds_bpermute_b32 v5, v184, v5
	v_cndmask_b32_e32 v3, v29, v25, vcc
	s_waitcnt lgkmcnt(2)
	v_add_f32_e32 v2, v3, v2
	v_cndmask_b32_e32 v3, v30, v26, vcc
	v_cndmask_b32_e32 v0, v0, v27, vcc
	s_waitcnt lgkmcnt(1)
	v_add_f32_e32 v3, v3, v4
	s_waitcnt lgkmcnt(0)
	v_add_f32_e32 v0, v0, v5
	v_cndmask_b32_e64 v4, v1, v3, s[4:5]
	v_cndmask_b32_e64 v5, v2, v0, s[4:5]
	ds_bpermute_b32 v4, v185, v4
	ds_bpermute_b32 v5, v185, v5
	v_cndmask_b32_e64 v1, v3, v1, s[4:5]
	v_cndmask_b32_e64 v0, v0, v2, s[4:5]
	s_waitcnt lgkmcnt(1)
	v_add_f32_e32 v1, v1, v4
	s_waitcnt lgkmcnt(0)
	v_add_f32_e32 v0, v0, v5
	v_cndmask_b32_e64 v2, v1, v0, s[6:7]
	ds_bpermute_b32 v2, v186, v2
	v_cndmask_b32_e64 v0, v0, v1, s[6:7]
	s_waitcnt lgkmcnt(0)
	v_add_f32_e32 v0, v0, v2
	ds_bpermute_b32 v1, v187, v0
	s_waitcnt lgkmcnt(0)
	v_add_f32_e32 v0, v0, v1
	ds_bpermute_b32 v1, v188, v0
	s_waitcnt lgkmcnt(0)
	v_add_f32_e32 v0, v0, v1
	ds_bpermute_b32 v1, v189, v0
	s_and_saveexec_b64 s[22:23], s[8:9]
	s_cbranch_execz .LBB0_91
	v_mov_b32_e32 v2, v216
	s_waitcnt lgkmcnt(0)
	v_add_f32_e32 v3, v0, v1
	s_ashr_i32 s0, s20, 31
	s_lshr_b32 s0, s0, 19
	s_add_i32 s0, s20, s0
	s_ashr_i32 s1, s0, 13
	s_and_b32 s0, s0, 0xffffe000
	v_lshl_or_b32 v0, s1, 3, v183
	s_sub_i32 s20, s20, s0
	v_ashrrev_i32_e32 v1, 31, v0
	v_lshlrev_b64 v[0:1], 15, v[0:1]
	s_ashr_i32 s21, s20, 31
	v_lshl_add_u64 v[0:1], s[12:13], 0, v[0:1]
	v_lshl_add_u64 v[0:1], s[20:21], 2, v[0:1]
	v_add_f32_e32 v2, v3, v2
	v_mul_f32_e64 v3, |v2|, s41
	v_exp_f32_e32 v16, v3
	v_min_f32_e32 v17, 0, v2
	v_add_f32_e32 v4, 1.0, v16
	v_add_f32_e32 v5, -1.0, v4
	v_frexp_mant_f32_e32 v6, v4
	v_cvt_f64_f32_e32 v[2:3], v4
	v_sub_f32_e32 v7, v5, v4
	v_frexp_exp_i32_f64_e32 v2, v[2:3]
	v_cmp_gt_f32_e64 s[0:1], s42, v6
	v_sub_f32_e32 v5, v16, v5
	v_add_f32_e32 v3, 1.0, v7
	v_subbrev_co_u32_e64 v2, s[0:1], 0, v2, s[0:1]
	v_add_f32_e32 v3, v5, v3
	v_sub_u32_e32 v5, 0, v2
	v_ldexp_f32 v4, v4, v5
	v_add_f32_e32 v6, -1.0, v4
	v_add_f32_e32 v7, 1.0, v4
	v_ldexp_f32 v3, v3, v5
	v_add_f32_e32 v5, 1.0, v6
	v_add_f32_e32 v8, -1.0, v7
	v_sub_f32_e32 v5, v4, v5
	v_sub_f32_e32 v4, v4, v8
	v_add_f32_e32 v8, v3, v5
	v_add_f32_e32 v3, v3, v4
	v_add_f32_e32 v10, v7, v3
	v_rcp_f32_e32 v11, v10
	v_add_f32_e32 v5, v6, v8
	v_sub_f32_e32 v6, v5, v6
	v_sub_f32_e32 v4, v10, v7
	v_mul_f32_e32 v13, v5, v11
	v_sub_f32_e32 v12, v8, v6
	v_mul_f32_e32 v6, v10, v13
	v_sub_f32_e32 v3, v3, v4
	v_fma_f32 v8, v13, v10, -v6
	v_fmac_f32_e32 v8, v13, v3
	v_add_f32_e32 v4, v6, v8
	v_sub_f32_e32 v7, v5, v4
	v_mov_b32_e32 v9, v4
	v_pk_add_f32 v[4:5], v[4:5], v[6:7] neg_lo:[0,1] neg_hi:[0,1]
	v_cvt_f32_i32_e32 v2, v2
	v_pk_add_f32 v[4:5], v[4:5], v[8:9] neg_lo:[0,1] neg_hi:[0,1]
	v_cmp_neq_f32_e64 s[0:1], s44, v16
	v_add_f32_e32 v5, v12, v5
	v_add_f32_e32 v4, v4, v5
	v_add_f32_e32 v5, v7, v4
	v_mul_f32_e32 v9, v11, v5
	v_mul_f32_e32 v6, v10, v9
	v_sub_f32_e32 v7, v7, v5
	v_add_f32_e32 v14, v13, v9
	v_fma_f32 v8, v9, v10, -v6
	v_add_f32_e32 v12, v4, v7
	v_sub_f32_e32 v4, v14, v13
	v_fmac_f32_e32 v8, v9, v3
	v_sub_f32_e32 v3, v9, v4
	v_add_f32_e32 v4, v6, v8
	v_sub_f32_e32 v7, v5, v4
	v_mov_b32_e32 v9, v4
	v_pk_add_f32 v[4:5], v[4:5], v[6:7] neg_lo:[0,1] neg_hi:[0,1]
	s_nop 0
	v_pk_add_f32 v[4:5], v[4:5], v[8:9] neg_lo:[0,1] neg_hi:[0,1]
	s_nop 0
	v_add_f32_e32 v5, v12, v5
	v_add_f32_e32 v4, v4, v5
	v_add_f32_e32 v4, v7, v4
	v_mul_f32_e32 v4, v11, v4
	v_add_f32_e32 v3, v3, v4
	v_add_f32_e32 v4, v14, v3
	v_mul_f32_e32 v6, v4, v4
	v_sub_f32_e32 v7, v4, v14
	v_fmamk_f32 v8, v6, 0x3e9b6dac, v195
	v_sub_f32_e32 v7, v3, v7
	v_mul_f32_e32 v3, v4, v6
	v_fmaak_f32 v147, v6, v8, 0x3f2aaada
	v_ldexp_f32 v9, v7, 1
	v_pk_mul_f32 v[6:7], v[2:3], v[146:147]
	v_ldexp_f32 v5, v4, 1
	v_fma_f32 v4, v2, s43, -v6
	v_fmac_f32_e32 v4, 0xb102e308, v2
	v_pk_add_f32 v[2:3], v[6:7], v[4:5]
	v_mov_b32_e32 v8, v6
	v_sub_f32_e32 v12, v3, v5
	v_pk_add_f32 v[10:11], v[2:3], v[6:7] neg_lo:[0,1] neg_hi:[0,1]
	v_sub_f32_e32 v6, v7, v12
	v_add_f32_e32 v9, v9, v6
	v_pk_add_f32 v[6:7], v[2:3], v[8:9]
	v_mov_b32_e32 v5, v2
	v_mov_b32_e32 v11, v7
	v_pk_add_f32 v[14:15], v[4:5], v[10:11] neg_lo:[0,1] neg_hi:[0,1]
	v_pk_add_f32 v[4:5], v[4:5], v[10:11]
	v_mov_b32_e32 v13, v2
	v_pk_add_f32 v[10:11], v[4:5], v[2:3] op_sel:[1,0] op_sel_hi:[0,1] neg_lo:[0,1] neg_hi:[0,1]
	v_mov_b32_e32 v12, v9
	v_mov_b32_e32 v8, v7
	v_mov_b32_e32 v9, v5
	v_pk_mov_b32 v[2:3], v[2:3], v[10:11] op_sel:[1,0]
	v_pk_add_f32 v[6:7], v[6:7], v[10:11] op_sel_hi:[1,0] neg_lo:[0,1] neg_hi:[0,1]
	v_pk_add_f32 v[2:3], v[8:9], v[2:3] neg_lo:[0,1] neg_hi:[0,1]
	v_mov_b32_e32 v6, v14
	v_pk_add_f32 v[2:3], v[12:13], v[2:3] neg_lo:[0,1] neg_hi:[0,1]
	v_mov_b32_e32 v15, v5
	v_pk_add_f32 v[6:7], v[6:7], v[2:3]
	s_nop 0
	v_pk_add_f32 v[8:9], v[6:7], v[6:7] op_sel:[0,1] op_sel_hi:[1,0]
	s_nop 0
	v_pk_add_f32 v[4:5], v[4:5], v[8:9] op_sel:[1,0] op_sel_hi:[0,1]
	v_mov_b32_e32 v7, v4
	v_mov_b32_e32 v3, v8
	v_pk_add_f32 v[8:9], v[6:7], v[14:15] neg_lo:[0,1] neg_hi:[0,1]
	s_nop 0
	v_sub_f32_e32 v5, v6, v8
	v_pk_add_f32 v[2:3], v[2:3], v[8:9] neg_lo:[0,1] neg_hi:[0,1]
	v_sub_f32_e32 v5, v14, v5
	v_add_f32_e32 v2, v2, v5
	v_add_f32_e32 v2, v2, v3
	v_add_f32_e32 v2, v4, v2
	v_cndmask_b32_e64 v2, v196, v2, s[0:1]
	v_cmp_ngt_f32_e64 s[0:1], -1.0, v16
	s_nop 1
	v_cndmask_b32_e64 v2, v197, v2, s[0:1]
	v_cmp_neq_f32_e64 s[0:1], -1.0, v16
	s_nop 1
	v_cndmask_b32_e64 v2, v198, v2, s[0:1]
	v_cmp_lt_f32_e64 s[0:1], |v16|, s45
	s_nop 1
	v_cndmask_b32_e64 v2, v2, v16, s[0:1]
	v_sub_f32_e32 v2, v17, v2
	global_store_dword v[0:1], v2, off
	s_branch .LBB0_91
